# prep weight transposes: nt (streaming) hint on the read-once f32 weight loads
# baseline (speedup 1.0000x reference)
; #define LAS __attribute__((address_space(3)))
; __device__ __forceinline__ void transpose_item(const float* W, int K, int Nsrc, bf16_t* WT, int Ndst, const float* gain, int maptype, LAS float* scr, int item, int lane) {
;     const int nblk = Ndst / 64, kb = item / nblk, nb = item % nblk, k0 = 64 * kb, n0 = 64 * nb;
;     const int nd = n0 + lane; const int src = (maptype == MAP_IN) ? map_in(nd) : nd;
;     const float* wp = W + (size_t)k0 * Nsrc + (src >= 0 ? src : 0);
; #pragma unroll
;     for (int h = 0; h < 2; ++h) {
;         float v[32];
; #pragma unroll
;         for (int i = 0; i < 32; ++i) v[i] = wp[(size_t)(32 * h + i) * Nsrc];
; #pragma unroll
;         for (int i = 0; i < 32; ++i) { float x = (src >= 0) ? v[i] : 0.f; if (gain) x *= gain[k0 + 32 * h + i]; scr[(32 * h + i) * 65 + lane] = x; }
; __device__ __forceinline__ void prep_phase(const Params& P, LAS unsigned char* lds) {
;     ...
;     for (int it = gw; it < DEPTH * I_LAYER; it += NGW) {
;         const int L = it / I_LAYER; int r = it % I_LAYER;
;         if (r < I_IN) { transpose_item(P.in[2] + (size_t)L * DM * IN_COLS, DM, IN_COLS, (bf16_t*)(ws + WS_WIN) + (size_t)L * NIN * DM, NIN, P.in[1] + L * DM, MAP_IN, scr, r, lane); continue; } r -= I_IN;
;         if (r < I_SQ) { transpose_item(P.in[10] + (size_t)L * DM * DM, DM, DM, (bf16_t*)(ws + WS_WAP) + (size_t)L * DM * DM, DM, nullptr, MAP_ID, scr, r, lane); continue; } r -= I_SQ;
;         if (r < I_SQ) { transpose_item(P.in[11] + (size_t)L * DM * DM, DM, DM, (bf16_t*)(ws + WS_WCO) + (size_t)L * DM * DM, DM, nullptr, MAP_ID, scr, r, lane); continue; } r -= I_SQ;
;         if (r < I_SQ) { transpose_item(P.in[12] + (size_t)L * DM * DM, DM, DM, (bf16_t*)(ws + WS_WO) + (size_t)L * DM * DM, DM, nullptr, MAP_ID, scr, r, lane); continue; } r -= I_SQ;
;         if (r < I_UP) { transpose_item(P.in[14] + (size_t)L * DM * FF, DM, FF, (bf16_t*)(ws + WS_WUP) + (size_t)L * FF * DM, FF, P.in[13] + L * DM, MAP_ID, scr, r, lane); continue; } r -= I_UP;
;         if (r < I_DN) { transpose_item(P.in[15] + (size_t)L * FF * DM, FF, DM, (bf16_t*)(ws + WS_WDN) + (size_t)L * DM * FF, DM, nullptr, MAP_ID, scr, r, lane); continue; } r -= I_DN;
;         if (r < I_C1) { transpose_item(P.in[4] + (size_t)L * 4096 * 256, 4096, 256, (bf16_t*)(ws + WS_CW1) + (size_t)(L * 2 + 0) * 256 * 4096, 256, nullptr, MAP_ID, scr, r, lane); continue; } r -= I_C1;
.LBB0_17:
	s_mov_b32 s4, 0xd62b80d7
	v_mul_hi_i32 v6, v64, s4
	v_add_u32_e32 v6, v6, v64
	v_lshrrev_b32_e32 v7, 31, v6
	v_ashrrev_i32_e32 v6, 14, v6
	v_add_u32_e32 v6, v6, v7
	v_mul_i32_i24_e32 v10, 0x4c80, v6
	v_sub_u32_e32 v9, v64, v10
	s_movk_i32 s4, 0x1e7f
	v_cmp_lt_i32_e32 vcc, s4, v9
	v_ashrrev_i32_e32 v7, 31, v6
	s_and_saveexec_b64 s[4:5], vcc
	s_xor_b64 s[6:7], exec, s[4:5]
	s_cbranch_execz .LBB0_93
	s_movk_i32 s4, 0x227f
	v_cmp_lt_u32_e32 vcc, s4, v9
	s_and_saveexec_b64 s[4:5], vcc
	s_xor_b64 s[74:75], exec, s[4:5]
	s_cbranch_execz .LBB0_90
	s_movk_i32 s4, 0x267f
	v_cmp_lt_u32_e32 vcc, s4, v9
	s_and_saveexec_b64 s[4:5], vcc
	s_xor_b64 s[76:77], exec, s[4:5]
	s_cbranch_execz .LBB0_87
	s_movk_i32 s4, 0x2a7f
	v_cmp_lt_u32_e32 vcc, s4, v9
	s_and_saveexec_b64 s[4:5], vcc
	s_xor_b64 s[78:79], exec, s[4:5]
	s_cbranch_execz .LBB0_84
	s_movk_i32 s4, 0x3a7f
	v_cmp_lt_u32_e32 vcc, s4, v9
	s_and_saveexec_b64 s[4:5], vcc
	s_xor_b64 s[4:5], exec, s[4:5]
	s_cbranch_execz .LBB0_31
	s_movk_i32 s48, 0x4a7f
	v_cmp_lt_u32_e32 vcc, s48, v9
	s_and_saveexec_b64 s[48:49], vcc
	s_xor_b64 s[80:81], exec, s[48:49]
	s_cbranch_execz .LBB0_28
	s_movk_i32 s48, 0x4b7f
	v_cmp_lt_u32_e32 vcc, s48, v9
	v_lshlrev_b64 v[8:9], 22, v[6:7]
	v_lshlrev_b32_e32 v7, 4, v10
	v_lshlrev_b32_e32 v6, 1, v6
	v_sub_u32_e32 v7, v45, v7
	s_and_saveexec_b64 s[48:49], vcc
	s_xor_b64 s[82:83], exec, s[48:49]
	s_cbranch_execz .LBB0_25
	s_movk_i32 s48, 0x800
	v_bitop3_b32 v20, v7, s48, v46 bitop3:0x6c
	v_lshlrev_b32_e32 v7, 6, v10
	v_sub_u32_e32 v7, v43, v7
	v_and_b32_e32 v21, 0xc0, v7
	v_lshl_add_u64 v[8:9], s[26:27], 0, v[8:9]
	v_or_b32_e32 v7, v21, v1
	v_lshlrev_b32_e32 v10, 10, v20
	v_mov_b32_e32 v11, v5
	v_lshl_add_u64 v[8:9], v[8:9], 0, v[10:11]
	v_lshlrev_b32_e32 v10, 2, v7
	v_lshl_add_u64 v[8:9], v[8:9], 0, v[10:11]
	s_movk_i32 s48, 0x1000
	v_add_co_u32_e32 v10, vcc, s48, v8
	s_movk_i32 s48, 0x3000
	s_nop 0
	v_addc_co_u32_e32 v11, vcc, 0, v9, vcc
	v_add_co_u32_e32 v12, vcc, s35, v8
	v_or_b32_e32 v6, 1, v6
	s_nop 0
	v_addc_co_u32_e32 v13, vcc, 0, v9, vcc
	v_add_co_u32_e32 v14, vcc, s48, v8
	s_movk_i32 s48, 0x5000
	s_nop 0
	v_addc_co_u32_e32 v15, vcc, 0, v9, vcc
	v_add_co_u32_e32 v16, vcc, s84, v8
	global_load_dword v7, v[12:13], off offset:-4096 nt
	global_load_dword v22, v[12:13], off nt
	global_load_dword v23, v[12:13], off offset:1024 nt
	v_addc_co_u32_e32 v17, vcc, 0, v9, vcc
	global_load_dword v24, v[8:9], off nt
	global_load_dword v25, v[8:9], off offset:1024 nt
	global_load_dword v26, v[8:9], off offset:2048 nt
	global_load_dword v27, v[8:9], off offset:3072 nt
	global_load_dword v28, v[10:11], off offset:1024 nt
	global_load_dword v29, v[10:11], off offset:2048 nt
	global_load_dword v30, v[10:11], off offset:3072 nt
	global_load_dword v31, v[14:15], off offset:1024 nt
	v_add_co_u32_e32 v10, vcc, s48, v8
	s_movk_i32 s48, 0x7000
	s_nop 0
	v_addc_co_u32_e32 v11, vcc, 0, v9, vcc
	v_add_co_u32_e32 v18, vcc, s86, v8
	s_nop 1
	v_addc_co_u32_e32 v19, vcc, 0, v9, vcc
	global_load_dword v65, v[12:13], off offset:2048 nt
	global_load_dword v66, v[12:13], off offset:3072 nt
	global_load_dword v67, v[16:17], off offset:-4096 nt
	global_load_dword v68, v[16:17], off nt
	global_load_dword v69, v[16:17], off offset:1024 nt
	global_load_dword v70, v[16:17], off offset:2048 nt
	global_load_dword v71, v[16:17], off offset:3072 nt
	global_load_dword v72, v[18:19], off offset:-4096 nt
	v_add_co_u32_e32 v12, vcc, s48, v8
	s_mov_b32 s48, 0x9000
	s_nop 0
	v_addc_co_u32_e32 v13, vcc, 0, v9, vcc
	v_add_co_u32_e32 v16, vcc, s88, v8
	s_nop 1
	v_addc_co_u32_e32 v17, vcc, 0, v9, vcc
	global_load_dword v73, v[14:15], off offset:2048 nt
	global_load_dword v74, v[14:15], off offset:3072 nt
	global_load_dword v75, v[10:11], off offset:1024 nt
	global_load_dword v76, v[10:11], off offset:2048 nt
	global_load_dword v77, v[10:11], off offset:3072 nt
	global_load_dword v78, v[12:13], off offset:1024 nt
	global_load_dword v79, v[12:13], off offset:2048 nt
	global_load_dword v80, v[12:13], off offset:3072 nt
	global_load_dword v81, v[18:19], off nt
	global_load_dword v82, v[18:19], off offset:1024 nt
	global_load_dword v83, v[18:19], off offset:2048 nt
	global_load_dword v84, v[18:19], off offset:3072 nt
	global_load_dword v85, v[16:17], off offset:-4096 nt
	global_load_dword v86, v[16:17], off nt
	global_load_dword v87, v[16:17], off offset:1024 nt
	global_load_dword v88, v[16:17], off offset:2048 nt
	v_add_co_u32_e32 v10, vcc, s48, v8
	s_mov_b32 s48, 0xb000
	s_nop 0
	v_addc_co_u32_e32 v11, vcc, 0, v9, vcc
	v_add_co_u32_e32 v12, vcc, s90, v8
	s_nop 1
	v_addc_co_u32_e32 v13, vcc, 0, v9, vcc
	v_add_co_u32_e32 v14, vcc, s48, v8
	s_mov_b32 s48, 0xd000
	s_nop 0
	v_addc_co_u32_e32 v15, vcc, 0, v9, vcc
	v_add_co_u32_e32 v18, vcc, s92, v8
	s_nop 1
	v_addc_co_u32_e32 v19, vcc, 0, v9, vcc
	global_load_dword v89, v[16:17], off offset:3072 nt
	global_load_dword v90, v[12:13], off offset:-4096 nt
	global_load_dword v91, v[12:13], off nt
	global_load_dword v92, v[12:13], off offset:1024 nt
	global_load_dword v93, v[12:13], off offset:2048 nt
	global_load_dword v94, v[12:13], off offset:3072 nt
	global_load_dword v95, v[18:19], off offset:-4096 nt
	global_load_dword v96, v[18:19], off nt
	v_add_co_u32_e32 v12, vcc, s48, v8
	v_readlane_b32 s48, v255, 11
	s_nop 0
	v_addc_co_u32_e32 v13, vcc, 0, v9, vcc
	v_add_co_u32_e32 v16, vcc, s94, v8
	v_readlane_b32 s49, v255, 12
	s_nop 0
	v_addc_co_u32_e32 v17, vcc, 0, v9, vcc
	v_add_co_u32_e32 v8, vcc, s95, v8
	global_load_dword v97, v[10:11], off offset:1024 nt
	global_load_dword v98, v[10:11], off offset:2048 nt
	s_nop 0
	global_load_dword v10, v[10:11], off offset:3072 nt
	s_nop 0
	global_load_dword v11, v[14:15], off offset:1024 nt
	global_load_dword v99, v[14:15], off offset:2048 nt
	s_nop 0
	global_load_dword v14, v[14:15], off offset:3072 nt
	s_nop 0
	global_load_dword v15, v[12:13], off offset:1024 nt
	global_load_dword v100, v[12:13], off offset:2048 nt
	global_load_dword v101, v[18:19], off offset:1024 nt
	global_load_dword v102, v[18:19], off offset:2048 nt
	s_nop 0
	global_load_dword v18, v[18:19], off offset:3072 nt
	s_nop 0
	global_load_dword v19, v[16:17], off offset:-4096 nt
	global_load_dword v103, v[16:17], off nt
	global_load_dword v104, v[16:17], off offset:1024 nt
	global_load_dword v105, v[16:17], off offset:2048 nt
	s_nop 0
	global_load_dword v16, v[16:17], off offset:3072 nt
	v_addc_co_u32_e32 v9, vcc, 0, v9, vcc
	global_load_dword v12, v[12:13], off offset:3072 nt
	s_nop 0
	global_load_dword v13, v[8:9], off nt
	global_load_dword v17, v[8:9], off offset:1024 nt
	global_load_dword v106, v[8:9], off offset:2048 nt
	s_nop 0
	global_load_dword v8, v[8:9], off offset:3072 nt
	s_waitcnt vmcnt(59)
; #define LAS __attribute__((address_space(3)))
; __device__ __forceinline__ unsigned cvt_pk_bf16(float lo, float hi) { unsigned r; asm volatile("v_cvt_pk_bf16_f32 %0, %1, %2" : "=v"(r) : "v"(lo), "v"(hi)); return r; }
; __device__ __forceinline__ void transpose_item(const float* W, int K, int Nsrc, bf16_t* WT, int Ndst, const float* gain, int maptype, LAS float* scr, int item, int lane) {
;     ...
;         for (int i = 0; i < 32; ++i) { float x = (src >= 0) ? v[i] : 0.f; if (gain) x *= gain[k0 + 32 * h + i]; scr[(32 * h + i) * 65 + lane] = x; }
;     }
;     asm volatile("s_waitcnt lgkmcnt(0)" ::: "memory");
;     const int cidx = lane & 7;
; #pragma unroll
;     for (int j = 0; j < 8; ++j) { const int n = (lane >> 3) + 8 * j; const LAS float* s = scr + (8 * cidx) * 65 + n;
;         u32x4 o; o.x = cvt_pk_bf16(s[0 * 65], s[1 * 65]); o.y = cvt_pk_bf16(s[2 * 65], s[3 * 65]); o.z = cvt_pk_bf16(s[4 * 65], s[5 * 65]); o.w = cvt_pk_bf16(s[6 * 65], s[7 * 65]);
;         *(u32x4*)(WT + (size_t)(n0 + n) * K + k0 + 8 * cidx) = o; }
	ds_write2_b32 v32, v24, v25 offset1:65
	s_waitcnt vmcnt(57)
	ds_write2_b32 v32, v26, v27 offset0:130 offset1:195
	s_waitcnt vmcnt(56)
	ds_write2_b32 v47, v7, v28 offset0:4 offset1:69
	s_waitcnt vmcnt(54)
	ds_write2_b32 v47, v29, v30 offset0:134 offset1:199
	ds_write2_b32 v48, v22, v23 offset0:8 offset1:73
	s_waitcnt vmcnt(51)
	ds_write2_b32 v48, v65, v66 offset0:138 offset1:203
	s_waitcnt vmcnt(50)
	ds_write2_b32 v49, v67, v31 offset0:12 offset1:77
	s_waitcnt vmcnt(43)
	ds_write2_b32 v49, v73, v74 offset0:142 offset1:207
	ds_write2_b32 v50, v68, v69 offset0:16 offset1:81
	ds_write2_b32 v50, v70, v71 offset0:146 offset1:211
	s_waitcnt vmcnt(42)
	ds_write2_b32 v51, v72, v75 offset0:20 offset1:85
	s_waitcnt vmcnt(40)
	ds_write2_b32 v51, v76, v77 offset0:150 offset1:215
	s_waitcnt vmcnt(35)
	ds_write2_b32 v52, v81, v82 offset0:24 offset1:89
	s_waitcnt vmcnt(33)
	ds_write2_b32 v52, v83, v84 offset0:154 offset1:219
	s_waitcnt vmcnt(32)
	ds_write2_b32 v53, v85, v78 offset0:28 offset1:93
	ds_write2_b32 v53, v79, v80 offset0:158 offset1:223
	s_waitcnt vmcnt(30)
	ds_write2_b32 v54, v86, v87 offset0:32 offset1:97
	s_waitcnt vmcnt(28)
	ds_write2_b32 v54, v88, v89 offset0:162 offset1:227
	s_waitcnt vmcnt(20)
	ds_write2_b32 v55, v90, v97 offset0:36 offset1:101
	s_waitcnt vmcnt(18)
	ds_write2_b32 v55, v98, v10 offset0:166 offset1:231
	ds_write2_b32 v56, v91, v92 offset0:40 offset1:105
	ds_write2_b32 v56, v93, v94 offset0:170 offset1:235
	s_waitcnt vmcnt(17)
	ds_write2_b32 v57, v95, v11 offset0:44 offset1:109
	s_waitcnt vmcnt(15)
	ds_write2_b32 v57, v99, v14 offset0:174 offset1:239
	s_waitcnt vmcnt(12)
	ds_write2_b32 v58, v96, v101 offset0:48 offset1:113
	s_waitcnt vmcnt(10)
	ds_write2_b32 v58, v102, v18 offset0:178 offset1:243
	s_waitcnt vmcnt(9)
	ds_write2_b32 v59, v19, v15 offset0:52 offset1:117
	s_waitcnt vmcnt(4)
	ds_write2_b32 v59, v100, v12 offset0:182 offset1:247
	ds_write2_b32 v60, v103, v104 offset0:56 offset1:121
	ds_write2_b32 v60, v105, v16 offset0:186 offset1:251
	s_waitcnt vmcnt(2)
	ds_write2_b32 v61, v13, v17 offset0:60 offset1:125
	s_waitcnt vmcnt(0)
	ds_write2_b32 v61, v106, v8 offset0:190 offset1:255
	s_waitcnt lgkmcnt(0)
	ds_read2_b32 v[8:9], v34 offset1:65
	s_waitcnt lgkmcnt(0)
	v_cvt_pk_bf16_f32 v8, v8, v9
	ds_read2_b32 v[10:11], v34 offset0:130 offset1:195
	v_ashrrev_i32_e32 v7, 31, v6
	s_waitcnt lgkmcnt(0)
	v_cvt_pk_bf16_f32 v9, v10, v11
	ds_read2_b32 v[10:11], v62 offset0:4 offset1:69
	v_lshlrev_b64 v[6:7], 21, v[6:7]
	v_lshl_add_u64 v[6:7], s[48:49], 0, v[6:7]
	s_waitcnt lgkmcnt(0)
	v_cvt_pk_bf16_f32 v10, v10, v11
	ds_read2_b32 v[12:13], v62 offset0:134 offset1:199
	v_lshlrev_b32_e32 v14, 1, v20
	v_mov_b32_e32 v15, v5
	v_lshl_add_u64 v[6:7], v[6:7], 0, v[14:15]
	s_waitcnt lgkmcnt(0)
	v_cvt_pk_bf16_f32 v11, v12, v13
	v_or_b32_e32 v12, v21, v33
	v_lshl_add_u64 v[14:15], v[6:7], 0, v[4:5]
	v_lshlrev_b32_e32 v12, 13, v12
	v_mov_b32_e32 v13, v5
	ds_read2_b32 v[6:7], v34 offset0:8 offset1:73
	v_lshl_add_u64 v[12:13], v[14:15], 0, v[12:13]
	global_store_dwordx4 v[12:13], v[8:11], off
	s_waitcnt lgkmcnt(0)
	v_cvt_pk_bf16_f32 v6, v6, v7
	ds_read2_b32 v[8:9], v34 offset0:138 offset1:203
	v_or_b32_e32 v12, v21, v35
	s_waitcnt lgkmcnt(0)
	v_cvt_pk_bf16_f32 v7, v8, v9
	ds_read2_b32 v[8:9], v62 offset0:12 offset1:77
	v_lshlrev_b32_e32 v12, 13, v12
	v_mov_b32_e32 v13, v5
	s_waitcnt lgkmcnt(0)
	v_cvt_pk_bf16_f32 v8, v8, v9
	ds_read2_b32 v[10:11], v62 offset0:142 offset1:207
	s_waitcnt lgkmcnt(0)
	v_cvt_pk_bf16_f32 v9, v10, v11
	v_lshl_add_u64 v[12:13], v[14:15], 0, v[12:13]
	ds_read2_b32 v[10:11], v34 offset0:16 offset1:81
	global_store_dwordx4 v[12:13], v[6:9], off
	v_or_b32_e32 v12, v21, v36
	v_lshlrev_b32_e32 v12, 13, v12
	s_waitcnt lgkmcnt(0)
	v_cvt_pk_bf16_f32 v6, v10, v11
	ds_read2_b32 v[8:9], v34 offset0:146 offset1:211
	s_waitcnt lgkmcnt(0)
	v_cvt_pk_bf16_f32 v7, v8, v9
	ds_read2_b32 v[8:9], v62 offset0:20 offset1:85
	v_mov_b32_e32 v13, v5
	s_waitcnt lgkmcnt(0)
	v_cvt_pk_bf16_f32 v8, v8, v9
	ds_read2_b32 v[10:11], v62 offset0:150 offset1:215
	s_waitcnt lgkmcnt(0)
	v_cvt_pk_bf16_f32 v9, v10, v11
	v_lshl_add_u64 v[12:13], v[14:15], 0, v[12:13]
	ds_read2_b32 v[10:11], v34 offset0:24 offset1:89
	global_store_dwordx4 v[12:13], v[6:9], off
	v_or_b32_e32 v12, v21, v37
	v_lshlrev_b32_e32 v12, 13, v12
	s_waitcnt lgkmcnt(0)
	v_cvt_pk_bf16_f32 v6, v10, v11
	ds_read2_b32 v[8:9], v34 offset0:154 offset1:219
	s_waitcnt lgkmcnt(0)
	v_cvt_pk_bf16_f32 v7, v8, v9
	ds_read2_b32 v[8:9], v62 offset0:28 offset1:93
	v_mov_b32_e32 v13, v5
	s_waitcnt lgkmcnt(0)
	v_cvt_pk_bf16_f32 v8, v8, v9
	ds_read2_b32 v[10:11], v62 offset0:158 offset1:223
	s_waitcnt lgkmcnt(0)
	v_cvt_pk_bf16_f32 v9, v10, v11
	v_lshl_add_u64 v[12:13], v[14:15], 0, v[12:13]
	ds_read2_b32 v[10:11], v34 offset0:32 offset1:97
	global_store_dwordx4 v[12:13], v[6:9], off
	v_or_b32_e32 v12, v21, v38
	v_lshlrev_b32_e32 v12, 13, v12
	s_waitcnt lgkmcnt(0)
	v_cvt_pk_bf16_f32 v6, v10, v11
	ds_read2_b32 v[8:9], v34 offset0:162 offset1:227
	s_waitcnt lgkmcnt(0)
	v_cvt_pk_bf16_f32 v7, v8, v9
	ds_read2_b32 v[8:9], v62 offset0:36 offset1:101
	v_mov_b32_e32 v13, v5
	s_waitcnt lgkmcnt(0)
	v_cvt_pk_bf16_f32 v8, v8, v9
	ds_read2_b32 v[10:11], v62 offset0:166 offset1:231
	s_waitcnt lgkmcnt(0)
	v_cvt_pk_bf16_f32 v9, v10, v11
	v_lshl_add_u64 v[12:13], v[14:15], 0, v[12:13]
	ds_read2_b32 v[10:11], v34 offset0:40 offset1:105
	global_store_dwordx4 v[12:13], v[6:9], off
	v_or_b32_e32 v12, v21, v39
	v_lshlrev_b32_e32 v12, 13, v12
	s_waitcnt lgkmcnt(0)
	v_cvt_pk_bf16_f32 v6, v10, v11
	ds_read2_b32 v[8:9], v34 offset0:170 offset1:235
	s_waitcnt lgkmcnt(0)
	v_cvt_pk_bf16_f32 v7, v8, v9
	ds_read2_b32 v[8:9], v62 offset0:44 offset1:109
	v_mov_b32_e32 v13, v5
	s_waitcnt lgkmcnt(0)
; #define LAS __attribute__((address_space(3)))
; __device__ __forceinline__ unsigned cvt_pk_bf16(float lo, float hi) { unsigned r; asm volatile("v_cvt_pk_bf16_f32 %0, %1, %2" : "=v"(r) : "v"(lo), "v"(hi)); return r; }
; __device__ __forceinline__ void transpose_item(const float* W, int K, int Nsrc, bf16_t* WT, int Ndst, const float* gain, int maptype, LAS float* scr, int item, int lane) {
;     const int nblk = Ndst / 64, kb = item / nblk, nb = item % nblk, k0 = 64 * kb, n0 = 64 * nb;
;     const int nd = n0 + lane; const int src = (maptype == MAP_IN) ? map_in(nd) : nd;
;     const float* wp = W + (size_t)k0 * Nsrc + (src >= 0 ? src : 0);
; #pragma unroll
;     for (int h = 0; h < 2; ++h) {
;         float v[32];
; #pragma unroll
;         for (int i = 0; i < 32; ++i) v[i] = wp[(size_t)(32 * h + i) * Nsrc];
; #pragma unroll
;         for (int i = 0; i < 32; ++i) { float x = (src >= 0) ? v[i] : 0.f; if (gain) x *= gain[k0 + 32 * h + i]; scr[(32 * h + i) * 65 + lane] = x; }
;     }
;     asm volatile("s_waitcnt lgkmcnt(0)" ::: "memory");
;     const int cidx = lane & 7;
; #pragma unroll
;     for (int j = 0; j < 8; ++j) { const int n = (lane >> 3) + 8 * j; const LAS float* s = scr + (8 * cidx) * 65 + n;
;         u32x4 o; o.x = cvt_pk_bf16(s[0 * 65], s[1 * 65]); o.y = cvt_pk_bf16(s[2 * 65], s[3 * 65]); o.z = cvt_pk_bf16(s[4 * 65], s[5 * 65]); o.w = cvt_pk_bf16(s[6 * 65], s[7 * 65]);
;         *(u32x4*)(WT + (size_t)(n0 + n) * K + k0 + 8 * cidx) = o; }
	v_cvt_pk_bf16_f32 v8, v8, v9
	ds_read2_b32 v[10:11], v62 offset0:174 offset1:239
	s_waitcnt lgkmcnt(0)
	v_cvt_pk_bf16_f32 v9, v10, v11
	v_lshl_add_u64 v[12:13], v[14:15], 0, v[12:13]
	ds_read2_b32 v[10:11], v34 offset0:48 offset1:113
	global_store_dwordx4 v[12:13], v[6:9], off
	v_or_b32_e32 v12, v21, v40
	v_lshlrev_b32_e32 v12, 13, v12
	s_waitcnt lgkmcnt(0)
	v_cvt_pk_bf16_f32 v6, v10, v11
	ds_read2_b32 v[8:9], v34 offset0:178 offset1:243
	s_waitcnt lgkmcnt(0)
	v_cvt_pk_bf16_f32 v7, v8, v9
	ds_read2_b32 v[8:9], v62 offset0:52 offset1:117
	v_mov_b32_e32 v13, v5
	s_waitcnt lgkmcnt(0)
	v_cvt_pk_bf16_f32 v8, v8, v9
	ds_read2_b32 v[10:11], v62 offset0:182 offset1:247
	s_waitcnt lgkmcnt(0)
	v_cvt_pk_bf16_f32 v9, v10, v11
	v_lshl_add_u64 v[12:13], v[14:15], 0, v[12:13]
	ds_read2_b32 v[10:11], v34 offset0:56 offset1:121
	global_store_dwordx4 v[12:13], v[6:9], off
	s_waitcnt lgkmcnt(0)
	s_nop 0
	v_cvt_pk_bf16_f32 v6, v10, v11
	ds_read2_b32 v[8:9], v34 offset0:186 offset1:251
	s_waitcnt lgkmcnt(0)
	v_cvt_pk_bf16_f32 v7, v8, v9
	ds_read2_b32 v[8:9], v62 offset0:60 offset1:125
	s_waitcnt lgkmcnt(0)
	v_cvt_pk_bf16_f32 v8, v8, v9
	ds_read2_b32 v[10:11], v62 offset0:190 offset1:255
	s_waitcnt lgkmcnt(0)
	v_cvt_pk_bf16_f32 v9, v10, v11
	v_or_b32_e32 v10, v21, v41
	v_lshlrev_b32_e32 v10, 13, v10
	v_mov_b32_e32 v11, v5
	v_lshl_add_u64 v[10:11], v[14:15], 0, v[10:11]
	global_store_dwordx4 v[10:11], v[6:9], off
	s_waitcnt lgkmcnt(0)
.LBB0_25:
	s_andn2_saveexec_b64 s[82:83], s[82:83]
	s_cbranch_execz .LBB0_27
	s_movk_i32 s48, 0x800
	v_lshl_add_u64 v[12:13], s[20:21], 0, v[8:9]
	v_bitop3_b32 v9, v7, s48, v46 bitop3:0x6c
	v_lshlrev_b32_e32 v7, 6, v10
	v_sub_u32_e32 v7, v43, v7
	v_and_b32_e32 v8, 0xc0, v7
	v_or_b32_e32 v7, v8, v1
	v_lshlrev_b32_e32 v10, 10, v9
	v_mov_b32_e32 v11, v5
	v_lshl_add_u64 v[10:11], v[12:13], 0, v[10:11]
	v_lshlrev_b32_e32 v12, 2, v7
	v_mov_b32_e32 v13, v5
	v_lshl_add_u64 v[10:11], v[10:11], 0, v[12:13]
	s_movk_i32 s48, 0x1000
	v_add_co_u32_e32 v12, vcc, s48, v10
	s_movk_i32 s48, 0x3000
	s_nop 0
	v_addc_co_u32_e32 v13, vcc, 0, v11, vcc
	v_add_co_u32_e32 v14, vcc, s35, v10
	s_nop 1
	v_addc_co_u32_e32 v15, vcc, 0, v11, vcc
	v_add_co_u32_e32 v16, vcc, s48, v10
	s_movk_i32 s48, 0x5000
	s_nop 0
	v_addc_co_u32_e32 v17, vcc, 0, v11, vcc
	v_add_co_u32_e32 v18, vcc, s84, v10
	s_nop 1
	v_addc_co_u32_e32 v19, vcc, 0, v11, vcc
	v_add_co_u32_e32 v20, vcc, s48, v10
	s_movk_i32 s48, 0x7000
	s_nop 0
	v_addc_co_u32_e32 v21, vcc, 0, v11, vcc
	v_add_co_u32_e32 v22, vcc, s86, v10
	s_nop 1
	v_addc_co_u32_e32 v23, vcc, 0, v11, vcc
	v_add_co_u32_e32 v24, vcc, s48, v10
	s_mov_b32 s48, 0x9000
	s_nop 0
	v_addc_co_u32_e32 v25, vcc, 0, v11, vcc
	v_add_co_u32_e32 v26, vcc, s88, v10
	s_nop 1
	v_addc_co_u32_e32 v27, vcc, 0, v11, vcc
	v_add_co_u32_e32 v28, vcc, s95, v10
	global_load_dword v7, v[10:11], off nt
	global_load_dword v30, v[10:11], off offset:1024 nt
	global_load_dword v31, v[10:11], off offset:2048 nt
	global_load_dword v65, v[10:11], off offset:3072 nt
	global_load_dword v66, v[12:13], off offset:1024 nt
	global_load_dword v67, v[12:13], off offset:2048 nt
	global_load_dword v68, v[12:13], off offset:3072 nt
	global_load_dword v69, v[16:17], off offset:1024 nt
	global_load_dword v70, v[14:15], off offset:2048 nt
	global_load_dword v71, v[14:15], off offset:3072 nt
	global_load_dword v72, v[18:19], off offset:-4096 nt
	global_load_dword v73, v[18:19], off nt
	global_load_dword v74, v[18:19], off offset:1024 nt
	global_load_dword v75, v[18:19], off offset:2048 nt
	global_load_dword v76, v[18:19], off offset:3072 nt
	global_load_dword v77, v[22:23], off offset:-4096 nt
	global_load_dword v78, v[16:17], off offset:2048 nt
	global_load_dword v79, v[16:17], off offset:3072 nt
	global_load_dword v80, v[20:21], off offset:1024 nt
	global_load_dword v81, v[20:21], off offset:2048 nt
	s_nop 0
	global_load_dword v20, v[20:21], off offset:3072 nt
	s_nop 0
	global_load_dword v21, v[24:25], off offset:1024 nt
	global_load_dword v82, v[24:25], off offset:2048 nt
	s_nop 0
	global_load_dword v24, v[24:25], off offset:3072 nt
	s_nop 0
	global_load_dword v25, v[22:23], off nt
	global_load_dword v83, v[22:23], off offset:1024 nt
	global_load_dword v84, v[22:23], off offset:2048 nt
	s_nop 0
	global_load_dword v22, v[22:23], off offset:3072 nt
	s_nop 0
	global_load_dword v23, v[26:27], off offset:-4096 nt
	global_load_dword v85, v[26:27], off nt
	global_load_dword v86, v[26:27], off offset:1024 nt
	global_load_dword v87, v[26:27], off offset:2048 nt
	global_load_dword v88, v[14:15], off offset:-4096 nt
	global_load_dword v89, v[14:15], off nt
	global_load_dword v90, v[14:15], off offset:1024 nt
	v_addc_co_u32_e32 v29, vcc, 0, v11, vcc
	v_add_co_u32_e32 v12, vcc, s48, v10
	s_mov_b32 s48, 0xb000
	s_nop 0
	v_addc_co_u32_e32 v13, vcc, 0, v11, vcc
	v_add_co_u32_e32 v14, vcc, s90, v10
	s_nop 1
	v_addc_co_u32_e32 v15, vcc, 0, v11, vcc
	v_add_co_u32_e32 v16, vcc, s48, v10
	s_mov_b32 s48, 0xd000
	s_nop 0
	v_addc_co_u32_e32 v17, vcc, 0, v11, vcc
	v_add_co_u32_e32 v18, vcc, s92, v10
	s_nop 1
	v_addc_co_u32_e32 v19, vcc, 0, v11, vcc
	global_load_dword v26, v[26:27], off offset:3072 nt
	s_nop 0
	global_load_dword v27, v[14:15], off offset:-4096 nt
	global_load_dword v91, v[14:15], off nt
	global_load_dword v92, v[14:15], off offset:1024 nt
	global_load_dword v93, v[14:15], off offset:2048 nt
	global_load_dword v94, v[14:15], off offset:3072 nt
	global_load_dword v95, v[18:19], off offset:-4096 nt
	global_load_dword v96, v[18:19], off nt
	v_add_co_u32_e32 v14, vcc, s48, v10
	v_readlane_b32 s48, v255, 11
	s_nop 0
	v_addc_co_u32_e32 v15, vcc, 0, v11, vcc
	v_add_co_u32_e32 v10, vcc, s94, v10
	v_readlane_b32 s49, v255, 12
	s_nop 0
	v_addc_co_u32_e32 v11, vcc, 0, v11, vcc
	global_load_dword v97, v[12:13], off offset:1024 nt
	global_load_dword v98, v[12:13], off offset:2048 nt
	s_nop 0
	global_load_dword v12, v[12:13], off offset:3072 nt
	s_nop 0
	global_load_dword v13, v[16:17], off offset:1024 nt
	global_load_dword v99, v[16:17], off offset:2048 nt
	s_nop 0
	global_load_dword v16, v[16:17], off offset:3072 nt
	s_nop 0
	global_load_dword v17, v[14:15], off offset:1024 nt
	global_load_dword v100, v[14:15], off offset:2048 nt
	global_load_dword v101, v[18:19], off offset:1024 nt
	global_load_dword v102, v[18:19], off offset:2048 nt
	s_nop 0
	global_load_dword v18, v[18:19], off offset:3072 nt
	s_nop 0
	global_load_dword v19, v[10:11], off offset:-4096 nt
	global_load_dword v103, v[10:11], off nt
	global_load_dword v104, v[10:11], off offset:1024 nt
	global_load_dword v105, v[10:11], off offset:2048 nt
	s_nop 0
	global_load_dword v10, v[10:11], off offset:3072 nt
	s_nop 0
	global_load_dword v11, v[14:15], off offset:3072 nt
	s_nop 0
	global_load_dword v14, v[28:29], off offset:3072 nt
	global_load_dword v15, v[28:29], off nt
	global_load_dword v106, v[28:29], off offset:1024 nt
	s_nop 0
	global_load_dword v28, v[28:29], off offset:2048 nt
	s_waitcnt vmcnt(62)
; #define LAS __attribute__((address_space(3)))
; __device__ __forceinline__ unsigned cvt_pk_bf16(float lo, float hi) { unsigned r; asm volatile("v_cvt_pk_bf16_f32 %0, %1, %2" : "=v"(r) : "v"(lo), "v"(hi)); return r; }
; __device__ __forceinline__ void transpose_item(const float* W, int K, int Nsrc, bf16_t* WT, int Ndst, const float* gain, int maptype, LAS float* scr, int item, int lane) {
;     ...
;         for (int i = 0; i < 32; ++i) { float x = (src >= 0) ? v[i] : 0.f; if (gain) x *= gain[k0 + 32 * h + i]; scr[(32 * h + i) * 65 + lane] = x; }
;     }
;     asm volatile("s_waitcnt lgkmcnt(0)" ::: "memory");
;     const int cidx = lane & 7;
; #pragma unroll
;     for (int j = 0; j < 8; ++j) { const int n = (lane >> 3) + 8 * j; const LAS float* s = scr + (8 * cidx) * 65 + n;
;         u32x4 o; o.x = cvt_pk_bf16(s[0 * 65], s[1 * 65]); o.y = cvt_pk_bf16(s[2 * 65], s[3 * 65]); o.z = cvt_pk_bf16(s[4 * 65], s[5 * 65]); o.w = cvt_pk_bf16(s[6 * 65], s[7 * 65]);
;         *(u32x4*)(WT + (size_t)(n0 + n) * K + k0 + 8 * cidx) = o; }
;     asm volatile("s_waitcnt lgkmcnt(0)" ::: "memory");
	ds_write2_b32 v32, v7, v30 offset1:65
	s_waitcnt vmcnt(60)
	ds_write2_b32 v32, v31, v65 offset0:130 offset1:195
	s_waitcnt vmcnt(31)
	ds_write2_b32 v47, v88, v66 offset0:4 offset1:69
	ds_write2_b32 v47, v67, v68 offset0:134 offset1:199
	s_waitcnt vmcnt(29)
	ds_write2_b32 v48, v89, v90 offset0:8 offset1:73
	ds_write2_b32 v48, v70, v71 offset0:138 offset1:203
	ds_write2_b32 v49, v72, v69 offset0:12 offset1:77
	ds_write2_b32 v49, v78, v79 offset0:142 offset1:207
	ds_write2_b32 v50, v73, v74 offset0:16 offset1:81
	ds_write2_b32 v50, v75, v76 offset0:146 offset1:211
	ds_write2_b32 v51, v77, v80 offset0:20 offset1:85
	ds_write2_b32 v51, v81, v20 offset0:150 offset1:215
	ds_write2_b32 v52, v25, v83 offset0:24 offset1:89
	ds_write2_b32 v52, v84, v22 offset0:154 offset1:219
	ds_write2_b32 v53, v23, v21 offset0:28 offset1:93
	ds_write2_b32 v53, v82, v24 offset0:158 offset1:223
	ds_write2_b32 v54, v85, v86 offset0:32 offset1:97
	s_waitcnt vmcnt(28)
	ds_write2_b32 v54, v87, v26 offset0:162 offset1:227
	s_waitcnt vmcnt(20)
	ds_write2_b32 v55, v27, v97 offset0:36 offset1:101
	s_waitcnt vmcnt(18)
	ds_write2_b32 v55, v98, v12 offset0:166 offset1:231
	ds_write2_b32 v56, v91, v92 offset0:40 offset1:105
	ds_write2_b32 v56, v93, v94 offset0:170 offset1:235
	s_waitcnt vmcnt(17)
	ds_write2_b32 v57, v95, v13 offset0:44 offset1:109
	s_waitcnt vmcnt(15)
	ds_write2_b32 v57, v99, v16 offset0:174 offset1:239
	s_waitcnt vmcnt(12)
	ds_write2_b32 v58, v96, v101 offset0:48 offset1:113
	s_waitcnt vmcnt(10)
	ds_write2_b32 v58, v102, v18 offset0:178 offset1:243
	s_waitcnt vmcnt(9)
	ds_write2_b32 v59, v19, v17 offset0:52 offset1:117
	s_waitcnt vmcnt(4)
	ds_write2_b32 v59, v100, v11 offset0:182 offset1:247
	ds_write2_b32 v60, v103, v104 offset0:56 offset1:121
	ds_write2_b32 v60, v105, v10 offset0:186 offset1:251
	s_waitcnt vmcnt(1)
	ds_write2_b32 v61, v15, v106 offset0:60 offset1:125
	s_waitcnt vmcnt(0)
	ds_write2_b32 v61, v28, v14 offset0:190 offset1:255
	v_ashrrev_i32_e32 v7, 31, v6
	s_waitcnt lgkmcnt(0)
	v_lshlrev_b64 v[6:7], 21, v[6:7]
	ds_read2_b32 v[10:11], v34 offset1:65
	v_lshl_add_u64 v[6:7], s[48:49], 0, v[6:7]
	v_lshlrev_b32_e32 v16, 1, v9
	v_mov_b32_e32 v17, v5
	s_waitcnt lgkmcnt(0)
	v_cvt_pk_bf16_f32 v10, v10, v11
	ds_read2_b32 v[12:13], v34 offset0:130 offset1:195
	v_lshl_add_u64 v[6:7], v[6:7], 0, v[16:17]
	v_or_b32_e32 v9, v8, v33
	s_waitcnt lgkmcnt(0)
	v_cvt_pk_bf16_f32 v11, v12, v13
	ds_read2_b32 v[12:13], v62 offset0:4 offset1:69
	v_lshl_add_u64 v[6:7], v[6:7], 0, v[4:5]
	v_lshlrev_b32_e32 v16, 13, v9
	s_waitcnt lgkmcnt(0)
	v_cvt_pk_bf16_f32 v12, v12, v13
	ds_read2_b32 v[14:15], v62 offset0:134 offset1:199
	s_waitcnt lgkmcnt(0)
	v_cvt_pk_bf16_f32 v13, v14, v15
	v_lshl_add_u64 v[16:17], v[6:7], 0, v[16:17]
	ds_read2_b32 v[14:15], v34 offset0:8 offset1:73
	global_store_dwordx4 v[16:17], v[10:13], off
	v_or_b32_e32 v9, v8, v35
	v_lshlrev_b32_e32 v16, 13, v9
	s_waitcnt lgkmcnt(0)
	v_cvt_pk_bf16_f32 v10, v14, v15
	ds_read2_b32 v[12:13], v34 offset0:138 offset1:203
	s_waitcnt lgkmcnt(0)
	v_cvt_pk_bf16_f32 v11, v12, v13
	ds_read2_b32 v[12:13], v62 offset0:12 offset1:77
	v_mov_b32_e32 v17, v5
	s_waitcnt lgkmcnt(0)
	v_cvt_pk_bf16_f32 v12, v12, v13
	ds_read2_b32 v[14:15], v62 offset0:142 offset1:207
	s_waitcnt lgkmcnt(0)
	v_cvt_pk_bf16_f32 v13, v14, v15
	v_lshl_add_u64 v[16:17], v[6:7], 0, v[16:17]
	ds_read2_b32 v[14:15], v34 offset0:16 offset1:81
	global_store_dwordx4 v[16:17], v[10:13], off
	v_or_b32_e32 v9, v8, v36
	v_lshlrev_b32_e32 v16, 13, v9
	s_waitcnt lgkmcnt(0)
	v_cvt_pk_bf16_f32 v10, v14, v15
	ds_read2_b32 v[12:13], v34 offset0:146 offset1:211
	s_waitcnt lgkmcnt(0)
	v_cvt_pk_bf16_f32 v11, v12, v13
	ds_read2_b32 v[12:13], v62 offset0:20 offset1:85
	v_mov_b32_e32 v17, v5
	s_waitcnt lgkmcnt(0)
	v_cvt_pk_bf16_f32 v12, v12, v13
	ds_read2_b32 v[14:15], v62 offset0:150 offset1:215
	s_waitcnt lgkmcnt(0)
	v_cvt_pk_bf16_f32 v13, v14, v15
	v_lshl_add_u64 v[16:17], v[6:7], 0, v[16:17]
	ds_read2_b32 v[14:15], v34 offset0:24 offset1:89
	global_store_dwordx4 v[16:17], v[10:13], off
	v_or_b32_e32 v9, v8, v37
	v_lshlrev_b32_e32 v16, 13, v9
	s_waitcnt lgkmcnt(0)
	v_cvt_pk_bf16_f32 v10, v14, v15
	ds_read2_b32 v[12:13], v34 offset0:154 offset1:219
	s_waitcnt lgkmcnt(0)
	v_cvt_pk_bf16_f32 v11, v12, v13
	ds_read2_b32 v[12:13], v62 offset0:28 offset1:93
	v_mov_b32_e32 v17, v5
	s_waitcnt lgkmcnt(0)
	v_cvt_pk_bf16_f32 v12, v12, v13
	ds_read2_b32 v[14:15], v62 offset0:158 offset1:223
	s_waitcnt lgkmcnt(0)
	v_cvt_pk_bf16_f32 v13, v14, v15
	v_lshl_add_u64 v[16:17], v[6:7], 0, v[16:17]
	ds_read2_b32 v[14:15], v34 offset0:32 offset1:97
	global_store_dwordx4 v[16:17], v[10:13], off
	v_or_b32_e32 v9, v8, v38
	v_lshlrev_b32_e32 v16, 13, v9
	s_waitcnt lgkmcnt(0)
	v_cvt_pk_bf16_f32 v10, v14, v15
	ds_read2_b32 v[12:13], v34 offset0:162 offset1:227
	s_waitcnt lgkmcnt(0)
	v_cvt_pk_bf16_f32 v11, v12, v13
	ds_read2_b32 v[12:13], v62 offset0:36 offset1:101
	v_mov_b32_e32 v17, v5
	s_waitcnt lgkmcnt(0)
	v_cvt_pk_bf16_f32 v12, v12, v13
	ds_read2_b32 v[14:15], v62 offset0:166 offset1:231
	s_waitcnt lgkmcnt(0)
	v_cvt_pk_bf16_f32 v13, v14, v15
	v_lshl_add_u64 v[16:17], v[6:7], 0, v[16:17]
	ds_read2_b32 v[14:15], v34 offset0:40 offset1:105
	global_store_dwordx4 v[16:17], v[10:13], off
	v_or_b32_e32 v9, v8, v39
	v_lshlrev_b32_e32 v16, 13, v9
	s_waitcnt lgkmcnt(0)
	v_cvt_pk_bf16_f32 v10, v14, v15
	ds_read2_b32 v[12:13], v34 offset0:170 offset1:235
	s_waitcnt lgkmcnt(0)
	v_cvt_pk_bf16_f32 v11, v12, v13
	ds_read2_b32 v[12:13], v62 offset0:44 offset1:109
	v_mov_b32_e32 v17, v5
	s_waitcnt lgkmcnt(0)
	v_cvt_pk_bf16_f32 v12, v12, v13
	ds_read2_b32 v[14:15], v62 offset0:174 offset1:239
	s_waitcnt lgkmcnt(0)
	v_cvt_pk_bf16_f32 v13, v14, v15
	v_lshl_add_u64 v[16:17], v[6:7], 0, v[16:17]
	ds_read2_b32 v[14:15], v34 offset0:48 offset1:113
	global_store_dwordx4 v[16:17], v[10:13], off
	v_or_b32_e32 v9, v8, v40
	v_lshlrev_b32_e32 v16, 13, v9
	s_waitcnt lgkmcnt(0)
	v_cvt_pk_bf16_f32 v10, v14, v15
	ds_read2_b32 v[12:13], v34 offset0:178 offset1:243
	s_waitcnt lgkmcnt(0)
	v_cvt_pk_bf16_f32 v11, v12, v13
	ds_read2_b32 v[12:13], v62 offset0:52 offset1:117
	v_mov_b32_e32 v17, v5
	s_waitcnt lgkmcnt(0)
	v_cvt_pk_bf16_f32 v12, v12, v13
	ds_read2_b32 v[14:15], v62 offset0:182 offset1:247
	s_waitcnt lgkmcnt(0)
	v_cvt_pk_bf16_f32 v13, v14, v15
	v_lshl_add_u64 v[16:17], v[6:7], 0, v[16:17]
	v_or_b32_e32 v8, v8, v41
	ds_read2_b32 v[14:15], v34 offset0:56 offset1:121
	global_store_dwordx4 v[16:17], v[10:13], off
	v_lshlrev_b32_e32 v8, 13, v8
	v_mov_b32_e32 v9, v5
	s_waitcnt lgkmcnt(0)
	v_cvt_pk_bf16_f32 v10, v14, v15
	ds_read2_b32 v[12:13], v34 offset0:186 offset1:251
	s_waitcnt lgkmcnt(0)
	v_cvt_pk_bf16_f32 v11, v12, v13
	ds_read2_b32 v[12:13], v62 offset0:60 offset1:125
	v_lshl_add_u64 v[6:7], v[6:7], 0, v[8:9]
	s_waitcnt lgkmcnt(0)
	v_cvt_pk_bf16_f32 v12, v12, v13
	ds_read2_b32 v[14:15], v62 offset0:190 offset1:255
	s_waitcnt lgkmcnt(0)
	v_cvt_pk_bf16_f32 v13, v14, v15
	global_store_dwordx4 v[6:7], v[10:13], off
	s_waitcnt lgkmcnt(0)

; __device__ __forceinline__ void transpose_item(const float* W, int K, int Nsrc, bf16_t* WT, int Ndst, const float* gain, int maptype, LAS float* scr, int item, int lane) {
;     const int nblk = Ndst / 64, kb = item / nblk, nb = item % nblk, k0 = 64 * kb, n0 = 64 * nb;
;     const int nd = n0 + lane; const int src = (maptype == MAP_IN) ? map_in(nd) : nd;
;     const float* wp = W + (size_t)k0 * Nsrc + (src >= 0 ? src : 0);
; #pragma unroll
;     for (int h = 0; h < 2; ++h) {
;         float v[32];
; #pragma unroll
;         for (int i = 0; i < 32; ++i) v[i] = wp[(size_t)(32 * h + i) * Nsrc];
.LBB0_28:
	s_andn2_saveexec_b64 s[80:81], s[80:81]
	s_cbranch_execz .LBB0_30
	v_lshlrev_b32_e32 v11, 1, v10
	v_sub_u32_e32 v11, v44, v11
	v_lshlrev_b32_e32 v10, 6, v10
	v_readlane_b32 s60, v255, 21
	v_add_u32_e32 v11, 0xffffc800, v11
	v_sub_u32_e32 v10, v43, v10
	v_lshlrev_b64 v[8:9], 26, v[6:7]
	v_readlane_b32 s62, v255, 23
	v_readlane_b32 s63, v255, 24
	v_and_b32_e32 v11, 0x1ffc0, v11
	v_and_b32_e32 v10, 0x7c0, v10
	v_lshl_add_u64 v[8:9], s[62:63], 0, v[8:9]
	v_or_b32_e32 v14, v10, v1
	v_lshlrev_b32_e32 v12, 13, v11
	v_mov_b32_e32 v13, v5
	v_lshl_add_u64 v[8:9], v[8:9], 0, v[12:13]
	v_lshlrev_b32_e32 v12, 2, v14
	v_lshl_add_u64 v[8:9], v[8:9], 0, v[12:13]
	v_add_co_u32_e32 v14, vcc, s35, v8
	s_mov_b32 s48, 0x12000
	s_nop 0
	v_addc_co_u32_e32 v15, vcc, 0, v9, vcc
	v_add_co_u32_e32 v16, vcc, s84, v8
	s_mov_b32 s60, 0x5e000
	s_nop 0
	v_addc_co_u32_e32 v17, vcc, 0, v9, vcc
	v_add_co_u32_e32 v18, vcc, s86, v8
	v_readlane_b32 s61, v255, 22
	s_nop 0
	v_addc_co_u32_e32 v19, vcc, 0, v9, vcc
	v_add_co_u32_e32 v20, vcc, s88, v8
	s_mov_b32 s61, 0x62000
	s_nop 0
	v_addc_co_u32_e32 v21, vcc, 0, v9, vcc
	v_add_co_u32_e32 v22, vcc, s90, v8
	s_mov_b32 s62, 0x64000
	s_nop 0
	v_addc_co_u32_e32 v23, vcc, 0, v9, vcc
	v_add_co_u32_e32 v24, vcc, s92, v8
	s_mov_b32 s63, 0x66000
	s_nop 0
	v_addc_co_u32_e32 v25, vcc, 0, v9, vcc
	v_add_co_u32_e32 v26, vcc, s94, v8
	v_lshlrev_b64 v[6:7], 25, v[6:7]
	s_nop 0
	v_addc_co_u32_e32 v27, vcc, 0, v9, vcc
	global_load_dword v12, v[8:9], off nt
	global_load_dword v13, v[14:15], off nt
	s_nop 0
	global_load_dword v14, v[16:17], off nt
	global_load_dword v15, v[18:19], off nt
	s_nop 0
	global_load_dword v16, v[20:21], off nt
	global_load_dword v17, v[22:23], off nt
	global_load_dword v18, v[24:25], off nt
	global_load_dword v19, v[26:27], off nt
	v_add_co_u32_e32 v20, vcc, s96, v8
	s_nop 1
	v_addc_co_u32_e32 v21, vcc, 0, v9, vcc
	v_add_co_u32_e32 v22, vcc, s48, v8
	s_mov_b32 s48, 0x14000
	s_nop 0
	v_addc_co_u32_e32 v23, vcc, 0, v9, vcc
	v_add_co_u32_e32 v24, vcc, s48, v8
	s_mov_b32 s48, 0x16000
	s_nop 0
	v_addc_co_u32_e32 v25, vcc, 0, v9, vcc
	v_add_co_u32_e32 v26, vcc, s48, v8
	s_mov_b32 s48, 0x1a000
	s_nop 0
	v_addc_co_u32_e32 v27, vcc, 0, v9, vcc
	v_add_co_u32_e32 v28, vcc, s47, v8
	s_nop 1
	v_addc_co_u32_e32 v29, vcc, 0, v9, vcc
	v_add_co_u32_e32 v30, vcc, s48, v8
	s_mov_b32 s48, 0x1c000
	s_nop 0
	v_addc_co_u32_e32 v31, vcc, 0, v9, vcc
	v_add_co_u32_e32 v66, vcc, s48, v8
	s_mov_b32 s48, 0x22000
	s_nop 0
	v_addc_co_u32_e32 v67, vcc, 0, v9, vcc
	v_add_co_u32_e32 v68, vcc, s89, v8
	s_nop 1
	v_addc_co_u32_e32 v69, vcc, 0, v9, vcc
	global_load_dword v20, v[20:21], off nt
	s_nop 0
	global_load_dword v21, v[22:23], off nt
	s_nop 0
	global_load_dword v22, v[24:25], off nt
	global_load_dword v23, v[26:27], off nt
	s_nop 0
	global_load_dword v24, v[28:29], off nt
	global_load_dword v25, v[30:31], off nt
	global_load_dword v26, v[66:67], off nt
	global_load_dword v27, v[68:69], off nt
	v_add_co_u32_e32 v28, vcc, s91, v8
	s_nop 1
	v_addc_co_u32_e32 v29, vcc, 0, v9, vcc
	v_add_co_u32_e32 v30, vcc, s48, v8
	s_mov_b32 s48, 0x24000
	s_nop 0
	v_addc_co_u32_e32 v31, vcc, 0, v9, vcc
	v_add_co_u32_e32 v66, vcc, s48, v8
	s_mov_b32 s48, 0x26000
	s_nop 0
	v_addc_co_u32_e32 v67, vcc, 0, v9, vcc
	v_add_co_u32_e32 v68, vcc, s48, v8
	s_mov_b32 s48, 0x2a000
	s_nop 0
	v_addc_co_u32_e32 v69, vcc, 0, v9, vcc
	v_add_co_u32_e32 v70, vcc, s10, v8
	s_nop 1
	v_addc_co_u32_e32 v71, vcc, 0, v9, vcc
	v_add_co_u32_e32 v72, vcc, s48, v8
	s_mov_b32 s48, 0x2c000
	s_nop 0
	v_addc_co_u32_e32 v73, vcc, 0, v9, vcc
	v_add_co_u32_e32 v74, vcc, s48, v8
	s_mov_b32 s48, 0x2e000
	s_nop 0
	v_addc_co_u32_e32 v75, vcc, 0, v9, vcc
	v_add_co_u32_e32 v76, vcc, s48, v8
	s_mov_b32 s48, 0x32000
	s_nop 0
	v_addc_co_u32_e32 v77, vcc, 0, v9, vcc
	global_load_dword v65, v[28:29], off nt
	global_load_dword v78, v[30:31], off nt
	global_load_dword v79, v[66:67], off nt
	global_load_dword v80, v[68:69], off nt
	global_load_dword v81, v[70:71], off nt
	global_load_dword v82, v[72:73], off nt
	global_load_dword v83, v[74:75], off nt
	global_load_dword v84, v[76:77], off nt
	v_add_co_u32_e32 v28, vcc, s68, v8
	s_nop 1
	v_addc_co_u32_e32 v29, vcc, 0, v9, vcc
	v_add_co_u32_e32 v30, vcc, s48, v8
	s_mov_b32 s48, 0x34000
	s_nop 0
	v_addc_co_u32_e32 v31, vcc, 0, v9, vcc
	v_add_co_u32_e32 v66, vcc, s48, v8
	s_mov_b32 s48, 0x36000
	s_nop 0
	v_addc_co_u32_e32 v67, vcc, 0, v9, vcc
	v_add_co_u32_e32 v68, vcc, s48, v8
	s_mov_b32 s48, 0x3a000
	s_nop 0
	v_addc_co_u32_e32 v69, vcc, 0, v9, vcc
	v_add_co_u32_e32 v70, vcc, s56, v8
	s_nop 1
	v_addc_co_u32_e32 v71, vcc, 0, v9, vcc
	v_add_co_u32_e32 v72, vcc, s48, v8
	s_mov_b32 s48, 0x3e000
	s_nop 0
	v_addc_co_u32_e32 v73, vcc, 0, v9, vcc
	v_add_co_u32_e32 v74, vcc, s58, v8
	s_nop 1
	v_addc_co_u32_e32 v75, vcc, 0, v9, vcc
	v_add_co_u32_e32 v76, vcc, s48, v8
	s_mov_b32 s48, 0x42000
	s_nop 0
	v_addc_co_u32_e32 v77, vcc, 0, v9, vcc
	global_load_dword v85, v[28:29], off nt
	global_load_dword v86, v[30:31], off nt
	global_load_dword v87, v[66:67], off nt
	global_load_dword v88, v[68:69], off nt
	global_load_dword v89, v[70:71], off nt
	global_load_dword v90, v[72:73], off nt
	global_load_dword v91, v[74:75], off nt
	global_load_dword v92, v[76:77], off nt
	v_add_co_u32_e32 v28, vcc, s50, v8
	s_nop 1
	v_addc_co_u32_e32 v29, vcc, 0, v9, vcc
	v_add_co_u32_e32 v30, vcc, s48, v8
	s_mov_b32 s48, 0x44000
	s_nop 0
	v_addc_co_u32_e32 v31, vcc, 0, v9, vcc
	v_add_co_u32_e32 v66, vcc, s48, v8
	s_mov_b32 s48, 0x46000
	s_nop 0
	v_addc_co_u32_e32 v67, vcc, 0, v9, vcc
	v_add_co_u32_e32 v68, vcc, s48, v8
	s_mov_b32 s48, 0x4a000
	s_nop 0
	v_addc_co_u32_e32 v69, vcc, 0, v9, vcc
; __device__ __forceinline__ void transpose_item(const float* W, int K, int Nsrc, bf16_t* WT, int Ndst, const float* gain, int maptype, LAS float* scr, int item, int lane) {
;     ...
;         for (int i = 0; i < 32; ++i) v[i] = wp[(size_t)(32 * h + i) * Nsrc];
; #pragma unroll
;         for (int i = 0; i < 32; ++i) { float x = (src >= 0) ? v[i] : 0.f; if (gain) x *= gain[k0 + 32 * h + i]; scr[(32 * h + i) * 65 + lane] = x; }
	v_add_co_u32_e32 v70, vcc, s69, v8
	s_nop 1
	v_addc_co_u32_e32 v71, vcc, 0, v9, vcc
	v_add_co_u32_e32 v72, vcc, s48, v8
	s_mov_b32 s48, 0x4c000
	s_nop 0
	v_addc_co_u32_e32 v73, vcc, 0, v9, vcc
	v_add_co_u32_e32 v74, vcc, s48, v8
	s_mov_b32 s48, 0x4e000
	s_nop 0
	v_addc_co_u32_e32 v75, vcc, 0, v9, vcc
	v_add_co_u32_e32 v76, vcc, s48, v8
	s_mov_b32 s48, 0x52000
	s_nop 0
	v_addc_co_u32_e32 v77, vcc, 0, v9, vcc
	global_load_dword v93, v[28:29], off nt
	global_load_dword v94, v[30:31], off nt
	global_load_dword v95, v[66:67], off nt
	global_load_dword v96, v[68:69], off nt
	global_load_dword v97, v[70:71], off nt
	global_load_dword v98, v[72:73], off nt
	global_load_dword v99, v[74:75], off nt
	global_load_dword v100, v[76:77], off nt
	v_add_co_u32_e32 v28, vcc, s34, v8
	s_nop 1
	v_addc_co_u32_e32 v29, vcc, 0, v9, vcc
	v_add_co_u32_e32 v30, vcc, s48, v8
	s_mov_b32 s48, 0x54000
	s_nop 0
	v_addc_co_u32_e32 v31, vcc, 0, v9, vcc
	v_add_co_u32_e32 v66, vcc, s48, v8
	s_mov_b32 s48, 0x56000
	s_nop 0
	v_addc_co_u32_e32 v67, vcc, 0, v9, vcc
	v_add_co_u32_e32 v68, vcc, s48, v8
	s_mov_b32 s48, 0x5c000
	s_nop 0
	v_addc_co_u32_e32 v69, vcc, 0, v9, vcc
	v_add_co_u32_e32 v70, vcc, s8, v8
	s_nop 1
	v_addc_co_u32_e32 v71, vcc, 0, v9, vcc
	v_add_co_u32_e32 v72, vcc, s9, v8
	s_nop 1
	v_addc_co_u32_e32 v73, vcc, 0, v9, vcc
	v_add_co_u32_e32 v74, vcc, s48, v8
	v_readlane_b32 s48, v255, 13
	s_nop 0
	v_addc_co_u32_e32 v75, vcc, 0, v9, vcc
	v_add_co_u32_e32 v76, vcc, s60, v8
	v_readlane_b32 s49, v255, 14
	s_nop 0
	v_addc_co_u32_e32 v77, vcc, 0, v9, vcc
	global_load_dword v101, v[28:29], off nt
	global_load_dword v102, v[30:31], off nt
	global_load_dword v103, v[66:67], off nt
	global_load_dword v104, v[68:69], off nt
	global_load_dword v105, v[70:71], off nt
	global_load_dword v106, v[72:73], off nt
	global_load_dword v107, v[74:75], off nt
	global_load_dword v108, v[76:77], off nt
	v_add_co_u32_e32 v28, vcc, s51, v8
	v_lshl_add_u64 v[6:7], s[48:49], 0, v[6:7]
	s_nop 0
	v_addc_co_u32_e32 v29, vcc, 0, v9, vcc
	v_add_co_u32_e32 v30, vcc, s61, v8
	s_nop 1
	v_addc_co_u32_e32 v31, vcc, 0, v9, vcc
	v_add_co_u32_e32 v66, vcc, s62, v8
	s_nop 1
	v_addc_co_u32_e32 v67, vcc, 0, v9, vcc
	v_add_co_u32_e32 v68, vcc, s63, v8
	s_nop 1
	v_addc_co_u32_e32 v69, vcc, 0, v9, vcc
	v_add_co_u32_e32 v70, vcc, s57, v8
	s_nop 1
	v_addc_co_u32_e32 v71, vcc, 0, v9, vcc
	v_add_co_u32_e32 v72, vcc, s59, v8
	s_nop 1
	v_addc_co_u32_e32 v73, vcc, 0, v9, vcc
	v_add_co_u32_e32 v74, vcc, s54, v8
	s_nop 1
	v_addc_co_u32_e32 v75, vcc, 0, v9, vcc
	v_add_co_u32_e32 v76, vcc, s52, v8
	s_nop 1
	v_addc_co_u32_e32 v77, vcc, 0, v9, vcc
	global_load_dword v109, v[28:29], off nt
	global_load_dword v110, v[30:31], off nt
	global_load_dword v111, v[66:67], off nt
	global_load_dword v112, v[68:69], off nt
	global_load_dword v113, v[70:71], off nt
	global_load_dword v114, v[72:73], off nt
	global_load_dword v115, v[74:75], off nt
	s_nop 0
	global_load_dword v76, v[76:77], off nt
	v_add_co_u32_e32 v28, vcc, s53, v8
	s_nop 1
	v_addc_co_u32_e32 v29, vcc, 0, v9, vcc
	v_add_co_u32_e32 v30, vcc, s55, v8
	s_nop 1
	v_addc_co_u32_e32 v31, vcc, 0, v9, vcc
	v_add_co_u32_e32 v66, vcc, s97, v8
	s_nop 1
	v_addc_co_u32_e32 v67, vcc, 0, v9, vcc
	v_add_co_u32_e32 v68, vcc, s3, v8
	s_nop 1
	v_addc_co_u32_e32 v69, vcc, 0, v9, vcc
	v_add_co_u32_e32 v70, vcc, s85, v8
	s_nop 1
	v_addc_co_u32_e32 v71, vcc, 0, v9, vcc
	v_add_co_u32_e32 v72, vcc, s87, v8
	s_nop 1
	v_addc_co_u32_e32 v73, vcc, 0, v9, vcc
	v_add_co_u32_e32 v74, vcc, s93, v8
	s_nop 1
	v_addc_co_u32_e32 v75, vcc, 0, v9, vcc
	v_add_co_u32_e32 v8, vcc, s11, v8
	s_nop 1
	v_addc_co_u32_e32 v9, vcc, 0, v9, vcc
	global_load_dword v28, v[28:29], off nt
	s_nop 0
	global_load_dword v29, v[30:31], off nt
	s_nop 0
	global_load_dword v30, v[66:67], off nt
	global_load_dword v31, v[68:69], off nt
	s_nop 0
	global_load_dword v66, v[70:71], off nt
	global_load_dword v67, v[72:73], off nt
	global_load_dword v68, v[74:75], off nt
	s_nop 0
	global_load_dword v8, v[8:9], off nt
	s_waitcnt vmcnt(62)
	ds_write2_b32 v32, v12, v13 offset1:65
	s_waitcnt vmcnt(60)
	ds_write2_b32 v32, v14, v15 offset0:130 offset1:195
	s_waitcnt vmcnt(58)
	ds_write2_b32 v47, v16, v17 offset0:4 offset1:69
	s_waitcnt vmcnt(56)
	ds_write2_b32 v47, v18, v19 offset0:134 offset1:199
	s_waitcnt vmcnt(54)
	ds_write2_b32 v48, v20, v21 offset0:8 offset1:73
	s_waitcnt vmcnt(52)
	ds_write2_b32 v48, v22, v23 offset0:138 offset1:203
	s_waitcnt vmcnt(50)
	ds_write2_b32 v49, v24, v25 offset0:12 offset1:77
	s_waitcnt vmcnt(48)
	ds_write2_b32 v49, v26, v27 offset0:142 offset1:207
	s_waitcnt vmcnt(46)
	ds_write2_b32 v50, v65, v78 offset0:16 offset1:81
	s_waitcnt vmcnt(44)
	ds_write2_b32 v50, v79, v80 offset0:146 offset1:211
	s_waitcnt vmcnt(42)
	ds_write2_b32 v51, v81, v82 offset0:20 offset1:85
	s_waitcnt vmcnt(40)
	ds_write2_b32 v51, v83, v84 offset0:150 offset1:215
	s_waitcnt vmcnt(38)
	ds_write2_b32 v52, v85, v86 offset0:24 offset1:89
	s_waitcnt vmcnt(36)
	ds_write2_b32 v52, v87, v88 offset0:154 offset1:219
	s_waitcnt vmcnt(34)
	ds_write2_b32 v53, v89, v90 offset0:28 offset1:93
	s_waitcnt vmcnt(32)
	ds_write2_b32 v53, v91, v92 offset0:158 offset1:223
	s_waitcnt vmcnt(30)
	ds_write2_b32 v54, v93, v94 offset0:32 offset1:97
	s_waitcnt vmcnt(28)
	ds_write2_b32 v54, v95, v96 offset0:162 offset1:227
	s_waitcnt vmcnt(26)
	ds_write2_b32 v55, v97, v98 offset0:36 offset1:101
	s_waitcnt vmcnt(24)
	ds_write2_b32 v55, v99, v100 offset0:166 offset1:231
	s_waitcnt vmcnt(22)
	ds_write2_b32 v56, v101, v102 offset0:40 offset1:105
	s_waitcnt vmcnt(20)
; #define LAS __attribute__((address_space(3)))
; __device__ __forceinline__ unsigned cvt_pk_bf16(float lo, float hi) { unsigned r; asm volatile("v_cvt_pk_bf16_f32 %0, %1, %2" : "=v"(r) : "v"(lo), "v"(hi)); return r; }
; __device__ __forceinline__ void transpose_item(const float* W, int K, int Nsrc, bf16_t* WT, int Ndst, const float* gain, int maptype, LAS float* scr, int item, int lane) {
;     ...
;         for (int i = 0; i < 32; ++i) { float x = (src >= 0) ? v[i] : 0.f; if (gain) x *= gain[k0 + 32 * h + i]; scr[(32 * h + i) * 65 + lane] = x; }
;     }
;     asm volatile("s_waitcnt lgkmcnt(0)" ::: "memory");
;     const int cidx = lane & 7;
; #pragma unroll
;     for (int j = 0; j < 8; ++j) { const int n = (lane >> 3) + 8 * j; const LAS float* s = scr + (8 * cidx) * 65 + n;
;         u32x4 o; o.x = cvt_pk_bf16(s[0 * 65], s[1 * 65]); o.y = cvt_pk_bf16(s[2 * 65], s[3 * 65]); o.z = cvt_pk_bf16(s[4 * 65], s[5 * 65]); o.w = cvt_pk_bf16(s[6 * 65], s[7 * 65]);
;         *(u32x4*)(WT + (size_t)(n0 + n) * K + k0 + 8 * cidx) = o; }
;     asm volatile("s_waitcnt lgkmcnt(0)" ::: "memory");
	ds_write2_b32 v56, v103, v104 offset0:170 offset1:235
	s_waitcnt vmcnt(18)
	ds_write2_b32 v57, v105, v106 offset0:44 offset1:109
	s_waitcnt vmcnt(16)
	ds_write2_b32 v57, v107, v108 offset0:174 offset1:239
	s_waitcnt vmcnt(14)
	ds_write2_b32 v58, v109, v110 offset0:48 offset1:113
	s_waitcnt vmcnt(12)
	ds_write2_b32 v58, v111, v112 offset0:178 offset1:243
	s_waitcnt vmcnt(10)
	ds_write2_b32 v59, v113, v114 offset0:52 offset1:117
	s_waitcnt vmcnt(8)
	ds_write2_b32 v59, v115, v76 offset0:182 offset1:247
	s_waitcnt vmcnt(6)
	ds_write2_b32 v60, v28, v29 offset0:56 offset1:121
	s_waitcnt vmcnt(4)
	ds_write2_b32 v60, v30, v31 offset0:186 offset1:251
	s_waitcnt vmcnt(2)
	ds_write2_b32 v61, v66, v67 offset0:60 offset1:125
	s_waitcnt vmcnt(0)
	ds_write2_b32 v61, v68, v8 offset0:190 offset1:255
	s_waitcnt lgkmcnt(0)
	ds_read2_b32 v[8:9], v34 offset1:65
	s_waitcnt lgkmcnt(0)
	v_cvt_pk_bf16_f32 v12, v8, v9
	ds_read2_b32 v[8:9], v34 offset0:130 offset1:195
	v_lshlrev_b32_e32 v16, 1, v11
	v_mov_b32_e32 v17, v5
	s_waitcnt lgkmcnt(0)
	v_cvt_pk_bf16_f32 v13, v8, v9
	ds_read2_b32 v[8:9], v62 offset0:4 offset1:69
	v_lshl_add_u64 v[6:7], v[6:7], 0, v[16:17]
	v_or_b32_e32 v11, v10, v33
	s_waitcnt lgkmcnt(0)
	v_cvt_pk_bf16_f32 v14, v8, v9
	ds_read2_b32 v[8:9], v62 offset0:134 offset1:199
	v_lshl_add_u64 v[6:7], v[6:7], 0, v[4:5]
	v_lshlrev_b32_e32 v16, 14, v11
	s_waitcnt lgkmcnt(0)
	v_cvt_pk_bf16_f32 v15, v8, v9
	ds_read2_b32 v[8:9], v34 offset0:8 offset1:73
	v_lshl_add_u64 v[16:17], v[6:7], 0, v[16:17]
	global_store_dwordx4 v[16:17], v[12:15], off
	v_or_b32_e32 v11, v10, v35
	v_lshlrev_b32_e32 v16, 14, v11
	s_waitcnt lgkmcnt(0)
	v_cvt_pk_bf16_f32 v12, v8, v9
	ds_read2_b32 v[8:9], v34 offset0:138 offset1:203
	s_waitcnt lgkmcnt(0)
	v_cvt_pk_bf16_f32 v13, v8, v9
	ds_read2_b32 v[8:9], v62 offset0:12 offset1:77
	s_waitcnt lgkmcnt(0)
	v_cvt_pk_bf16_f32 v14, v8, v9
	ds_read2_b32 v[8:9], v62 offset0:142 offset1:207
	v_mov_b32_e32 v17, v5
	s_waitcnt lgkmcnt(0)
	v_cvt_pk_bf16_f32 v15, v8, v9
	ds_read2_b32 v[8:9], v34 offset0:16 offset1:81
	v_lshl_add_u64 v[16:17], v[6:7], 0, v[16:17]
	global_store_dwordx4 v[16:17], v[12:15], off
	v_or_b32_e32 v11, v10, v36
	v_lshlrev_b32_e32 v16, 14, v11
	s_waitcnt lgkmcnt(0)
	v_cvt_pk_bf16_f32 v12, v8, v9
	ds_read2_b32 v[8:9], v34 offset0:146 offset1:211
	s_waitcnt lgkmcnt(0)
	v_cvt_pk_bf16_f32 v13, v8, v9
	ds_read2_b32 v[8:9], v62 offset0:20 offset1:85
	s_waitcnt lgkmcnt(0)
	v_cvt_pk_bf16_f32 v14, v8, v9
	ds_read2_b32 v[8:9], v62 offset0:150 offset1:215
	v_mov_b32_e32 v17, v5
	s_waitcnt lgkmcnt(0)
	v_cvt_pk_bf16_f32 v15, v8, v9
	ds_read2_b32 v[8:9], v34 offset0:24 offset1:89
	v_lshl_add_u64 v[16:17], v[6:7], 0, v[16:17]
	global_store_dwordx4 v[16:17], v[12:15], off
	v_or_b32_e32 v11, v10, v37
	v_lshlrev_b32_e32 v16, 14, v11
	s_waitcnt lgkmcnt(0)
	v_cvt_pk_bf16_f32 v12, v8, v9
	ds_read2_b32 v[8:9], v34 offset0:154 offset1:219
	s_waitcnt lgkmcnt(0)
	v_cvt_pk_bf16_f32 v13, v8, v9
	ds_read2_b32 v[8:9], v62 offset0:28 offset1:93
	s_waitcnt lgkmcnt(0)
	v_cvt_pk_bf16_f32 v14, v8, v9
	ds_read2_b32 v[8:9], v62 offset0:158 offset1:223
	v_mov_b32_e32 v17, v5
	s_waitcnt lgkmcnt(0)
	v_cvt_pk_bf16_f32 v15, v8, v9
	ds_read2_b32 v[8:9], v34 offset0:32 offset1:97
	v_lshl_add_u64 v[16:17], v[6:7], 0, v[16:17]
	global_store_dwordx4 v[16:17], v[12:15], off
	v_or_b32_e32 v11, v10, v38
	v_lshlrev_b32_e32 v16, 14, v11
	s_waitcnt lgkmcnt(0)
	v_cvt_pk_bf16_f32 v12, v8, v9
	ds_read2_b32 v[8:9], v34 offset0:162 offset1:227
	s_waitcnt lgkmcnt(0)
	v_cvt_pk_bf16_f32 v13, v8, v9
	ds_read2_b32 v[8:9], v62 offset0:36 offset1:101
	s_waitcnt lgkmcnt(0)
	v_cvt_pk_bf16_f32 v14, v8, v9
	ds_read2_b32 v[8:9], v62 offset0:166 offset1:231
	v_mov_b32_e32 v17, v5
	s_waitcnt lgkmcnt(0)
	v_cvt_pk_bf16_f32 v15, v8, v9
	ds_read2_b32 v[8:9], v34 offset0:40 offset1:105
	v_lshl_add_u64 v[16:17], v[6:7], 0, v[16:17]
	global_store_dwordx4 v[16:17], v[12:15], off
	v_or_b32_e32 v11, v10, v39
	v_lshlrev_b32_e32 v16, 14, v11
	s_waitcnt lgkmcnt(0)
	v_cvt_pk_bf16_f32 v12, v8, v9
	ds_read2_b32 v[8:9], v34 offset0:170 offset1:235
	s_waitcnt lgkmcnt(0)
	v_cvt_pk_bf16_f32 v13, v8, v9
	ds_read2_b32 v[8:9], v62 offset0:44 offset1:109
	s_waitcnt lgkmcnt(0)
	v_cvt_pk_bf16_f32 v14, v8, v9
	ds_read2_b32 v[8:9], v62 offset0:174 offset1:239
	v_mov_b32_e32 v17, v5
	s_waitcnt lgkmcnt(0)
	v_cvt_pk_bf16_f32 v15, v8, v9
	ds_read2_b32 v[8:9], v34 offset0:48 offset1:113
	v_lshl_add_u64 v[16:17], v[6:7], 0, v[16:17]
	global_store_dwordx4 v[16:17], v[12:15], off
	v_or_b32_e32 v11, v10, v40
	v_lshlrev_b32_e32 v16, 14, v11
	s_waitcnt lgkmcnt(0)
	v_cvt_pk_bf16_f32 v12, v8, v9
	ds_read2_b32 v[8:9], v34 offset0:178 offset1:243
	s_waitcnt lgkmcnt(0)
	v_cvt_pk_bf16_f32 v13, v8, v9
	ds_read2_b32 v[8:9], v62 offset0:52 offset1:117
	s_waitcnt lgkmcnt(0)
	v_cvt_pk_bf16_f32 v14, v8, v9
	ds_read2_b32 v[8:9], v62 offset0:182 offset1:247
	v_mov_b32_e32 v17, v5
	s_waitcnt lgkmcnt(0)
	v_cvt_pk_bf16_f32 v15, v8, v9
	ds_read2_b32 v[8:9], v34 offset0:56 offset1:121
	v_lshl_add_u64 v[16:17], v[6:7], 0, v[16:17]
	global_store_dwordx4 v[16:17], v[12:15], off
	s_waitcnt lgkmcnt(0)
	s_nop 0
	v_cvt_pk_bf16_f32 v12, v8, v9
	ds_read2_b32 v[8:9], v34 offset0:186 offset1:251
	s_waitcnt lgkmcnt(0)
	v_cvt_pk_bf16_f32 v13, v8, v9
	ds_read2_b32 v[8:9], v62 offset0:60 offset1:125
	s_waitcnt lgkmcnt(0)
	v_cvt_pk_bf16_f32 v14, v8, v9
	ds_read2_b32 v[8:9], v62 offset0:190 offset1:255
	s_waitcnt lgkmcnt(0)
	v_cvt_pk_bf16_f32 v15, v8, v9
	v_or_b32_e32 v8, v10, v41
	v_lshlrev_b32_e32 v8, 14, v8
	v_mov_b32_e32 v9, v5
	v_lshl_add_u64 v[6:7], v[6:7], 0, v[8:9]
	global_store_dwordx4 v[6:7], v[12:15], off
	s_waitcnt lgkmcnt(0)

; __device__ __forceinline__ void transpose_item(const float* W, int K, int Nsrc, bf16_t* WT, int Ndst, const float* gain, int maptype, LAS float* scr, int item, int lane) {
;     const int nblk = Ndst / 64, kb = item / nblk, nb = item % nblk, k0 = 64 * kb, n0 = 64 * nb;
;     const int nd = n0 + lane; const int src = (maptype == MAP_IN) ? map_in(nd) : nd;
;     const float* wp = W + (size_t)k0 * Nsrc + (src >= 0 ? src : 0);
; #pragma unroll
;     for (int h = 0; h < 2; ++h) {
;         float v[32];
; #pragma unroll
;         for (int i = 0; i < 32; ++i) v[i] = wp[(size_t)(32 * h + i) * Nsrc];
; #pragma unroll
;         for (int i = 0; i < 32; ++i) { float x = (src >= 0) ? v[i] : 0.f; if (gain) x *= gain[k0 + 32 * h + i]; scr[(32 * h + i) * 65 + lane] = x; }
.LBB0_31:
	s_andn2_saveexec_b64 s[80:81], s[4:5]
	s_cbranch_execz .LBB0_83
	v_add_u32_e32 v8, 0xd580, v9
	v_lshrrev_b32_e32 v8, 1, v8
	v_and_b32_e32 v66, 0x7fc0, v8
	v_lshlrev_b32_e32 v8, 6, v10
	v_readlane_b32 s60, v255, 21
	v_sub_u32_e32 v8, v43, v8
	v_lshlrev_b64 v[12:13], 26, v[6:7]
	v_readlane_b32 s61, v255, 22
	v_and_b32_e32 v65, 0x1fc0, v8
	v_or_b32_e32 v10, v65, v1
	v_lshl_add_u64 v[12:13], s[60:61], 0, v[12:13]
	v_lshlrev_b32_e32 v8, 15, v66
	v_mov_b32_e32 v9, v5
	v_lshl_add_u64 v[8:9], v[12:13], 0, v[8:9]
	v_lshlrev_b32_e32 v10, 2, v10
	v_mov_b32_e32 v11, v5
	v_lshl_add_u64 v[12:13], v[8:9], 0, v[10:11]
	v_add_co_u32_e32 v8, vcc, s88, v12
	s_mov_b32 s4, 0x80000
	s_nop 0
	v_addc_co_u32_e32 v9, vcc, 0, v13, vcc
	v_add_co_u32_e32 v10, vcc, s96, v12
	v_readlane_b32 s48, v255, 19
	s_nop 0
	v_addc_co_u32_e32 v11, vcc, 0, v13, vcc
	v_add_co_u32_e32 v14, vcc, s47, v12
	v_readlane_b32 s49, v255, 20
	s_nop 0
	v_addc_co_u32_e32 v15, vcc, 0, v13, vcc
	v_add_co_u32_e32 v16, vcc, s91, v12
	v_readlane_b32 s62, v255, 23
	s_nop 0
	v_addc_co_u32_e32 v17, vcc, 0, v13, vcc
	v_add_co_u32_e32 v18, vcc, s10, v12
	v_readlane_b32 s63, v255, 24
	s_nop 0
	v_addc_co_u32_e32 v19, vcc, 0, v13, vcc
	v_add_co_u32_e32 v20, vcc, s68, v12
	s_nop 1
	v_addc_co_u32_e32 v21, vcc, 0, v13, vcc
	v_add_co_u32_e32 v22, vcc, s56, v12
	s_nop 1
	v_addc_co_u32_e32 v23, vcc, 0, v13, vcc
	global_load_dword v81, v[12:13], off nt
	global_load_dword v82, v[8:9], off nt
	global_load_dword v28, v[10:11], off nt
	global_load_dword v29, v[14:15], off nt
	global_load_dword v79, v[16:17], off nt
	global_load_dword v80, v[18:19], off nt
	global_load_dword v26, v[20:21], off nt
	global_load_dword v27, v[22:23], off nt
	v_add_co_u32_e32 v8, vcc, s50, v12
	s_nop 1
	v_addc_co_u32_e32 v9, vcc, 0, v13, vcc
	v_add_co_u32_e32 v10, vcc, s69, v12
	s_nop 1
	v_addc_co_u32_e32 v11, vcc, 0, v13, vcc
	v_add_co_u32_e32 v14, vcc, s34, v12
	s_nop 1
	v_addc_co_u32_e32 v15, vcc, 0, v13, vcc
	v_add_co_u32_e32 v16, vcc, s8, v12
	s_nop 1
	v_addc_co_u32_e32 v17, vcc, 0, v13, vcc
	v_add_co_u32_e32 v18, vcc, s51, v12
	s_nop 1
	v_addc_co_u32_e32 v19, vcc, 0, v13, vcc
	v_add_co_u32_e32 v20, vcc, s57, v12
	s_nop 1
	v_addc_co_u32_e32 v21, vcc, 0, v13, vcc
	v_add_co_u32_e32 v22, vcc, s53, v12
	s_nop 1
	v_addc_co_u32_e32 v23, vcc, 0, v13, vcc
	v_add_co_u32_e32 v30, vcc, s85, v12
	s_nop 1
	v_addc_co_u32_e32 v31, vcc, 0, v13, vcc
	global_load_dword v77, v[8:9], off nt
	global_load_dword v78, v[10:11], off nt
	global_load_dword v24, v[14:15], off nt
	global_load_dword v25, v[16:17], off nt
	global_load_dword v73, v[18:19], off nt
	global_load_dword v74, v[20:21], off nt
	s_nop 0
	global_load_dword v20, v[22:23], off nt
	global_load_dword v21, v[30:31], off nt
	v_add_co_u32_e32 v8, vcc, s4, v12
	s_mov_b32 s4, 0x88000
	s_nop 0
	v_addc_co_u32_e32 v9, vcc, 0, v13, vcc
	v_add_co_u32_e32 v10, vcc, s4, v12
	s_mov_b32 s4, 0x90000
	s_nop 0
	v_addc_co_u32_e32 v11, vcc, 0, v13, vcc
	v_add_co_u32_e32 v14, vcc, s4, v12
	s_mov_b32 s4, 0x98000
	s_nop 0
	v_addc_co_u32_e32 v15, vcc, 0, v13, vcc
	v_add_co_u32_e32 v16, vcc, s4, v12
	s_mov_b32 s4, 0xa0000
	s_nop 0
	v_addc_co_u32_e32 v17, vcc, 0, v13, vcc
	v_add_co_u32_e32 v18, vcc, s4, v12
	s_mov_b32 s4, 0xa8000
	s_nop 0
	v_addc_co_u32_e32 v19, vcc, 0, v13, vcc
	v_add_co_u32_e32 v30, vcc, s4, v12
	s_mov_b32 s4, 0xb0000
	s_nop 0
	v_addc_co_u32_e32 v31, vcc, 0, v13, vcc
	v_add_co_u32_e32 v84, vcc, s4, v12
	s_mov_b32 s4, 0xb8000
	s_nop 0
	v_addc_co_u32_e32 v85, vcc, 0, v13, vcc
	v_add_co_u32_e32 v86, vcc, s4, v12
	s_mov_b32 s4, 0xc0000
	s_nop 0
	v_addc_co_u32_e32 v87, vcc, 0, v13, vcc
	global_load_dword v75, v[8:9], off nt
	global_load_dword v76, v[10:11], off nt
	global_load_dword v22, v[14:15], off nt
	global_load_dword v23, v[16:17], off nt
	global_load_dword v69, v[18:19], off nt
	global_load_dword v70, v[30:31], off nt
	s_nop 0
	global_load_dword v16, v[84:85], off nt
	global_load_dword v17, v[86:87], off nt
	v_add_co_u32_e32 v8, vcc, s4, v12
	s_mov_b32 s4, 0xc8000
	s_nop 0
	v_addc_co_u32_e32 v9, vcc, 0, v13, vcc
	v_add_co_u32_e32 v10, vcc, s4, v12
	s_mov_b32 s4, 0xd0000
	s_nop 0
	v_addc_co_u32_e32 v11, vcc, 0, v13, vcc
	v_add_co_u32_e32 v14, vcc, s4, v12
	s_mov_b32 s4, 0xd8000
	s_nop 0
	v_addc_co_u32_e32 v15, vcc, 0, v13, vcc
	v_add_co_u32_e32 v30, vcc, s4, v12
	s_mov_b32 s4, 0xe0000
	s_nop 0
	v_addc_co_u32_e32 v31, vcc, 0, v13, vcc
	v_add_co_u32_e32 v84, vcc, s4, v12
	s_nop 1
	v_addc_co_u32_e32 v85, vcc, 0, v13, vcc
	v_add_co_u32_e32 v86, vcc, 0xe8000, v12
	s_nop 1
	v_addc_co_u32_e32 v87, vcc, 0, v13, vcc
	v_add_co_u32_e32 v88, vcc, 0xf0000, v12
	s_nop 1
	v_addc_co_u32_e32 v89, vcc, 0, v13, vcc
	v_add_co_u32_e32 v90, vcc, 0xf8000, v12
	s_nop 1
	v_addc_co_u32_e32 v91, vcc, 0, v13, vcc
	global_load_dword v71, v[8:9], off nt
	global_load_dword v72, v[10:11], off nt
	global_load_dword v18, v[14:15], off nt
	global_load_dword v19, v[30:31], off nt
	global_load_dword v67, v[84:85], off nt
	global_load_dword v68, v[86:87], off nt
	s_nop 0
	global_load_dword v14, v[88:89], off nt
	global_load_dword v15, v[90:91], off nt
	v_lshlrev_b32_e32 v8, 11, v6
	v_ashrrev_i32_e32 v9, 31, v8
	v_cndmask_b32_e64 v10, 0, 1, s[48:49]
	v_lshl_add_u64 v[8:9], v[8:9], 2, s[42:43]
	v_cmp_ne_u32_e64 s[4:5], 1, v10
	s_andn2_b64 vcc, exec, s[48:49]
	v_lshlrev_b32_e32 v10, 2, v66
	s_cbranch_vccnz .LBB0_34
	v_mov_b32_e32 v11, v5
	v_lshl_add_u64 v[30:31], v[8:9], 0, v[10:11]
	global_load_dwordx4 v[84:87], v[30:31], off
	s_mov_b64 s[82:83], 0
	s_waitcnt vmcnt(0)
	v_mul_f32_e32 v11, v81, v84
	v_mul_f32_e32 v83, v82, v85
	v_pk_mul_f32 v[30:31], v[28:29], v[86:87]
	ds_write2_b32 v32, v11, v83 offset1:65
	s_branch .LBB0_35

; __device__ __forceinline__ void transpose_item(const float* W, int K, int Nsrc, bf16_t* WT, int Ndst, const float* gain, int maptype, LAS float* scr, int item, int lane) {
;     ...
;         for (int i = 0; i < 32; ++i) v[i] = wp[(size_t)(32 * h + i) * Nsrc];
; #pragma unroll
;         for (int i = 0; i < 32; ++i) { float x = (src >= 0) ? v[i] : 0.f; if (gain) x *= gain[k0 + 32 * h + i]; scr[(32 * h + i) * 65 + lane] = x; }
.LBB0_58:
	s_waitcnt vmcnt(1)
	v_add_co_u32_e32 v14, vcc, 0x100000, v12
	s_waitcnt vmcnt(0)
	s_nop 0
	v_addc_co_u32_e32 v15, vcc, 0, v13, vcc
	v_add_co_u32_e32 v16, vcc, 0x108000, v12
	s_nop 1
	v_addc_co_u32_e32 v17, vcc, 0, v13, vcc
	v_add_co_u32_e32 v18, vcc, 0x110000, v12
	s_nop 1
	v_addc_co_u32_e32 v19, vcc, 0, v13, vcc
	v_add_co_u32_e32 v22, vcc, 0x118000, v12
	s_nop 1
	v_addc_co_u32_e32 v23, vcc, 0, v13, vcc
	v_add_co_u32_e32 v24, vcc, 0x120000, v12
	s_nop 1
	v_addc_co_u32_e32 v25, vcc, 0, v13, vcc
	v_add_co_u32_e32 v26, vcc, 0x128000, v12
	s_nop 1
	v_addc_co_u32_e32 v27, vcc, 0, v13, vcc
	v_add_co_u32_e32 v30, vcc, 0x130000, v12
	s_nop 1
	v_addc_co_u32_e32 v31, vcc, 0, v13, vcc
	v_add_co_u32_e32 v68, vcc, 0x138000, v12
	s_nop 1
	v_addc_co_u32_e32 v69, vcc, 0, v13, vcc
	global_load_dword v79, v[14:15], off nt
	global_load_dword v80, v[16:17], off nt
	global_load_dword v28, v[18:19], off nt
	global_load_dword v29, v[22:23], off nt
	global_load_dword v71, v[24:25], off nt
	global_load_dword v72, v[26:27], off nt
	s_nop 0
	global_load_dword v18, v[30:31], off nt
	global_load_dword v19, v[68:69], off nt
	v_add_co_u32_e32 v14, vcc, 0x140000, v12
	s_nop 1
	v_addc_co_u32_e32 v15, vcc, 0, v13, vcc
	v_add_co_u32_e32 v16, vcc, 0x148000, v12
	s_nop 1
	v_addc_co_u32_e32 v17, vcc, 0, v13, vcc
	v_add_co_u32_e32 v22, vcc, 0x150000, v12
	s_nop 1
	v_addc_co_u32_e32 v23, vcc, 0, v13, vcc
	v_add_co_u32_e32 v24, vcc, 0x158000, v12
	s_nop 1
	v_addc_co_u32_e32 v25, vcc, 0, v13, vcc
	v_add_co_u32_e32 v30, vcc, 0x160000, v12
	s_nop 1
	v_addc_co_u32_e32 v31, vcc, 0, v13, vcc
	v_add_co_u32_e32 v74, vcc, 0x168000, v12
	s_nop 1
	v_addc_co_u32_e32 v75, vcc, 0, v13, vcc
	v_add_co_u32_e32 v82, vcc, 0x170000, v12
	s_nop 1
	v_addc_co_u32_e32 v83, vcc, 0, v13, vcc
	v_add_co_u32_e32 v84, vcc, 0x178000, v12
	s_nop 1
	v_addc_co_u32_e32 v85, vcc, 0, v13, vcc
	global_load_dword v77, v[14:15], off nt
	global_load_dword v78, v[16:17], off nt
	global_load_dword v26, v[22:23], off nt
	global_load_dword v27, v[24:25], off nt
	global_load_dword v69, v[30:31], off nt
	global_load_dword v70, v[74:75], off nt
	s_nop 0
	global_load_dword v16, v[82:83], off nt
	global_load_dword v17, v[84:85], off nt
	v_add_co_u32_e32 v14, vcc, 0x180000, v12
	s_nop 1
	v_addc_co_u32_e32 v15, vcc, 0, v13, vcc
	v_add_co_u32_e32 v22, vcc, 0x188000, v12
	s_nop 1
	v_addc_co_u32_e32 v23, vcc, 0, v13, vcc
	v_add_co_u32_e32 v24, vcc, 0x190000, v12
	s_nop 1
	v_addc_co_u32_e32 v25, vcc, 0, v13, vcc
	v_add_co_u32_e32 v30, vcc, 0x198000, v12
	s_nop 1
	v_addc_co_u32_e32 v31, vcc, 0, v13, vcc
	v_add_co_u32_e32 v82, vcc, 0x1a0000, v12
	s_nop 1
	v_addc_co_u32_e32 v83, vcc, 0, v13, vcc
	v_add_co_u32_e32 v84, vcc, 0x1a8000, v12
	s_nop 1
	v_addc_co_u32_e32 v85, vcc, 0, v13, vcc
	v_add_co_u32_e32 v86, vcc, 0x1b0000, v12
	s_nop 1
	v_addc_co_u32_e32 v87, vcc, 0, v13, vcc
	v_add_co_u32_e32 v88, vcc, 0x1b8000, v12
	s_nop 1
	v_addc_co_u32_e32 v89, vcc, 0, v13, vcc
	global_load_dword v75, v[14:15], off nt
	global_load_dword v76, v[22:23], off nt
	s_nop 0
	global_load_dword v24, v[24:25], off nt
	s_nop 0
	global_load_dword v25, v[30:31], off nt
	global_load_dword v67, v[82:83], off nt
	global_load_dword v68, v[84:85], off nt
	global_load_dword v14, v[86:87], off nt
	global_load_dword v15, v[88:89], off nt
	v_add_co_u32_e32 v22, vcc, 0x1c0000, v12
	s_nop 1
	v_addc_co_u32_e32 v23, vcc, 0, v13, vcc
	v_add_co_u32_e32 v30, vcc, 0x1c8000, v12
	s_nop 1
	v_addc_co_u32_e32 v31, vcc, 0, v13, vcc
	v_add_co_u32_e32 v82, vcc, 0x1d0000, v12
	s_nop 1
	v_addc_co_u32_e32 v83, vcc, 0, v13, vcc
	v_add_co_u32_e32 v84, vcc, 0x1d8000, v12
	s_nop 1
	v_addc_co_u32_e32 v85, vcc, 0, v13, vcc
	v_add_co_u32_e32 v86, vcc, 0x1e0000, v12
	s_nop 1
	v_addc_co_u32_e32 v87, vcc, 0, v13, vcc
	v_add_co_u32_e32 v88, vcc, 0x1e8000, v12
	s_nop 1
	v_addc_co_u32_e32 v89, vcc, 0, v13, vcc
	v_add_co_u32_e32 v90, vcc, 0x1f0000, v12
	s_nop 1
	v_addc_co_u32_e32 v91, vcc, 0, v13, vcc
	v_add_co_u32_e32 v92, vcc, 0x1f8000, v12
	s_nop 1
	v_addc_co_u32_e32 v93, vcc, 0, v13, vcc
	global_load_dword v73, v[22:23], off nt
	global_load_dword v74, v[30:31], off nt
	s_nop 0
	global_load_dword v22, v[82:83], off nt
	global_load_dword v23, v[84:85], off nt
	global_load_dword v30, v[86:87], off nt
	global_load_dword v31, v[88:89], off nt
	global_load_dword v12, v[90:91], off nt
	global_load_dword v13, v[92:93], off nt
	s_and_b64 vcc, exec, s[4:5]
	ds_write2_b32 v53, v20, v21 offset0:158 offset1:223
	s_cbranch_vccnz .LBB0_251
	v_mov_b32_e32 v11, v5
	v_lshl_add_u64 v[20:21], v[8:9], 0, v[10:11]
	global_load_dwordx4 v[82:85], v[20:21], off offset:128
	s_waitcnt vmcnt(0)
	v_mul_f32_e32 v11, v79, v82
	v_mul_f32_e32 v81, v80, v83
	v_pk_mul_f32 v[20:21], v[28:29], v[84:85]
	ds_write2_b32 v54, v11, v81 offset0:32 offset1:97
	s_cbranch_execnz .LBB0_61

; __device__ __forceinline__ void transpose_item(const float* W, int K, int Nsrc, bf16_t* WT, int Ndst, const float* gain, int maptype, LAS float* scr, int item, int lane) {
;     const int nblk = Ndst / 64, kb = item / nblk, nb = item % nblk, k0 = 64 * kb, n0 = 64 * nb;
;     const int nd = n0 + lane; const int src = (maptype == MAP_IN) ? map_in(nd) : nd;
;     const float* wp = W + (size_t)k0 * Nsrc + (src >= 0 ? src : 0);
; #pragma unroll
;     for (int h = 0; h < 2; ++h) {
;         float v[32];
; #pragma unroll
;         for (int i = 0; i < 32; ++i) v[i] = wp[(size_t)(32 * h + i) * Nsrc];
.LBB0_84:
	s_andn2_saveexec_b64 s[4:5], s[78:79]
	s_cbranch_execz .LBB0_86
	v_lshlrev_b32_e32 v11, 1, v10
	v_sub_u32_e32 v11, v44, v11
	v_lshlrev_b32_e32 v10, 6, v10
	v_add_u32_e32 v11, 0xfffff000, v11
	v_sub_u32_e32 v10, v43, v10
	v_lshlrev_b64 v[8:9], 24, v[6:7]
	v_and_b32_e32 v11, 0x1ffc0, v11
	v_and_b32_e32 v10, 0x7c0, v10
	v_lshl_add_u64 v[8:9], s[40:41], 0, v[8:9]
	v_or_b32_e32 v14, v10, v1
	v_lshlrev_b32_e32 v12, 13, v11
	v_mov_b32_e32 v13, v5
	v_lshl_add_u64 v[8:9], v[8:9], 0, v[12:13]
	v_lshlrev_b32_e32 v12, 2, v14
	v_lshl_add_u64 v[8:9], v[8:9], 0, v[12:13]
	v_add_co_u32_e32 v14, vcc, s35, v8
	s_mov_b32 s48, 0x12000
	s_nop 0
	v_addc_co_u32_e32 v15, vcc, 0, v9, vcc
	v_add_co_u32_e32 v16, vcc, s84, v8
	v_lshlrev_b64 v[6:7], 23, v[6:7]
	s_nop 0
	v_addc_co_u32_e32 v17, vcc, 0, v9, vcc
	v_add_co_u32_e32 v18, vcc, s86, v8
	s_nop 1
	v_addc_co_u32_e32 v19, vcc, 0, v9, vcc
	v_add_co_u32_e32 v20, vcc, s88, v8
	s_nop 1
	v_addc_co_u32_e32 v21, vcc, 0, v9, vcc
	v_add_co_u32_e32 v22, vcc, s90, v8
	s_nop 1
	v_addc_co_u32_e32 v23, vcc, 0, v9, vcc
	v_add_co_u32_e32 v24, vcc, s92, v8
	s_nop 1
	v_addc_co_u32_e32 v25, vcc, 0, v9, vcc
	v_add_co_u32_e32 v26, vcc, s94, v8
	s_nop 1
	v_addc_co_u32_e32 v27, vcc, 0, v9, vcc
	global_load_dword v12, v[8:9], off nt
	global_load_dword v13, v[14:15], off nt
	s_nop 0
	global_load_dword v14, v[16:17], off nt
	global_load_dword v15, v[18:19], off nt
	s_nop 0
	global_load_dword v16, v[20:21], off nt
	global_load_dword v17, v[22:23], off nt
	global_load_dword v18, v[24:25], off nt
	global_load_dword v19, v[26:27], off nt
	v_add_co_u32_e32 v20, vcc, s96, v8
	s_nop 1
	v_addc_co_u32_e32 v21, vcc, 0, v9, vcc
	v_add_co_u32_e32 v22, vcc, s48, v8
	s_mov_b32 s48, 0x14000
	s_nop 0
	v_addc_co_u32_e32 v23, vcc, 0, v9, vcc
	v_add_co_u32_e32 v24, vcc, s48, v8
	s_mov_b32 s48, 0x16000
	s_nop 0
	v_addc_co_u32_e32 v25, vcc, 0, v9, vcc
	v_add_co_u32_e32 v26, vcc, s48, v8
	s_mov_b32 s48, 0x1a000
	s_nop 0
	v_addc_co_u32_e32 v27, vcc, 0, v9, vcc
	v_add_co_u32_e32 v28, vcc, s47, v8
	s_nop 1
	v_addc_co_u32_e32 v29, vcc, 0, v9, vcc
	v_add_co_u32_e32 v30, vcc, s48, v8
	s_mov_b32 s48, 0x1c000
	s_nop 0
	v_addc_co_u32_e32 v31, vcc, 0, v9, vcc
	v_add_co_u32_e32 v66, vcc, s48, v8
	s_mov_b32 s48, 0x22000
	s_nop 0
	v_addc_co_u32_e32 v67, vcc, 0, v9, vcc
	v_add_co_u32_e32 v68, vcc, s89, v8
	s_nop 1
	v_addc_co_u32_e32 v69, vcc, 0, v9, vcc
	global_load_dword v20, v[20:21], off nt
	s_nop 0
	global_load_dword v21, v[22:23], off nt
	s_nop 0
	global_load_dword v22, v[24:25], off nt
	global_load_dword v23, v[26:27], off nt
	s_nop 0
	global_load_dword v24, v[28:29], off nt
	global_load_dword v25, v[30:31], off nt
	global_load_dword v26, v[66:67], off nt
	global_load_dword v27, v[68:69], off nt
	v_add_co_u32_e32 v28, vcc, s91, v8
	s_nop 1
	v_addc_co_u32_e32 v29, vcc, 0, v9, vcc
	v_add_co_u32_e32 v30, vcc, s48, v8
	s_mov_b32 s48, 0x24000
	s_nop 0
	v_addc_co_u32_e32 v31, vcc, 0, v9, vcc
	v_add_co_u32_e32 v66, vcc, s48, v8
	s_mov_b32 s48, 0x26000
	s_nop 0
	v_addc_co_u32_e32 v67, vcc, 0, v9, vcc
	v_add_co_u32_e32 v68, vcc, s48, v8
	s_mov_b32 s48, 0x2a000
	s_nop 0
	v_addc_co_u32_e32 v69, vcc, 0, v9, vcc
	v_add_co_u32_e32 v70, vcc, s10, v8
	s_nop 1
	v_addc_co_u32_e32 v71, vcc, 0, v9, vcc
	v_add_co_u32_e32 v72, vcc, s48, v8
	s_mov_b32 s48, 0x2c000
	s_nop 0
	v_addc_co_u32_e32 v73, vcc, 0, v9, vcc
	v_add_co_u32_e32 v74, vcc, s48, v8
	s_mov_b32 s48, 0x2e000
	s_nop 0
	v_addc_co_u32_e32 v75, vcc, 0, v9, vcc
	v_add_co_u32_e32 v76, vcc, s48, v8
	s_mov_b32 s48, 0x32000
	s_nop 0
	v_addc_co_u32_e32 v77, vcc, 0, v9, vcc
	global_load_dword v65, v[28:29], off nt
	global_load_dword v78, v[30:31], off nt
	global_load_dword v79, v[66:67], off nt
	global_load_dword v80, v[68:69], off nt
	global_load_dword v81, v[70:71], off nt
	global_load_dword v82, v[72:73], off nt
	global_load_dword v83, v[74:75], off nt
	global_load_dword v84, v[76:77], off nt
	v_add_co_u32_e32 v28, vcc, s68, v8
	s_nop 1
	v_addc_co_u32_e32 v29, vcc, 0, v9, vcc
	v_add_co_u32_e32 v30, vcc, s48, v8
	s_mov_b32 s48, 0x34000
	s_nop 0
	v_addc_co_u32_e32 v31, vcc, 0, v9, vcc
	v_add_co_u32_e32 v66, vcc, s48, v8
	s_mov_b32 s48, 0x36000
	s_nop 0
	v_addc_co_u32_e32 v67, vcc, 0, v9, vcc
	v_add_co_u32_e32 v68, vcc, s48, v8
	s_mov_b32 s48, 0x3a000
	s_nop 0
	v_addc_co_u32_e32 v69, vcc, 0, v9, vcc
	v_add_co_u32_e32 v70, vcc, s56, v8
	s_nop 1
	v_addc_co_u32_e32 v71, vcc, 0, v9, vcc
	v_add_co_u32_e32 v72, vcc, s48, v8
	s_mov_b32 s48, 0x3e000
	s_nop 0
	v_addc_co_u32_e32 v73, vcc, 0, v9, vcc
	v_add_co_u32_e32 v74, vcc, s58, v8
	s_nop 1
	v_addc_co_u32_e32 v75, vcc, 0, v9, vcc
	v_add_co_u32_e32 v76, vcc, s48, v8
	s_mov_b32 s48, 0x42000
	s_nop 0
	v_addc_co_u32_e32 v77, vcc, 0, v9, vcc
	global_load_dword v85, v[28:29], off nt
	global_load_dword v86, v[30:31], off nt
	global_load_dword v87, v[66:67], off nt
	global_load_dword v88, v[68:69], off nt
	global_load_dword v89, v[70:71], off nt
	global_load_dword v90, v[72:73], off nt
	global_load_dword v91, v[74:75], off nt
	global_load_dword v92, v[76:77], off nt
	v_add_co_u32_e32 v28, vcc, s50, v8
	s_nop 1
	v_addc_co_u32_e32 v29, vcc, 0, v9, vcc
	v_add_co_u32_e32 v30, vcc, s48, v8
	s_mov_b32 s48, 0x44000
	s_nop 0
	v_addc_co_u32_e32 v31, vcc, 0, v9, vcc
	v_add_co_u32_e32 v66, vcc, s48, v8
	s_mov_b32 s48, 0x46000
	s_nop 0
	v_addc_co_u32_e32 v67, vcc, 0, v9, vcc
	v_add_co_u32_e32 v68, vcc, s48, v8
	s_mov_b32 s48, 0x4a000
	s_nop 0
	v_addc_co_u32_e32 v69, vcc, 0, v9, vcc
	v_add_co_u32_e32 v70, vcc, s69, v8
	s_nop 1
	v_addc_co_u32_e32 v71, vcc, 0, v9, vcc
	v_add_co_u32_e32 v72, vcc, s48, v8
	s_mov_b32 s48, 0x4c000
	s_nop 0
	v_addc_co_u32_e32 v73, vcc, 0, v9, vcc
	v_add_co_u32_e32 v74, vcc, s48, v8
; __device__ __forceinline__ void transpose_item(const float* W, int K, int Nsrc, bf16_t* WT, int Ndst, const float* gain, int maptype, LAS float* scr, int item, int lane) {
;     ...
;         for (int i = 0; i < 32; ++i) v[i] = wp[(size_t)(32 * h + i) * Nsrc];
; #pragma unroll
;         for (int i = 0; i < 32; ++i) { float x = (src >= 0) ? v[i] : 0.f; if (gain) x *= gain[k0 + 32 * h + i]; scr[(32 * h + i) * 65 + lane] = x; }
	s_mov_b32 s48, 0x4e000
	s_nop 0
	v_addc_co_u32_e32 v75, vcc, 0, v9, vcc
	v_add_co_u32_e32 v76, vcc, s48, v8
	s_mov_b32 s48, 0x52000
	s_nop 0
	v_addc_co_u32_e32 v77, vcc, 0, v9, vcc
	global_load_dword v93, v[28:29], off nt
	global_load_dword v94, v[30:31], off nt
	global_load_dword v95, v[66:67], off nt
	global_load_dword v96, v[68:69], off nt
	global_load_dword v97, v[70:71], off nt
	global_load_dword v98, v[72:73], off nt
	global_load_dword v99, v[74:75], off nt
	global_load_dword v100, v[76:77], off nt
	v_add_co_u32_e32 v28, vcc, s34, v8
	s_nop 1
	v_addc_co_u32_e32 v29, vcc, 0, v9, vcc
	v_add_co_u32_e32 v30, vcc, s48, v8
	s_mov_b32 s48, 0x54000
	s_nop 0
	v_addc_co_u32_e32 v31, vcc, 0, v9, vcc
	v_add_co_u32_e32 v66, vcc, s48, v8
	s_mov_b32 s48, 0x56000
	s_nop 0
	v_addc_co_u32_e32 v67, vcc, 0, v9, vcc
	v_add_co_u32_e32 v68, vcc, s48, v8
	s_mov_b32 s48, 0x5c000
	s_nop 0
	v_addc_co_u32_e32 v69, vcc, 0, v9, vcc
	v_add_co_u32_e32 v70, vcc, s8, v8
	s_nop 1
	v_addc_co_u32_e32 v71, vcc, 0, v9, vcc
	v_add_co_u32_e32 v72, vcc, s9, v8
	s_nop 1
	v_addc_co_u32_e32 v73, vcc, 0, v9, vcc
	v_add_co_u32_e32 v74, vcc, s48, v8
	v_readlane_b32 s48, v255, 17
	s_nop 0
	v_addc_co_u32_e32 v75, vcc, 0, v9, vcc
	v_add_co_u32_e32 v76, vcc, s60, v8
	v_readlane_b32 s49, v255, 18
	s_nop 0
	v_addc_co_u32_e32 v77, vcc, 0, v9, vcc
	global_load_dword v101, v[28:29], off nt
	global_load_dword v102, v[30:31], off nt
	global_load_dword v103, v[66:67], off nt
	global_load_dword v104, v[68:69], off nt
	global_load_dword v105, v[70:71], off nt
	global_load_dword v106, v[72:73], off nt
	global_load_dword v107, v[74:75], off nt
	global_load_dword v108, v[76:77], off nt
	v_add_co_u32_e32 v28, vcc, s51, v8
	v_lshl_add_u64 v[6:7], s[48:49], 0, v[6:7]
	s_nop 0
	v_addc_co_u32_e32 v29, vcc, 0, v9, vcc
	v_add_co_u32_e32 v30, vcc, s61, v8
	s_nop 1
	v_addc_co_u32_e32 v31, vcc, 0, v9, vcc
	v_add_co_u32_e32 v66, vcc, s62, v8
	s_nop 1
	v_addc_co_u32_e32 v67, vcc, 0, v9, vcc
	v_add_co_u32_e32 v68, vcc, s63, v8
	s_nop 1
	v_addc_co_u32_e32 v69, vcc, 0, v9, vcc
	v_add_co_u32_e32 v70, vcc, s57, v8
	s_nop 1
	v_addc_co_u32_e32 v71, vcc, 0, v9, vcc
	v_add_co_u32_e32 v72, vcc, s59, v8
	s_nop 1
	v_addc_co_u32_e32 v73, vcc, 0, v9, vcc
	v_add_co_u32_e32 v74, vcc, s54, v8
	s_nop 1
	v_addc_co_u32_e32 v75, vcc, 0, v9, vcc
	v_add_co_u32_e32 v76, vcc, s52, v8
	s_nop 1
	v_addc_co_u32_e32 v77, vcc, 0, v9, vcc
	global_load_dword v109, v[28:29], off nt
	global_load_dword v110, v[30:31], off nt
	global_load_dword v111, v[66:67], off nt
	global_load_dword v112, v[68:69], off nt
	global_load_dword v113, v[70:71], off nt
	global_load_dword v114, v[72:73], off nt
	global_load_dword v115, v[74:75], off nt
	s_nop 0
	global_load_dword v76, v[76:77], off nt
	v_add_co_u32_e32 v28, vcc, s53, v8
	s_nop 1
	v_addc_co_u32_e32 v29, vcc, 0, v9, vcc
	v_add_co_u32_e32 v30, vcc, s55, v8
	s_nop 1
	v_addc_co_u32_e32 v31, vcc, 0, v9, vcc
	v_add_co_u32_e32 v66, vcc, s97, v8
	s_nop 1
	v_addc_co_u32_e32 v67, vcc, 0, v9, vcc
	v_add_co_u32_e32 v68, vcc, s3, v8
	s_nop 1
	v_addc_co_u32_e32 v69, vcc, 0, v9, vcc
	v_add_co_u32_e32 v70, vcc, s85, v8
	s_nop 1
	v_addc_co_u32_e32 v71, vcc, 0, v9, vcc
	v_add_co_u32_e32 v72, vcc, s87, v8
	s_nop 1
	v_addc_co_u32_e32 v73, vcc, 0, v9, vcc
	v_add_co_u32_e32 v74, vcc, s93, v8
	s_nop 1
	v_addc_co_u32_e32 v75, vcc, 0, v9, vcc
	v_add_co_u32_e32 v8, vcc, s11, v8
	s_nop 1
	v_addc_co_u32_e32 v9, vcc, 0, v9, vcc
	global_load_dword v28, v[28:29], off nt
	s_nop 0
	global_load_dword v29, v[30:31], off nt
	s_nop 0
	global_load_dword v30, v[66:67], off nt
	global_load_dword v31, v[68:69], off nt
	s_nop 0
	global_load_dword v66, v[70:71], off nt
	global_load_dword v67, v[72:73], off nt
	global_load_dword v68, v[74:75], off nt
	s_nop 0
	global_load_dword v8, v[8:9], off nt
	s_waitcnt vmcnt(62)
	ds_write2_b32 v32, v12, v13 offset1:65
	s_waitcnt vmcnt(60)
	ds_write2_b32 v32, v14, v15 offset0:130 offset1:195
	s_waitcnt vmcnt(58)
	ds_write2_b32 v47, v16, v17 offset0:4 offset1:69
	s_waitcnt vmcnt(56)
	ds_write2_b32 v47, v18, v19 offset0:134 offset1:199
	s_waitcnt vmcnt(54)
	ds_write2_b32 v48, v20, v21 offset0:8 offset1:73
	s_waitcnt vmcnt(52)
	ds_write2_b32 v48, v22, v23 offset0:138 offset1:203
	s_waitcnt vmcnt(50)
	ds_write2_b32 v49, v24, v25 offset0:12 offset1:77
	s_waitcnt vmcnt(48)
	ds_write2_b32 v49, v26, v27 offset0:142 offset1:207
	s_waitcnt vmcnt(46)
	ds_write2_b32 v50, v65, v78 offset0:16 offset1:81
	s_waitcnt vmcnt(44)
	ds_write2_b32 v50, v79, v80 offset0:146 offset1:211
	s_waitcnt vmcnt(42)
	ds_write2_b32 v51, v81, v82 offset0:20 offset1:85
	s_waitcnt vmcnt(40)
	ds_write2_b32 v51, v83, v84 offset0:150 offset1:215
	s_waitcnt vmcnt(38)
	ds_write2_b32 v52, v85, v86 offset0:24 offset1:89
	s_waitcnt vmcnt(36)
	ds_write2_b32 v52, v87, v88 offset0:154 offset1:219
	s_waitcnt vmcnt(34)
	ds_write2_b32 v53, v89, v90 offset0:28 offset1:93
	s_waitcnt vmcnt(32)
	ds_write2_b32 v53, v91, v92 offset0:158 offset1:223
	s_waitcnt vmcnt(30)
	ds_write2_b32 v54, v93, v94 offset0:32 offset1:97
	s_waitcnt vmcnt(28)
	ds_write2_b32 v54, v95, v96 offset0:162 offset1:227
	s_waitcnt vmcnt(26)
	ds_write2_b32 v55, v97, v98 offset0:36 offset1:101
	s_waitcnt vmcnt(24)
	ds_write2_b32 v55, v99, v100 offset0:166 offset1:231
	s_waitcnt vmcnt(22)
	ds_write2_b32 v56, v101, v102 offset0:40 offset1:105
	s_waitcnt vmcnt(20)
	ds_write2_b32 v56, v103, v104 offset0:170 offset1:235
	s_waitcnt vmcnt(18)
	ds_write2_b32 v57, v105, v106 offset0:44 offset1:109
	s_waitcnt vmcnt(16)
; #define LAS __attribute__((address_space(3)))
; __device__ __forceinline__ unsigned cvt_pk_bf16(float lo, float hi) { unsigned r; asm volatile("v_cvt_pk_bf16_f32 %0, %1, %2" : "=v"(r) : "v"(lo), "v"(hi)); return r; }
; __device__ __forceinline__ void transpose_item(const float* W, int K, int Nsrc, bf16_t* WT, int Ndst, const float* gain, int maptype, LAS float* scr, int item, int lane) {
;     ...
;         for (int i = 0; i < 32; ++i) { float x = (src >= 0) ? v[i] : 0.f; if (gain) x *= gain[k0 + 32 * h + i]; scr[(32 * h + i) * 65 + lane] = x; }
;     }
;     asm volatile("s_waitcnt lgkmcnt(0)" ::: "memory");
;     const int cidx = lane & 7;
; #pragma unroll
;     for (int j = 0; j < 8; ++j) { const int n = (lane >> 3) + 8 * j; const LAS float* s = scr + (8 * cidx) * 65 + n;
;         u32x4 o; o.x = cvt_pk_bf16(s[0 * 65], s[1 * 65]); o.y = cvt_pk_bf16(s[2 * 65], s[3 * 65]); o.z = cvt_pk_bf16(s[4 * 65], s[5 * 65]); o.w = cvt_pk_bf16(s[6 * 65], s[7 * 65]);
;         *(u32x4*)(WT + (size_t)(n0 + n) * K + k0 + 8 * cidx) = o; }
;     asm volatile("s_waitcnt lgkmcnt(0)" ::: "memory");
	ds_write2_b32 v57, v107, v108 offset0:174 offset1:239
	s_waitcnt vmcnt(14)
	ds_write2_b32 v58, v109, v110 offset0:48 offset1:113
	s_waitcnt vmcnt(12)
	ds_write2_b32 v58, v111, v112 offset0:178 offset1:243
	s_waitcnt vmcnt(10)
	ds_write2_b32 v59, v113, v114 offset0:52 offset1:117
	s_waitcnt vmcnt(8)
	ds_write2_b32 v59, v115, v76 offset0:182 offset1:247
	s_waitcnt vmcnt(6)
	ds_write2_b32 v60, v28, v29 offset0:56 offset1:121
	s_waitcnt vmcnt(4)
	ds_write2_b32 v60, v30, v31 offset0:186 offset1:251
	s_waitcnt vmcnt(2)
	ds_write2_b32 v61, v66, v67 offset0:60 offset1:125
	s_waitcnt vmcnt(0)
	ds_write2_b32 v61, v68, v8 offset0:190 offset1:255
	s_waitcnt lgkmcnt(0)
	ds_read2_b32 v[8:9], v34 offset1:65
	s_waitcnt lgkmcnt(0)
	v_cvt_pk_bf16_f32 v12, v8, v9
	ds_read2_b32 v[8:9], v34 offset0:130 offset1:195
	v_lshlrev_b32_e32 v16, 1, v11
	v_mov_b32_e32 v17, v5
	s_waitcnt lgkmcnt(0)
	v_cvt_pk_bf16_f32 v13, v8, v9
	ds_read2_b32 v[8:9], v62 offset0:4 offset1:69
	v_lshl_add_u64 v[6:7], v[6:7], 0, v[16:17]
	v_or_b32_e32 v11, v10, v33
	s_waitcnt lgkmcnt(0)
	v_cvt_pk_bf16_f32 v14, v8, v9
	ds_read2_b32 v[8:9], v62 offset0:134 offset1:199
	v_lshl_add_u64 v[6:7], v[6:7], 0, v[4:5]
	v_lshlrev_b32_e32 v16, 12, v11
	s_waitcnt lgkmcnt(0)
	v_cvt_pk_bf16_f32 v15, v8, v9
	ds_read2_b32 v[8:9], v34 offset0:8 offset1:73
	v_lshl_add_u64 v[16:17], v[6:7], 0, v[16:17]
	global_store_dwordx4 v[16:17], v[12:15], off
	v_or_b32_e32 v11, v10, v35
	v_lshlrev_b32_e32 v16, 12, v11
	s_waitcnt lgkmcnt(0)
	v_cvt_pk_bf16_f32 v12, v8, v9
	ds_read2_b32 v[8:9], v34 offset0:138 offset1:203
	s_waitcnt lgkmcnt(0)
	v_cvt_pk_bf16_f32 v13, v8, v9
	ds_read2_b32 v[8:9], v62 offset0:12 offset1:77
	s_waitcnt lgkmcnt(0)
	v_cvt_pk_bf16_f32 v14, v8, v9
	ds_read2_b32 v[8:9], v62 offset0:142 offset1:207
	v_mov_b32_e32 v17, v5
	s_waitcnt lgkmcnt(0)
	v_cvt_pk_bf16_f32 v15, v8, v9
	ds_read2_b32 v[8:9], v34 offset0:16 offset1:81
	v_lshl_add_u64 v[16:17], v[6:7], 0, v[16:17]
	global_store_dwordx4 v[16:17], v[12:15], off
	v_or_b32_e32 v11, v10, v36
	v_lshlrev_b32_e32 v16, 12, v11
	s_waitcnt lgkmcnt(0)
	v_cvt_pk_bf16_f32 v12, v8, v9
	ds_read2_b32 v[8:9], v34 offset0:146 offset1:211
	s_waitcnt lgkmcnt(0)
	v_cvt_pk_bf16_f32 v13, v8, v9
	ds_read2_b32 v[8:9], v62 offset0:20 offset1:85
	s_waitcnt lgkmcnt(0)
	v_cvt_pk_bf16_f32 v14, v8, v9
	ds_read2_b32 v[8:9], v62 offset0:150 offset1:215
	v_mov_b32_e32 v17, v5
	s_waitcnt lgkmcnt(0)
	v_cvt_pk_bf16_f32 v15, v8, v9
	ds_read2_b32 v[8:9], v34 offset0:24 offset1:89
	v_lshl_add_u64 v[16:17], v[6:7], 0, v[16:17]
	global_store_dwordx4 v[16:17], v[12:15], off
	v_or_b32_e32 v11, v10, v37
	v_lshlrev_b32_e32 v16, 12, v11
	s_waitcnt lgkmcnt(0)
	v_cvt_pk_bf16_f32 v12, v8, v9
	ds_read2_b32 v[8:9], v34 offset0:154 offset1:219
	s_waitcnt lgkmcnt(0)
	v_cvt_pk_bf16_f32 v13, v8, v9
	ds_read2_b32 v[8:9], v62 offset0:28 offset1:93
	s_waitcnt lgkmcnt(0)
	v_cvt_pk_bf16_f32 v14, v8, v9
	ds_read2_b32 v[8:9], v62 offset0:158 offset1:223
	v_mov_b32_e32 v17, v5
	s_waitcnt lgkmcnt(0)
	v_cvt_pk_bf16_f32 v15, v8, v9
	ds_read2_b32 v[8:9], v34 offset0:32 offset1:97
	v_lshl_add_u64 v[16:17], v[6:7], 0, v[16:17]
	global_store_dwordx4 v[16:17], v[12:15], off
	v_or_b32_e32 v11, v10, v38
	v_lshlrev_b32_e32 v16, 12, v11
	s_waitcnt lgkmcnt(0)
	v_cvt_pk_bf16_f32 v12, v8, v9
	ds_read2_b32 v[8:9], v34 offset0:162 offset1:227
	s_waitcnt lgkmcnt(0)
	v_cvt_pk_bf16_f32 v13, v8, v9
	ds_read2_b32 v[8:9], v62 offset0:36 offset1:101
	s_waitcnt lgkmcnt(0)
	v_cvt_pk_bf16_f32 v14, v8, v9
	ds_read2_b32 v[8:9], v62 offset0:166 offset1:231
	v_mov_b32_e32 v17, v5
	s_waitcnt lgkmcnt(0)
	v_cvt_pk_bf16_f32 v15, v8, v9
	ds_read2_b32 v[8:9], v34 offset0:40 offset1:105
	v_lshl_add_u64 v[16:17], v[6:7], 0, v[16:17]
	global_store_dwordx4 v[16:17], v[12:15], off
	v_or_b32_e32 v11, v10, v39
	v_lshlrev_b32_e32 v16, 12, v11
	s_waitcnt lgkmcnt(0)
	v_cvt_pk_bf16_f32 v12, v8, v9
	ds_read2_b32 v[8:9], v34 offset0:170 offset1:235
	s_waitcnt lgkmcnt(0)
	v_cvt_pk_bf16_f32 v13, v8, v9
	ds_read2_b32 v[8:9], v62 offset0:44 offset1:109
	s_waitcnt lgkmcnt(0)
	v_cvt_pk_bf16_f32 v14, v8, v9
	ds_read2_b32 v[8:9], v62 offset0:174 offset1:239
	v_mov_b32_e32 v17, v5
	s_waitcnt lgkmcnt(0)
	v_cvt_pk_bf16_f32 v15, v8, v9
	ds_read2_b32 v[8:9], v34 offset0:48 offset1:113
	v_lshl_add_u64 v[16:17], v[6:7], 0, v[16:17]
	global_store_dwordx4 v[16:17], v[12:15], off
	v_or_b32_e32 v11, v10, v40
	v_lshlrev_b32_e32 v16, 12, v11
	s_waitcnt lgkmcnt(0)
	v_cvt_pk_bf16_f32 v12, v8, v9
	ds_read2_b32 v[8:9], v34 offset0:178 offset1:243
	s_waitcnt lgkmcnt(0)
	v_cvt_pk_bf16_f32 v13, v8, v9
	ds_read2_b32 v[8:9], v62 offset0:52 offset1:117
	s_waitcnt lgkmcnt(0)
	v_cvt_pk_bf16_f32 v14, v8, v9
	ds_read2_b32 v[8:9], v62 offset0:182 offset1:247
	v_mov_b32_e32 v17, v5
	s_waitcnt lgkmcnt(0)
	v_cvt_pk_bf16_f32 v15, v8, v9
	ds_read2_b32 v[8:9], v34 offset0:56 offset1:121
	v_lshl_add_u64 v[16:17], v[6:7], 0, v[16:17]
	global_store_dwordx4 v[16:17], v[12:15], off
	s_waitcnt lgkmcnt(0)
	s_nop 0
	v_cvt_pk_bf16_f32 v12, v8, v9
	ds_read2_b32 v[8:9], v34 offset0:186 offset1:251
	s_waitcnt lgkmcnt(0)
	v_cvt_pk_bf16_f32 v13, v8, v9
	ds_read2_b32 v[8:9], v62 offset0:60 offset1:125
	s_waitcnt lgkmcnt(0)
	v_cvt_pk_bf16_f32 v14, v8, v9
	ds_read2_b32 v[8:9], v62 offset0:190 offset1:255
	s_waitcnt lgkmcnt(0)
	v_cvt_pk_bf16_f32 v15, v8, v9
	v_or_b32_e32 v8, v10, v41
	v_lshlrev_b32_e32 v8, 12, v8
	v_mov_b32_e32 v9, v5
	v_lshl_add_u64 v[6:7], v[6:7], 0, v[8:9]
	global_store_dwordx4 v[6:7], v[12:15], off
	s_waitcnt lgkmcnt(0)

; __device__ __forceinline__ void transpose_item(const float* W, int K, int Nsrc, bf16_t* WT, int Ndst, const float* gain, int maptype, LAS float* scr, int item, int lane) {
;     const int nblk = Ndst / 64, kb = item / nblk, nb = item % nblk, k0 = 64 * kb, n0 = 64 * nb;
;     const int nd = n0 + lane; const int src = (maptype == MAP_IN) ? map_in(nd) : nd;
;     const float* wp = W + (size_t)k0 * Nsrc + (src >= 0 ? src : 0);
; #pragma unroll
;     for (int h = 0; h < 2; ++h) {
;         float v[32];
; #pragma unroll
;         for (int i = 0; i < 32; ++i) v[i] = wp[(size_t)(32 * h + i) * Nsrc];
.LBB0_87:
	s_andn2_saveexec_b64 s[4:5], s[76:77]
	s_cbranch_execz .LBB0_89
	v_lshlrev_b32_e32 v11, 1, v10
	v_sub_u32_e32 v11, v44, v11
	v_lshlrev_b32_e32 v10, 6, v10
	v_add_u32_e32 v11, 0xfffff800, v11
	v_sub_u32_e32 v10, v43, v10
	v_lshlrev_b64 v[8:9], 24, v[6:7]
	v_and_b32_e32 v11, 0x1ffc0, v11
	v_and_b32_e32 v10, 0x7c0, v10
	v_lshl_add_u64 v[8:9], s[38:39], 0, v[8:9]
	v_or_b32_e32 v14, v10, v1
	v_lshlrev_b32_e32 v12, 13, v11
	v_mov_b32_e32 v13, v5
	v_lshl_add_u64 v[8:9], v[8:9], 0, v[12:13]
	v_lshlrev_b32_e32 v12, 2, v14
	v_lshl_add_u64 v[8:9], v[8:9], 0, v[12:13]
	v_add_co_u32_e32 v14, vcc, s35, v8
	s_mov_b32 s48, 0x12000
	s_nop 0
	v_addc_co_u32_e32 v15, vcc, 0, v9, vcc
	v_add_co_u32_e32 v16, vcc, s84, v8
	v_lshlrev_b64 v[6:7], 23, v[6:7]
	s_nop 0
	v_addc_co_u32_e32 v17, vcc, 0, v9, vcc
	v_add_co_u32_e32 v18, vcc, s86, v8
	v_lshl_add_u64 v[6:7], s[82:83], 0, v[6:7]
	s_nop 0
	v_addc_co_u32_e32 v19, vcc, 0, v9, vcc
	v_add_co_u32_e32 v20, vcc, s88, v8
	s_nop 1
	v_addc_co_u32_e32 v21, vcc, 0, v9, vcc
	v_add_co_u32_e32 v22, vcc, s90, v8
	s_nop 1
	v_addc_co_u32_e32 v23, vcc, 0, v9, vcc
	v_add_co_u32_e32 v24, vcc, s92, v8
	s_nop 1
	v_addc_co_u32_e32 v25, vcc, 0, v9, vcc
	v_add_co_u32_e32 v26, vcc, s94, v8
	s_nop 1
	v_addc_co_u32_e32 v27, vcc, 0, v9, vcc
	global_load_dword v12, v[8:9], off nt
	global_load_dword v13, v[14:15], off nt
	s_nop 0
	global_load_dword v14, v[16:17], off nt
	global_load_dword v15, v[18:19], off nt
	s_nop 0
	global_load_dword v16, v[20:21], off nt
	global_load_dword v17, v[22:23], off nt
	global_load_dword v18, v[24:25], off nt
	global_load_dword v19, v[26:27], off nt
	v_add_co_u32_e32 v20, vcc, s96, v8
	s_nop 1
	v_addc_co_u32_e32 v21, vcc, 0, v9, vcc
	v_add_co_u32_e32 v22, vcc, s48, v8
	s_mov_b32 s48, 0x14000
	s_nop 0
	v_addc_co_u32_e32 v23, vcc, 0, v9, vcc
	v_add_co_u32_e32 v24, vcc, s48, v8
	s_mov_b32 s48, 0x16000
	s_nop 0
	v_addc_co_u32_e32 v25, vcc, 0, v9, vcc
	v_add_co_u32_e32 v26, vcc, s48, v8
	s_mov_b32 s48, 0x1a000
	s_nop 0
	v_addc_co_u32_e32 v27, vcc, 0, v9, vcc
	v_add_co_u32_e32 v28, vcc, s47, v8
	s_nop 1
	v_addc_co_u32_e32 v29, vcc, 0, v9, vcc
	v_add_co_u32_e32 v30, vcc, s48, v8
	s_mov_b32 s48, 0x1c000
	s_nop 0
	v_addc_co_u32_e32 v31, vcc, 0, v9, vcc
	v_add_co_u32_e32 v66, vcc, s48, v8
	s_mov_b32 s48, 0x22000
	s_nop 0
	v_addc_co_u32_e32 v67, vcc, 0, v9, vcc
	v_add_co_u32_e32 v68, vcc, s89, v8
	s_nop 1
	v_addc_co_u32_e32 v69, vcc, 0, v9, vcc
	global_load_dword v20, v[20:21], off nt
	s_nop 0
	global_load_dword v21, v[22:23], off nt
	s_nop 0
	global_load_dword v22, v[24:25], off nt
	global_load_dword v23, v[26:27], off nt
	s_nop 0
	global_load_dword v24, v[28:29], off nt
	global_load_dword v25, v[30:31], off nt
	global_load_dword v26, v[66:67], off nt
	global_load_dword v27, v[68:69], off nt
	v_add_co_u32_e32 v28, vcc, s91, v8
	s_nop 1
	v_addc_co_u32_e32 v29, vcc, 0, v9, vcc
	v_add_co_u32_e32 v30, vcc, s48, v8
	s_mov_b32 s48, 0x24000
	s_nop 0
	v_addc_co_u32_e32 v31, vcc, 0, v9, vcc
	v_add_co_u32_e32 v66, vcc, s48, v8
	s_mov_b32 s48, 0x26000
	s_nop 0
	v_addc_co_u32_e32 v67, vcc, 0, v9, vcc
	v_add_co_u32_e32 v68, vcc, s48, v8
	s_mov_b32 s48, 0x2a000
	s_nop 0
	v_addc_co_u32_e32 v69, vcc, 0, v9, vcc
	v_add_co_u32_e32 v70, vcc, s10, v8
	s_nop 1
	v_addc_co_u32_e32 v71, vcc, 0, v9, vcc
	v_add_co_u32_e32 v72, vcc, s48, v8
	s_mov_b32 s48, 0x2c000
	s_nop 0
	v_addc_co_u32_e32 v73, vcc, 0, v9, vcc
	v_add_co_u32_e32 v74, vcc, s48, v8
	s_mov_b32 s48, 0x2e000
	s_nop 0
	v_addc_co_u32_e32 v75, vcc, 0, v9, vcc
	v_add_co_u32_e32 v76, vcc, s48, v8
	s_mov_b32 s48, 0x32000
	s_nop 0
	v_addc_co_u32_e32 v77, vcc, 0, v9, vcc
	global_load_dword v65, v[28:29], off nt
	global_load_dword v78, v[30:31], off nt
	global_load_dword v79, v[66:67], off nt
	global_load_dword v80, v[68:69], off nt
	global_load_dword v81, v[70:71], off nt
	global_load_dword v82, v[72:73], off nt
	global_load_dword v83, v[74:75], off nt
	global_load_dword v84, v[76:77], off nt
	v_add_co_u32_e32 v28, vcc, s68, v8
	s_nop 1
	v_addc_co_u32_e32 v29, vcc, 0, v9, vcc
	v_add_co_u32_e32 v30, vcc, s48, v8
	s_mov_b32 s48, 0x34000
	s_nop 0
	v_addc_co_u32_e32 v31, vcc, 0, v9, vcc
	v_add_co_u32_e32 v66, vcc, s48, v8
	s_mov_b32 s48, 0x36000
	s_nop 0
	v_addc_co_u32_e32 v67, vcc, 0, v9, vcc
	v_add_co_u32_e32 v68, vcc, s48, v8
	s_mov_b32 s48, 0x3a000
	s_nop 0
	v_addc_co_u32_e32 v69, vcc, 0, v9, vcc
	v_add_co_u32_e32 v70, vcc, s56, v8
	s_nop 1
	v_addc_co_u32_e32 v71, vcc, 0, v9, vcc
	v_add_co_u32_e32 v72, vcc, s48, v8
	s_mov_b32 s48, 0x3e000
	s_nop 0
	v_addc_co_u32_e32 v73, vcc, 0, v9, vcc
	v_add_co_u32_e32 v74, vcc, s58, v8
	s_nop 1
	v_addc_co_u32_e32 v75, vcc, 0, v9, vcc
	v_add_co_u32_e32 v76, vcc, s48, v8
	s_mov_b32 s48, 0x42000
	s_nop 0
	v_addc_co_u32_e32 v77, vcc, 0, v9, vcc
	global_load_dword v85, v[28:29], off nt
	global_load_dword v86, v[30:31], off nt
	global_load_dword v87, v[66:67], off nt
	global_load_dword v88, v[68:69], off nt
	global_load_dword v89, v[70:71], off nt
	global_load_dword v90, v[72:73], off nt
	global_load_dword v91, v[74:75], off nt
	global_load_dword v92, v[76:77], off nt
	v_add_co_u32_e32 v28, vcc, s50, v8
	s_nop 1
	v_addc_co_u32_e32 v29, vcc, 0, v9, vcc
	v_add_co_u32_e32 v30, vcc, s48, v8
	s_mov_b32 s48, 0x44000
	s_nop 0
	v_addc_co_u32_e32 v31, vcc, 0, v9, vcc
	v_add_co_u32_e32 v66, vcc, s48, v8
	s_mov_b32 s48, 0x46000
	s_nop 0
	v_addc_co_u32_e32 v67, vcc, 0, v9, vcc
	v_add_co_u32_e32 v68, vcc, s48, v8
	s_mov_b32 s48, 0x4a000
	s_nop 0
	v_addc_co_u32_e32 v69, vcc, 0, v9, vcc
	v_add_co_u32_e32 v70, vcc, s69, v8
	s_nop 1
	v_addc_co_u32_e32 v71, vcc, 0, v9, vcc
	v_add_co_u32_e32 v72, vcc, s48, v8
	s_mov_b32 s48, 0x4c000
	s_nop 0
	v_addc_co_u32_e32 v73, vcc, 0, v9, vcc
; __device__ __forceinline__ void transpose_item(const float* W, int K, int Nsrc, bf16_t* WT, int Ndst, const float* gain, int maptype, LAS float* scr, int item, int lane) {
;     ...
;         for (int i = 0; i < 32; ++i) v[i] = wp[(size_t)(32 * h + i) * Nsrc];
; #pragma unroll
;         for (int i = 0; i < 32; ++i) { float x = (src >= 0) ? v[i] : 0.f; if (gain) x *= gain[k0 + 32 * h + i]; scr[(32 * h + i) * 65 + lane] = x; }
	v_add_co_u32_e32 v74, vcc, s48, v8
	s_mov_b32 s48, 0x4e000
	s_nop 0
	v_addc_co_u32_e32 v75, vcc, 0, v9, vcc
	v_add_co_u32_e32 v76, vcc, s48, v8
	s_mov_b32 s48, 0x52000
	s_nop 0
	v_addc_co_u32_e32 v77, vcc, 0, v9, vcc
	global_load_dword v93, v[28:29], off nt
	global_load_dword v94, v[30:31], off nt
	global_load_dword v95, v[66:67], off nt
	global_load_dword v96, v[68:69], off nt
	global_load_dword v97, v[70:71], off nt
	global_load_dword v98, v[72:73], off nt
	global_load_dword v99, v[74:75], off nt
	global_load_dword v100, v[76:77], off nt
	v_add_co_u32_e32 v28, vcc, s34, v8
	s_nop 1
	v_addc_co_u32_e32 v29, vcc, 0, v9, vcc
	v_add_co_u32_e32 v30, vcc, s48, v8
	s_mov_b32 s48, 0x54000
	s_nop 0
	v_addc_co_u32_e32 v31, vcc, 0, v9, vcc
	v_add_co_u32_e32 v66, vcc, s48, v8
	s_mov_b32 s48, 0x56000
	s_nop 0
	v_addc_co_u32_e32 v67, vcc, 0, v9, vcc
	v_add_co_u32_e32 v68, vcc, s48, v8
	s_mov_b32 s48, 0x5c000
	s_nop 0
	v_addc_co_u32_e32 v69, vcc, 0, v9, vcc
	v_add_co_u32_e32 v70, vcc, s8, v8
	s_nop 1
	v_addc_co_u32_e32 v71, vcc, 0, v9, vcc
	v_add_co_u32_e32 v72, vcc, s9, v8
	s_nop 1
	v_addc_co_u32_e32 v73, vcc, 0, v9, vcc
	v_add_co_u32_e32 v74, vcc, s48, v8
	s_nop 1
	v_addc_co_u32_e32 v75, vcc, 0, v9, vcc
	v_add_co_u32_e32 v76, vcc, s60, v8
	s_nop 1
	v_addc_co_u32_e32 v77, vcc, 0, v9, vcc
	global_load_dword v101, v[28:29], off nt
	global_load_dword v102, v[30:31], off nt
	global_load_dword v103, v[66:67], off nt
	global_load_dword v104, v[68:69], off nt
	global_load_dword v105, v[70:71], off nt
	global_load_dword v106, v[72:73], off nt
	global_load_dword v107, v[74:75], off nt
	global_load_dword v108, v[76:77], off nt
	v_add_co_u32_e32 v28, vcc, s51, v8
	s_nop 1
	v_addc_co_u32_e32 v29, vcc, 0, v9, vcc
	v_add_co_u32_e32 v30, vcc, s61, v8
	s_nop 1
	v_addc_co_u32_e32 v31, vcc, 0, v9, vcc
	v_add_co_u32_e32 v66, vcc, s62, v8
	s_nop 1
	v_addc_co_u32_e32 v67, vcc, 0, v9, vcc
	v_add_co_u32_e32 v68, vcc, s63, v8
	s_nop 1
	v_addc_co_u32_e32 v69, vcc, 0, v9, vcc
	v_add_co_u32_e32 v70, vcc, s57, v8
	s_nop 1
	v_addc_co_u32_e32 v71, vcc, 0, v9, vcc
	v_add_co_u32_e32 v72, vcc, s59, v8
	s_nop 1
	v_addc_co_u32_e32 v73, vcc, 0, v9, vcc
	v_add_co_u32_e32 v74, vcc, s54, v8
	s_nop 1
	v_addc_co_u32_e32 v75, vcc, 0, v9, vcc
	v_add_co_u32_e32 v76, vcc, s52, v8
	s_nop 1
	v_addc_co_u32_e32 v77, vcc, 0, v9, vcc
	global_load_dword v109, v[28:29], off nt
	global_load_dword v110, v[30:31], off nt
	global_load_dword v111, v[66:67], off nt
	global_load_dword v112, v[68:69], off nt
	global_load_dword v113, v[70:71], off nt
	global_load_dword v114, v[72:73], off nt
	global_load_dword v115, v[74:75], off nt
	s_nop 0
	global_load_dword v76, v[76:77], off nt
	v_add_co_u32_e32 v28, vcc, s53, v8
	s_nop 1
	v_addc_co_u32_e32 v29, vcc, 0, v9, vcc
	v_add_co_u32_e32 v30, vcc, s55, v8
	s_nop 1
	v_addc_co_u32_e32 v31, vcc, 0, v9, vcc
	v_add_co_u32_e32 v66, vcc, s97, v8
	s_nop 1
	v_addc_co_u32_e32 v67, vcc, 0, v9, vcc
	v_add_co_u32_e32 v68, vcc, s3, v8
	s_nop 1
	v_addc_co_u32_e32 v69, vcc, 0, v9, vcc
	v_add_co_u32_e32 v70, vcc, s85, v8
	s_nop 1
	v_addc_co_u32_e32 v71, vcc, 0, v9, vcc
	v_add_co_u32_e32 v72, vcc, s87, v8
	s_nop 1
	v_addc_co_u32_e32 v73, vcc, 0, v9, vcc
	v_add_co_u32_e32 v74, vcc, s93, v8
	s_nop 1
	v_addc_co_u32_e32 v75, vcc, 0, v9, vcc
	v_add_co_u32_e32 v8, vcc, s11, v8
	s_nop 1
	v_addc_co_u32_e32 v9, vcc, 0, v9, vcc
	global_load_dword v28, v[28:29], off nt
	s_nop 0
	global_load_dword v29, v[30:31], off nt
	s_nop 0
	global_load_dword v30, v[66:67], off nt
	global_load_dword v31, v[68:69], off nt
	s_nop 0
	global_load_dword v66, v[70:71], off nt
	global_load_dword v67, v[72:73], off nt
	global_load_dword v68, v[74:75], off nt
	s_nop 0
	global_load_dword v8, v[8:9], off nt
	s_waitcnt vmcnt(62)
	ds_write2_b32 v32, v12, v13 offset1:65
	s_waitcnt vmcnt(60)
	ds_write2_b32 v32, v14, v15 offset0:130 offset1:195
	s_waitcnt vmcnt(58)
	ds_write2_b32 v47, v16, v17 offset0:4 offset1:69
	s_waitcnt vmcnt(56)
	ds_write2_b32 v47, v18, v19 offset0:134 offset1:199
	s_waitcnt vmcnt(54)
	ds_write2_b32 v48, v20, v21 offset0:8 offset1:73
	s_waitcnt vmcnt(52)
	ds_write2_b32 v48, v22, v23 offset0:138 offset1:203
	s_waitcnt vmcnt(50)
	ds_write2_b32 v49, v24, v25 offset0:12 offset1:77
	s_waitcnt vmcnt(48)
	ds_write2_b32 v49, v26, v27 offset0:142 offset1:207
	s_waitcnt vmcnt(46)
	ds_write2_b32 v50, v65, v78 offset0:16 offset1:81
	s_waitcnt vmcnt(44)
	ds_write2_b32 v50, v79, v80 offset0:146 offset1:211
	s_waitcnt vmcnt(42)
	ds_write2_b32 v51, v81, v82 offset0:20 offset1:85
	s_waitcnt vmcnt(40)
	ds_write2_b32 v51, v83, v84 offset0:150 offset1:215
	s_waitcnt vmcnt(38)
	ds_write2_b32 v52, v85, v86 offset0:24 offset1:89
	s_waitcnt vmcnt(36)
	ds_write2_b32 v52, v87, v88 offset0:154 offset1:219
	s_waitcnt vmcnt(34)
	ds_write2_b32 v53, v89, v90 offset0:28 offset1:93
	s_waitcnt vmcnt(32)
	ds_write2_b32 v53, v91, v92 offset0:158 offset1:223
	s_waitcnt vmcnt(30)
	ds_write2_b32 v54, v93, v94 offset0:32 offset1:97
	s_waitcnt vmcnt(28)
	ds_write2_b32 v54, v95, v96 offset0:162 offset1:227
	s_waitcnt vmcnt(26)
	ds_write2_b32 v55, v97, v98 offset0:36 offset1:101
	s_waitcnt vmcnt(24)
	ds_write2_b32 v55, v99, v100 offset0:166 offset1:231
	s_waitcnt vmcnt(22)
	ds_write2_b32 v56, v101, v102 offset0:40 offset1:105
	s_waitcnt vmcnt(20)
	ds_write2_b32 v56, v103, v104 offset0:170 offset1:235
	s_waitcnt vmcnt(18)
	ds_write2_b32 v57, v105, v106 offset0:44 offset1:109
	s_waitcnt vmcnt(16)
; #define LAS __attribute__((address_space(3)))
; __device__ __forceinline__ unsigned cvt_pk_bf16(float lo, float hi) { unsigned r; asm volatile("v_cvt_pk_bf16_f32 %0, %1, %2" : "=v"(r) : "v"(lo), "v"(hi)); return r; }
; __device__ __forceinline__ void transpose_item(const float* W, int K, int Nsrc, bf16_t* WT, int Ndst, const float* gain, int maptype, LAS float* scr, int item, int lane) {
;     ...
;         for (int i = 0; i < 32; ++i) { float x = (src >= 0) ? v[i] : 0.f; if (gain) x *= gain[k0 + 32 * h + i]; scr[(32 * h + i) * 65 + lane] = x; }
;     }
;     asm volatile("s_waitcnt lgkmcnt(0)" ::: "memory");
;     const int cidx = lane & 7;
; #pragma unroll
;     for (int j = 0; j < 8; ++j) { const int n = (lane >> 3) + 8 * j; const LAS float* s = scr + (8 * cidx) * 65 + n;
;         u32x4 o; o.x = cvt_pk_bf16(s[0 * 65], s[1 * 65]); o.y = cvt_pk_bf16(s[2 * 65], s[3 * 65]); o.z = cvt_pk_bf16(s[4 * 65], s[5 * 65]); o.w = cvt_pk_bf16(s[6 * 65], s[7 * 65]);
;         *(u32x4*)(WT + (size_t)(n0 + n) * K + k0 + 8 * cidx) = o; }
;     asm volatile("s_waitcnt lgkmcnt(0)" ::: "memory");
	ds_write2_b32 v57, v107, v108 offset0:174 offset1:239
	s_waitcnt vmcnt(14)
	ds_write2_b32 v58, v109, v110 offset0:48 offset1:113
	s_waitcnt vmcnt(12)
	ds_write2_b32 v58, v111, v112 offset0:178 offset1:243
	s_waitcnt vmcnt(10)
	ds_write2_b32 v59, v113, v114 offset0:52 offset1:117
	s_waitcnt vmcnt(8)
	ds_write2_b32 v59, v115, v76 offset0:182 offset1:247
	s_waitcnt vmcnt(6)
	ds_write2_b32 v60, v28, v29 offset0:56 offset1:121
	s_waitcnt vmcnt(4)
	ds_write2_b32 v60, v30, v31 offset0:186 offset1:251
	s_waitcnt vmcnt(2)
	ds_write2_b32 v61, v66, v67 offset0:60 offset1:125
	s_waitcnt vmcnt(0)
	ds_write2_b32 v61, v68, v8 offset0:190 offset1:255
	s_waitcnt lgkmcnt(0)
	ds_read2_b32 v[8:9], v34 offset1:65
	s_waitcnt lgkmcnt(0)
	v_cvt_pk_bf16_f32 v12, v8, v9
	ds_read2_b32 v[8:9], v34 offset0:130 offset1:195
	v_lshlrev_b32_e32 v16, 1, v11
	v_mov_b32_e32 v17, v5
	s_waitcnt lgkmcnt(0)
	v_cvt_pk_bf16_f32 v13, v8, v9
	ds_read2_b32 v[8:9], v62 offset0:4 offset1:69
	v_lshl_add_u64 v[6:7], v[6:7], 0, v[16:17]
	v_or_b32_e32 v11, v10, v33
	s_waitcnt lgkmcnt(0)
	v_cvt_pk_bf16_f32 v14, v8, v9
	ds_read2_b32 v[8:9], v62 offset0:134 offset1:199
	v_lshl_add_u64 v[6:7], v[6:7], 0, v[4:5]
	v_lshlrev_b32_e32 v16, 12, v11
	s_waitcnt lgkmcnt(0)
	v_cvt_pk_bf16_f32 v15, v8, v9
	ds_read2_b32 v[8:9], v34 offset0:8 offset1:73
	v_lshl_add_u64 v[16:17], v[6:7], 0, v[16:17]
	global_store_dwordx4 v[16:17], v[12:15], off
	v_or_b32_e32 v11, v10, v35
	v_lshlrev_b32_e32 v16, 12, v11
	s_waitcnt lgkmcnt(0)
	v_cvt_pk_bf16_f32 v12, v8, v9
	ds_read2_b32 v[8:9], v34 offset0:138 offset1:203
	s_waitcnt lgkmcnt(0)
	v_cvt_pk_bf16_f32 v13, v8, v9
	ds_read2_b32 v[8:9], v62 offset0:12 offset1:77
	s_waitcnt lgkmcnt(0)
	v_cvt_pk_bf16_f32 v14, v8, v9
	ds_read2_b32 v[8:9], v62 offset0:142 offset1:207
	v_mov_b32_e32 v17, v5
	s_waitcnt lgkmcnt(0)
	v_cvt_pk_bf16_f32 v15, v8, v9
	ds_read2_b32 v[8:9], v34 offset0:16 offset1:81
	v_lshl_add_u64 v[16:17], v[6:7], 0, v[16:17]
	global_store_dwordx4 v[16:17], v[12:15], off
	v_or_b32_e32 v11, v10, v36
	v_lshlrev_b32_e32 v16, 12, v11
	s_waitcnt lgkmcnt(0)
	v_cvt_pk_bf16_f32 v12, v8, v9
	ds_read2_b32 v[8:9], v34 offset0:146 offset1:211
	s_waitcnt lgkmcnt(0)
	v_cvt_pk_bf16_f32 v13, v8, v9
	ds_read2_b32 v[8:9], v62 offset0:20 offset1:85
	s_waitcnt lgkmcnt(0)
	v_cvt_pk_bf16_f32 v14, v8, v9
	ds_read2_b32 v[8:9], v62 offset0:150 offset1:215
	v_mov_b32_e32 v17, v5
	s_waitcnt lgkmcnt(0)
	v_cvt_pk_bf16_f32 v15, v8, v9
	ds_read2_b32 v[8:9], v34 offset0:24 offset1:89
	v_lshl_add_u64 v[16:17], v[6:7], 0, v[16:17]
	global_store_dwordx4 v[16:17], v[12:15], off
	v_or_b32_e32 v11, v10, v37
	v_lshlrev_b32_e32 v16, 12, v11
	s_waitcnt lgkmcnt(0)
	v_cvt_pk_bf16_f32 v12, v8, v9
	ds_read2_b32 v[8:9], v34 offset0:154 offset1:219
	s_waitcnt lgkmcnt(0)
	v_cvt_pk_bf16_f32 v13, v8, v9
	ds_read2_b32 v[8:9], v62 offset0:28 offset1:93
	s_waitcnt lgkmcnt(0)
	v_cvt_pk_bf16_f32 v14, v8, v9
	ds_read2_b32 v[8:9], v62 offset0:158 offset1:223
	v_mov_b32_e32 v17, v5
	s_waitcnt lgkmcnt(0)
	v_cvt_pk_bf16_f32 v15, v8, v9
	ds_read2_b32 v[8:9], v34 offset0:32 offset1:97
	v_lshl_add_u64 v[16:17], v[6:7], 0, v[16:17]
	global_store_dwordx4 v[16:17], v[12:15], off
	v_or_b32_e32 v11, v10, v38
	v_lshlrev_b32_e32 v16, 12, v11
	s_waitcnt lgkmcnt(0)
	v_cvt_pk_bf16_f32 v12, v8, v9
	ds_read2_b32 v[8:9], v34 offset0:162 offset1:227
	s_waitcnt lgkmcnt(0)
	v_cvt_pk_bf16_f32 v13, v8, v9
	ds_read2_b32 v[8:9], v62 offset0:36 offset1:101
	s_waitcnt lgkmcnt(0)
	v_cvt_pk_bf16_f32 v14, v8, v9
	ds_read2_b32 v[8:9], v62 offset0:166 offset1:231
	v_mov_b32_e32 v17, v5
	s_waitcnt lgkmcnt(0)
	v_cvt_pk_bf16_f32 v15, v8, v9
	ds_read2_b32 v[8:9], v34 offset0:40 offset1:105
	v_lshl_add_u64 v[16:17], v[6:7], 0, v[16:17]
	global_store_dwordx4 v[16:17], v[12:15], off
	v_or_b32_e32 v11, v10, v39
	v_lshlrev_b32_e32 v16, 12, v11
	s_waitcnt lgkmcnt(0)
	v_cvt_pk_bf16_f32 v12, v8, v9
	ds_read2_b32 v[8:9], v34 offset0:170 offset1:235
	s_waitcnt lgkmcnt(0)
	v_cvt_pk_bf16_f32 v13, v8, v9
	ds_read2_b32 v[8:9], v62 offset0:44 offset1:109
	s_waitcnt lgkmcnt(0)
	v_cvt_pk_bf16_f32 v14, v8, v9
	ds_read2_b32 v[8:9], v62 offset0:174 offset1:239
	v_mov_b32_e32 v17, v5
	s_waitcnt lgkmcnt(0)
	v_cvt_pk_bf16_f32 v15, v8, v9
	ds_read2_b32 v[8:9], v34 offset0:48 offset1:113
	v_lshl_add_u64 v[16:17], v[6:7], 0, v[16:17]
	global_store_dwordx4 v[16:17], v[12:15], off
	v_or_b32_e32 v11, v10, v40
	v_lshlrev_b32_e32 v16, 12, v11
	s_waitcnt lgkmcnt(0)
	v_cvt_pk_bf16_f32 v12, v8, v9
	ds_read2_b32 v[8:9], v34 offset0:178 offset1:243
	s_waitcnt lgkmcnt(0)
	v_cvt_pk_bf16_f32 v13, v8, v9
	ds_read2_b32 v[8:9], v62 offset0:52 offset1:117
	s_waitcnt lgkmcnt(0)
	v_cvt_pk_bf16_f32 v14, v8, v9
	ds_read2_b32 v[8:9], v62 offset0:182 offset1:247
	v_mov_b32_e32 v17, v5
	s_waitcnt lgkmcnt(0)
	v_cvt_pk_bf16_f32 v15, v8, v9
	ds_read2_b32 v[8:9], v34 offset0:56 offset1:121
	v_lshl_add_u64 v[16:17], v[6:7], 0, v[16:17]
	global_store_dwordx4 v[16:17], v[12:15], off
	s_waitcnt lgkmcnt(0)
	s_nop 0
	v_cvt_pk_bf16_f32 v12, v8, v9
	ds_read2_b32 v[8:9], v34 offset0:186 offset1:251
	s_waitcnt lgkmcnt(0)
	v_cvt_pk_bf16_f32 v13, v8, v9
	ds_read2_b32 v[8:9], v62 offset0:60 offset1:125
	s_waitcnt lgkmcnt(0)
	v_cvt_pk_bf16_f32 v14, v8, v9
	ds_read2_b32 v[8:9], v62 offset0:190 offset1:255
	s_waitcnt lgkmcnt(0)
	v_cvt_pk_bf16_f32 v15, v8, v9
	v_or_b32_e32 v8, v10, v41
	v_lshlrev_b32_e32 v8, 12, v8
	v_mov_b32_e32 v9, v5
	v_lshl_add_u64 v[6:7], v[6:7], 0, v[8:9]
	global_store_dwordx4 v[6:7], v[12:15], off
	s_waitcnt lgkmcnt(0)

; __device__ __forceinline__ void transpose_item(const float* W, int K, int Nsrc, bf16_t* WT, int Ndst, const float* gain, int maptype, LAS float* scr, int item, int lane) {
;     const int nblk = Ndst / 64, kb = item / nblk, nb = item % nblk, k0 = 64 * kb, n0 = 64 * nb;
;     const int nd = n0 + lane; const int src = (maptype == MAP_IN) ? map_in(nd) : nd;
;     const float* wp = W + (size_t)k0 * Nsrc + (src >= 0 ? src : 0);
; #pragma unroll
;     for (int h = 0; h < 2; ++h) {
;         float v[32];
; #pragma unroll
;         for (int i = 0; i < 32; ++i) v[i] = wp[(size_t)(32 * h + i) * Nsrc];
.LBB0_90:
	s_andn2_saveexec_b64 s[4:5], s[74:75]
	s_cbranch_execz .LBB0_92
	v_lshlrev_b32_e32 v11, 1, v10
	v_lshlrev_b32_e32 v10, 6, v10
	v_sub_u32_e32 v11, v44, v11
	v_sub_u32_e32 v10, v43, v10
	v_lshlrev_b64 v[8:9], 24, v[6:7]
	v_and_b32_e32 v11, 0x1ffc0, v11
	v_and_b32_e32 v10, 0x7c0, v10
	v_lshl_add_u64 v[8:9], s[36:37], 0, v[8:9]
	v_or_b32_e32 v14, v10, v1
	v_lshlrev_b32_e32 v12, 13, v11
	v_mov_b32_e32 v13, v5
	v_lshl_add_u64 v[8:9], v[8:9], 0, v[12:13]
	v_lshlrev_b32_e32 v12, 2, v14
	v_lshl_add_u64 v[8:9], v[8:9], 0, v[12:13]
	v_add_co_u32_e32 v14, vcc, s35, v8
	s_mov_b32 s48, 0x12000
	s_nop 0
	v_addc_co_u32_e32 v15, vcc, 0, v9, vcc
	v_add_co_u32_e32 v16, vcc, s84, v8
	v_lshlrev_b64 v[6:7], 23, v[6:7]
	s_nop 0
	v_addc_co_u32_e32 v17, vcc, 0, v9, vcc
	v_add_co_u32_e32 v18, vcc, s86, v8
	v_lshl_add_u64 v[6:7], s[64:65], 0, v[6:7]
	s_nop 0
	v_addc_co_u32_e32 v19, vcc, 0, v9, vcc
	v_add_co_u32_e32 v20, vcc, s88, v8
	s_nop 1
	v_addc_co_u32_e32 v21, vcc, 0, v9, vcc
	v_add_co_u32_e32 v22, vcc, s90, v8
	s_nop 1
	v_addc_co_u32_e32 v23, vcc, 0, v9, vcc
	v_add_co_u32_e32 v24, vcc, s92, v8
	s_nop 1
	v_addc_co_u32_e32 v25, vcc, 0, v9, vcc
	v_add_co_u32_e32 v26, vcc, s94, v8
	s_nop 1
	v_addc_co_u32_e32 v27, vcc, 0, v9, vcc
	global_load_dword v12, v[8:9], off nt
	global_load_dword v13, v[14:15], off nt
	s_nop 0
	global_load_dword v14, v[16:17], off nt
	global_load_dword v15, v[18:19], off nt
	s_nop 0
	global_load_dword v16, v[20:21], off nt
	global_load_dword v17, v[22:23], off nt
	global_load_dword v18, v[24:25], off nt
	global_load_dword v19, v[26:27], off nt
	v_add_co_u32_e32 v20, vcc, s96, v8
	s_nop 1
	v_addc_co_u32_e32 v21, vcc, 0, v9, vcc
	v_add_co_u32_e32 v22, vcc, s48, v8
	s_mov_b32 s48, 0x14000
	s_nop 0
	v_addc_co_u32_e32 v23, vcc, 0, v9, vcc
	v_add_co_u32_e32 v24, vcc, s48, v8
	s_mov_b32 s48, 0x16000
	s_nop 0
	v_addc_co_u32_e32 v25, vcc, 0, v9, vcc
	v_add_co_u32_e32 v26, vcc, s48, v8
	s_mov_b32 s48, 0x1a000
	s_nop 0
	v_addc_co_u32_e32 v27, vcc, 0, v9, vcc
	v_add_co_u32_e32 v28, vcc, s47, v8
	s_nop 1
	v_addc_co_u32_e32 v29, vcc, 0, v9, vcc
	v_add_co_u32_e32 v30, vcc, s48, v8
	s_mov_b32 s48, 0x1c000
	s_nop 0
	v_addc_co_u32_e32 v31, vcc, 0, v9, vcc
	v_add_co_u32_e32 v66, vcc, s48, v8
	s_mov_b32 s48, 0x22000
	s_nop 0
	v_addc_co_u32_e32 v67, vcc, 0, v9, vcc
	v_add_co_u32_e32 v68, vcc, s89, v8
	s_nop 1
	v_addc_co_u32_e32 v69, vcc, 0, v9, vcc
	global_load_dword v20, v[20:21], off nt
	s_nop 0
	global_load_dword v21, v[22:23], off nt
	s_nop 0
	global_load_dword v22, v[24:25], off nt
	global_load_dword v23, v[26:27], off nt
	s_nop 0
	global_load_dword v24, v[28:29], off nt
	global_load_dword v25, v[30:31], off nt
	global_load_dword v26, v[66:67], off nt
	global_load_dword v27, v[68:69], off nt
	v_add_co_u32_e32 v28, vcc, s91, v8
	s_nop 1
	v_addc_co_u32_e32 v29, vcc, 0, v9, vcc
	v_add_co_u32_e32 v30, vcc, s48, v8
	s_mov_b32 s48, 0x24000
	s_nop 0
	v_addc_co_u32_e32 v31, vcc, 0, v9, vcc
	v_add_co_u32_e32 v66, vcc, s48, v8
	s_mov_b32 s48, 0x26000
	s_nop 0
	v_addc_co_u32_e32 v67, vcc, 0, v9, vcc
	v_add_co_u32_e32 v68, vcc, s48, v8
	s_mov_b32 s48, 0x2a000
	s_nop 0
	v_addc_co_u32_e32 v69, vcc, 0, v9, vcc
	v_add_co_u32_e32 v70, vcc, s10, v8
	s_nop 1
	v_addc_co_u32_e32 v71, vcc, 0, v9, vcc
	v_add_co_u32_e32 v72, vcc, s48, v8
	s_mov_b32 s48, 0x2c000
	s_nop 0
	v_addc_co_u32_e32 v73, vcc, 0, v9, vcc
	v_add_co_u32_e32 v74, vcc, s48, v8
	s_mov_b32 s48, 0x2e000
	s_nop 0
	v_addc_co_u32_e32 v75, vcc, 0, v9, vcc
	v_add_co_u32_e32 v76, vcc, s48, v8
	s_mov_b32 s48, 0x32000
	s_nop 0
	v_addc_co_u32_e32 v77, vcc, 0, v9, vcc
	global_load_dword v65, v[28:29], off nt
	global_load_dword v78, v[30:31], off nt
	global_load_dword v79, v[66:67], off nt
	global_load_dword v80, v[68:69], off nt
	global_load_dword v81, v[70:71], off nt
	global_load_dword v82, v[72:73], off nt
	global_load_dword v83, v[74:75], off nt
	global_load_dword v84, v[76:77], off nt
	v_add_co_u32_e32 v28, vcc, s68, v8
	s_nop 1
	v_addc_co_u32_e32 v29, vcc, 0, v9, vcc
	v_add_co_u32_e32 v30, vcc, s48, v8
	s_mov_b32 s48, 0x34000
	s_nop 0
	v_addc_co_u32_e32 v31, vcc, 0, v9, vcc
	v_add_co_u32_e32 v66, vcc, s48, v8
	s_mov_b32 s48, 0x36000
	s_nop 0
	v_addc_co_u32_e32 v67, vcc, 0, v9, vcc
	v_add_co_u32_e32 v68, vcc, s48, v8
	s_mov_b32 s48, 0x3a000
	s_nop 0
	v_addc_co_u32_e32 v69, vcc, 0, v9, vcc
	v_add_co_u32_e32 v70, vcc, s56, v8
	s_nop 1
	v_addc_co_u32_e32 v71, vcc, 0, v9, vcc
	v_add_co_u32_e32 v72, vcc, s48, v8
	s_mov_b32 s48, 0x3e000
	s_nop 0
	v_addc_co_u32_e32 v73, vcc, 0, v9, vcc
	v_add_co_u32_e32 v74, vcc, s58, v8
	s_nop 1
	v_addc_co_u32_e32 v75, vcc, 0, v9, vcc
	v_add_co_u32_e32 v76, vcc, s48, v8
	s_mov_b32 s48, 0x42000
	s_nop 0
	v_addc_co_u32_e32 v77, vcc, 0, v9, vcc
	global_load_dword v85, v[28:29], off nt
	global_load_dword v86, v[30:31], off nt
	global_load_dword v87, v[66:67], off nt
	global_load_dword v88, v[68:69], off nt
	global_load_dword v89, v[70:71], off nt
	global_load_dword v90, v[72:73], off nt
	global_load_dword v91, v[74:75], off nt
	global_load_dword v92, v[76:77], off nt
	v_add_co_u32_e32 v28, vcc, s50, v8
	s_nop 1
	v_addc_co_u32_e32 v29, vcc, 0, v9, vcc
	v_add_co_u32_e32 v30, vcc, s48, v8
	s_mov_b32 s48, 0x44000
	s_nop 0
	v_addc_co_u32_e32 v31, vcc, 0, v9, vcc
	v_add_co_u32_e32 v66, vcc, s48, v8
	s_mov_b32 s48, 0x46000
	s_nop 0
	v_addc_co_u32_e32 v67, vcc, 0, v9, vcc
	v_add_co_u32_e32 v68, vcc, s48, v8
	s_mov_b32 s48, 0x4a000
	s_nop 0
	v_addc_co_u32_e32 v69, vcc, 0, v9, vcc
	v_add_co_u32_e32 v70, vcc, s69, v8
	s_nop 1
	v_addc_co_u32_e32 v71, vcc, 0, v9, vcc
	v_add_co_u32_e32 v72, vcc, s48, v8
	s_mov_b32 s48, 0x4c000
	s_nop 0
	v_addc_co_u32_e32 v73, vcc, 0, v9, vcc
	v_add_co_u32_e32 v74, vcc, s48, v8
; __device__ __forceinline__ void transpose_item(const float* W, int K, int Nsrc, bf16_t* WT, int Ndst, const float* gain, int maptype, LAS float* scr, int item, int lane) {
;     ...
;         for (int i = 0; i < 32; ++i) v[i] = wp[(size_t)(32 * h + i) * Nsrc];
; #pragma unroll
;         for (int i = 0; i < 32; ++i) { float x = (src >= 0) ? v[i] : 0.f; if (gain) x *= gain[k0 + 32 * h + i]; scr[(32 * h + i) * 65 + lane] = x; }
	s_mov_b32 s48, 0x4e000
	s_nop 0
	v_addc_co_u32_e32 v75, vcc, 0, v9, vcc
	v_add_co_u32_e32 v76, vcc, s48, v8
	s_mov_b32 s48, 0x52000
	s_nop 0
	v_addc_co_u32_e32 v77, vcc, 0, v9, vcc
	global_load_dword v93, v[28:29], off nt
	global_load_dword v94, v[30:31], off nt
	global_load_dword v95, v[66:67], off nt
	global_load_dword v96, v[68:69], off nt
	global_load_dword v97, v[70:71], off nt
	global_load_dword v98, v[72:73], off nt
	global_load_dword v99, v[74:75], off nt
	global_load_dword v100, v[76:77], off nt
	v_add_co_u32_e32 v28, vcc, s34, v8
	s_nop 1
	v_addc_co_u32_e32 v29, vcc, 0, v9, vcc
	v_add_co_u32_e32 v30, vcc, s48, v8
	s_mov_b32 s48, 0x54000
	s_nop 0
	v_addc_co_u32_e32 v31, vcc, 0, v9, vcc
	v_add_co_u32_e32 v66, vcc, s48, v8
	s_mov_b32 s48, 0x56000
	s_nop 0
	v_addc_co_u32_e32 v67, vcc, 0, v9, vcc
	v_add_co_u32_e32 v68, vcc, s48, v8
	s_mov_b32 s48, 0x5c000
	s_nop 0
	v_addc_co_u32_e32 v69, vcc, 0, v9, vcc
	v_add_co_u32_e32 v70, vcc, s8, v8
	s_nop 1
	v_addc_co_u32_e32 v71, vcc, 0, v9, vcc
	v_add_co_u32_e32 v72, vcc, s9, v8
	s_nop 1
	v_addc_co_u32_e32 v73, vcc, 0, v9, vcc
	v_add_co_u32_e32 v74, vcc, s48, v8
	s_nop 1
	v_addc_co_u32_e32 v75, vcc, 0, v9, vcc
	v_add_co_u32_e32 v76, vcc, s60, v8
	s_nop 1
	v_addc_co_u32_e32 v77, vcc, 0, v9, vcc
	global_load_dword v101, v[28:29], off nt
	global_load_dword v102, v[30:31], off nt
	global_load_dword v103, v[66:67], off nt
	global_load_dword v104, v[68:69], off nt
	global_load_dword v105, v[70:71], off nt
	global_load_dword v106, v[72:73], off nt
	global_load_dword v107, v[74:75], off nt
	global_load_dword v108, v[76:77], off nt
	v_add_co_u32_e32 v28, vcc, s51, v8
	s_nop 1
	v_addc_co_u32_e32 v29, vcc, 0, v9, vcc
	v_add_co_u32_e32 v30, vcc, s61, v8
	s_nop 1
	v_addc_co_u32_e32 v31, vcc, 0, v9, vcc
	v_add_co_u32_e32 v66, vcc, s62, v8
	s_nop 1
	v_addc_co_u32_e32 v67, vcc, 0, v9, vcc
	v_add_co_u32_e32 v68, vcc, s63, v8
	s_nop 1
	v_addc_co_u32_e32 v69, vcc, 0, v9, vcc
	v_add_co_u32_e32 v70, vcc, s57, v8
	s_nop 1
	v_addc_co_u32_e32 v71, vcc, 0, v9, vcc
	v_add_co_u32_e32 v72, vcc, s59, v8
	s_nop 1
	v_addc_co_u32_e32 v73, vcc, 0, v9, vcc
	v_add_co_u32_e32 v74, vcc, s54, v8
	s_nop 1
	v_addc_co_u32_e32 v75, vcc, 0, v9, vcc
	v_add_co_u32_e32 v76, vcc, s52, v8
	s_nop 1
	v_addc_co_u32_e32 v77, vcc, 0, v9, vcc
	global_load_dword v109, v[28:29], off nt
	global_load_dword v110, v[30:31], off nt
	global_load_dword v111, v[66:67], off nt
	global_load_dword v112, v[68:69], off nt
	global_load_dword v113, v[70:71], off nt
	global_load_dword v114, v[72:73], off nt
	global_load_dword v115, v[74:75], off nt
	s_nop 0
	global_load_dword v76, v[76:77], off nt
	v_add_co_u32_e32 v28, vcc, s53, v8
	s_nop 1
	v_addc_co_u32_e32 v29, vcc, 0, v9, vcc
	v_add_co_u32_e32 v30, vcc, s55, v8
	s_nop 1
	v_addc_co_u32_e32 v31, vcc, 0, v9, vcc
	v_add_co_u32_e32 v66, vcc, s97, v8
	s_nop 1
	v_addc_co_u32_e32 v67, vcc, 0, v9, vcc
	v_add_co_u32_e32 v68, vcc, s3, v8
	s_nop 1
	v_addc_co_u32_e32 v69, vcc, 0, v9, vcc
	v_add_co_u32_e32 v70, vcc, s85, v8
	s_nop 1
	v_addc_co_u32_e32 v71, vcc, 0, v9, vcc
	v_add_co_u32_e32 v72, vcc, s87, v8
	s_nop 1
	v_addc_co_u32_e32 v73, vcc, 0, v9, vcc
	v_add_co_u32_e32 v74, vcc, s93, v8
	s_nop 1
	v_addc_co_u32_e32 v75, vcc, 0, v9, vcc
	v_add_co_u32_e32 v8, vcc, s11, v8
	s_nop 1
	v_addc_co_u32_e32 v9, vcc, 0, v9, vcc
	global_load_dword v28, v[28:29], off nt
	s_nop 0
	global_load_dword v29, v[30:31], off nt
	s_nop 0
	global_load_dword v30, v[66:67], off nt
	global_load_dword v31, v[68:69], off nt
	s_nop 0
	global_load_dword v66, v[70:71], off nt
	global_load_dword v67, v[72:73], off nt
	global_load_dword v68, v[74:75], off nt
	s_nop 0
	global_load_dword v8, v[8:9], off nt
	s_waitcnt vmcnt(62)
	ds_write2_b32 v32, v12, v13 offset1:65
	s_waitcnt vmcnt(60)
	ds_write2_b32 v32, v14, v15 offset0:130 offset1:195
	s_waitcnt vmcnt(58)
	ds_write2_b32 v47, v16, v17 offset0:4 offset1:69
	s_waitcnt vmcnt(56)
	ds_write2_b32 v47, v18, v19 offset0:134 offset1:199
	s_waitcnt vmcnt(54)
	ds_write2_b32 v48, v20, v21 offset0:8 offset1:73
	s_waitcnt vmcnt(52)
	ds_write2_b32 v48, v22, v23 offset0:138 offset1:203
	s_waitcnt vmcnt(50)
	ds_write2_b32 v49, v24, v25 offset0:12 offset1:77
	s_waitcnt vmcnt(48)
	ds_write2_b32 v49, v26, v27 offset0:142 offset1:207
	s_waitcnt vmcnt(46)
	ds_write2_b32 v50, v65, v78 offset0:16 offset1:81
	s_waitcnt vmcnt(44)
	ds_write2_b32 v50, v79, v80 offset0:146 offset1:211
	s_waitcnt vmcnt(42)
	ds_write2_b32 v51, v81, v82 offset0:20 offset1:85
	s_waitcnt vmcnt(40)
	ds_write2_b32 v51, v83, v84 offset0:150 offset1:215
	s_waitcnt vmcnt(38)
	ds_write2_b32 v52, v85, v86 offset0:24 offset1:89
	s_waitcnt vmcnt(36)
	ds_write2_b32 v52, v87, v88 offset0:154 offset1:219
	s_waitcnt vmcnt(34)
	ds_write2_b32 v53, v89, v90 offset0:28 offset1:93
	s_waitcnt vmcnt(32)
	ds_write2_b32 v53, v91, v92 offset0:158 offset1:223
	s_waitcnt vmcnt(30)
	ds_write2_b32 v54, v93, v94 offset0:32 offset1:97
	s_waitcnt vmcnt(28)
	ds_write2_b32 v54, v95, v96 offset0:162 offset1:227
	s_waitcnt vmcnt(26)
	ds_write2_b32 v55, v97, v98 offset0:36 offset1:101
	s_waitcnt vmcnt(24)
	ds_write2_b32 v55, v99, v100 offset0:166 offset1:231
	s_waitcnt vmcnt(22)
	ds_write2_b32 v56, v101, v102 offset0:40 offset1:105
	s_waitcnt vmcnt(20)
	ds_write2_b32 v56, v103, v104 offset0:170 offset1:235
	s_waitcnt vmcnt(18)
	ds_write2_b32 v57, v105, v106 offset0:44 offset1:109
	s_waitcnt vmcnt(16)
	ds_write2_b32 v57, v107, v108 offset0:174 offset1:239
	s_waitcnt vmcnt(14)
; #define LAS __attribute__((address_space(3)))
; __device__ __forceinline__ unsigned cvt_pk_bf16(float lo, float hi) { unsigned r; asm volatile("v_cvt_pk_bf16_f32 %0, %1, %2" : "=v"(r) : "v"(lo), "v"(hi)); return r; }
; __device__ __forceinline__ void transpose_item(const float* W, int K, int Nsrc, bf16_t* WT, int Ndst, const float* gain, int maptype, LAS float* scr, int item, int lane) {
;     ...
;         for (int i = 0; i < 32; ++i) { float x = (src >= 0) ? v[i] : 0.f; if (gain) x *= gain[k0 + 32 * h + i]; scr[(32 * h + i) * 65 + lane] = x; }
;     }
;     asm volatile("s_waitcnt lgkmcnt(0)" ::: "memory");
;     const int cidx = lane & 7;
; #pragma unroll
;     for (int j = 0; j < 8; ++j) { const int n = (lane >> 3) + 8 * j; const LAS float* s = scr + (8 * cidx) * 65 + n;
;         u32x4 o; o.x = cvt_pk_bf16(s[0 * 65], s[1 * 65]); o.y = cvt_pk_bf16(s[2 * 65], s[3 * 65]); o.z = cvt_pk_bf16(s[4 * 65], s[5 * 65]); o.w = cvt_pk_bf16(s[6 * 65], s[7 * 65]);
;         *(u32x4*)(WT + (size_t)(n0 + n) * K + k0 + 8 * cidx) = o; }
;     asm volatile("s_waitcnt lgkmcnt(0)" ::: "memory");
	ds_write2_b32 v58, v109, v110 offset0:48 offset1:113
	s_waitcnt vmcnt(12)
	ds_write2_b32 v58, v111, v112 offset0:178 offset1:243
	s_waitcnt vmcnt(10)
	ds_write2_b32 v59, v113, v114 offset0:52 offset1:117
	s_waitcnt vmcnt(8)
	ds_write2_b32 v59, v115, v76 offset0:182 offset1:247
	s_waitcnt vmcnt(6)
	ds_write2_b32 v60, v28, v29 offset0:56 offset1:121
	s_waitcnt vmcnt(4)
	ds_write2_b32 v60, v30, v31 offset0:186 offset1:251
	s_waitcnt vmcnt(2)
	ds_write2_b32 v61, v66, v67 offset0:60 offset1:125
	s_waitcnt vmcnt(0)
	ds_write2_b32 v61, v68, v8 offset0:190 offset1:255
	s_waitcnt lgkmcnt(0)
	ds_read2_b32 v[8:9], v34 offset1:65
	s_waitcnt lgkmcnt(0)
	v_cvt_pk_bf16_f32 v12, v8, v9
	ds_read2_b32 v[8:9], v34 offset0:130 offset1:195
	v_lshlrev_b32_e32 v16, 1, v11
	v_mov_b32_e32 v17, v5
	s_waitcnt lgkmcnt(0)
	v_cvt_pk_bf16_f32 v13, v8, v9
	ds_read2_b32 v[8:9], v62 offset0:4 offset1:69
	v_lshl_add_u64 v[6:7], v[6:7], 0, v[16:17]
	v_or_b32_e32 v11, v10, v33
	s_waitcnt lgkmcnt(0)
	v_cvt_pk_bf16_f32 v14, v8, v9
	ds_read2_b32 v[8:9], v62 offset0:134 offset1:199
	v_lshl_add_u64 v[6:7], v[6:7], 0, v[4:5]
	v_lshlrev_b32_e32 v16, 12, v11
	s_waitcnt lgkmcnt(0)
	v_cvt_pk_bf16_f32 v15, v8, v9
	ds_read2_b32 v[8:9], v34 offset0:8 offset1:73
	v_lshl_add_u64 v[16:17], v[6:7], 0, v[16:17]
	global_store_dwordx4 v[16:17], v[12:15], off
	v_or_b32_e32 v11, v10, v35
	v_lshlrev_b32_e32 v16, 12, v11
	s_waitcnt lgkmcnt(0)
	v_cvt_pk_bf16_f32 v12, v8, v9
	ds_read2_b32 v[8:9], v34 offset0:138 offset1:203
	s_waitcnt lgkmcnt(0)
	v_cvt_pk_bf16_f32 v13, v8, v9
	ds_read2_b32 v[8:9], v62 offset0:12 offset1:77
	s_waitcnt lgkmcnt(0)
	v_cvt_pk_bf16_f32 v14, v8, v9
	ds_read2_b32 v[8:9], v62 offset0:142 offset1:207
	v_mov_b32_e32 v17, v5
	s_waitcnt lgkmcnt(0)
	v_cvt_pk_bf16_f32 v15, v8, v9
	ds_read2_b32 v[8:9], v34 offset0:16 offset1:81
	v_lshl_add_u64 v[16:17], v[6:7], 0, v[16:17]
	global_store_dwordx4 v[16:17], v[12:15], off
	v_or_b32_e32 v11, v10, v36
	v_lshlrev_b32_e32 v16, 12, v11
	s_waitcnt lgkmcnt(0)
	v_cvt_pk_bf16_f32 v12, v8, v9
	ds_read2_b32 v[8:9], v34 offset0:146 offset1:211
	s_waitcnt lgkmcnt(0)
	v_cvt_pk_bf16_f32 v13, v8, v9
	ds_read2_b32 v[8:9], v62 offset0:20 offset1:85
	s_waitcnt lgkmcnt(0)
	v_cvt_pk_bf16_f32 v14, v8, v9
	ds_read2_b32 v[8:9], v62 offset0:150 offset1:215
	v_mov_b32_e32 v17, v5
	s_waitcnt lgkmcnt(0)
	v_cvt_pk_bf16_f32 v15, v8, v9
	ds_read2_b32 v[8:9], v34 offset0:24 offset1:89
	v_lshl_add_u64 v[16:17], v[6:7], 0, v[16:17]
	global_store_dwordx4 v[16:17], v[12:15], off
	v_or_b32_e32 v11, v10, v37
	v_lshlrev_b32_e32 v16, 12, v11
	s_waitcnt lgkmcnt(0)
	v_cvt_pk_bf16_f32 v12, v8, v9
	ds_read2_b32 v[8:9], v34 offset0:154 offset1:219
	s_waitcnt lgkmcnt(0)
	v_cvt_pk_bf16_f32 v13, v8, v9
	ds_read2_b32 v[8:9], v62 offset0:28 offset1:93
	s_waitcnt lgkmcnt(0)
	v_cvt_pk_bf16_f32 v14, v8, v9
	ds_read2_b32 v[8:9], v62 offset0:158 offset1:223
	v_mov_b32_e32 v17, v5
	s_waitcnt lgkmcnt(0)
	v_cvt_pk_bf16_f32 v15, v8, v9
	ds_read2_b32 v[8:9], v34 offset0:32 offset1:97
	v_lshl_add_u64 v[16:17], v[6:7], 0, v[16:17]
	global_store_dwordx4 v[16:17], v[12:15], off
	v_or_b32_e32 v11, v10, v38
	v_lshlrev_b32_e32 v16, 12, v11
	s_waitcnt lgkmcnt(0)
	v_cvt_pk_bf16_f32 v12, v8, v9
	ds_read2_b32 v[8:9], v34 offset0:162 offset1:227
	s_waitcnt lgkmcnt(0)
	v_cvt_pk_bf16_f32 v13, v8, v9
	ds_read2_b32 v[8:9], v62 offset0:36 offset1:101
	s_waitcnt lgkmcnt(0)
	v_cvt_pk_bf16_f32 v14, v8, v9
	ds_read2_b32 v[8:9], v62 offset0:166 offset1:231
	v_mov_b32_e32 v17, v5
	s_waitcnt lgkmcnt(0)
	v_cvt_pk_bf16_f32 v15, v8, v9
	ds_read2_b32 v[8:9], v34 offset0:40 offset1:105
	v_lshl_add_u64 v[16:17], v[6:7], 0, v[16:17]
	global_store_dwordx4 v[16:17], v[12:15], off
	v_or_b32_e32 v11, v10, v39
	v_lshlrev_b32_e32 v16, 12, v11
	s_waitcnt lgkmcnt(0)
	v_cvt_pk_bf16_f32 v12, v8, v9
	ds_read2_b32 v[8:9], v34 offset0:170 offset1:235
	s_waitcnt lgkmcnt(0)
	v_cvt_pk_bf16_f32 v13, v8, v9
	ds_read2_b32 v[8:9], v62 offset0:44 offset1:109
	s_waitcnt lgkmcnt(0)
	v_cvt_pk_bf16_f32 v14, v8, v9
	ds_read2_b32 v[8:9], v62 offset0:174 offset1:239
	v_mov_b32_e32 v17, v5
	s_waitcnt lgkmcnt(0)
	v_cvt_pk_bf16_f32 v15, v8, v9
	ds_read2_b32 v[8:9], v34 offset0:48 offset1:113
	v_lshl_add_u64 v[16:17], v[6:7], 0, v[16:17]
	global_store_dwordx4 v[16:17], v[12:15], off
	v_or_b32_e32 v11, v10, v40
	v_lshlrev_b32_e32 v16, 12, v11
	s_waitcnt lgkmcnt(0)
	v_cvt_pk_bf16_f32 v12, v8, v9
	ds_read2_b32 v[8:9], v34 offset0:178 offset1:243
	s_waitcnt lgkmcnt(0)
	v_cvt_pk_bf16_f32 v13, v8, v9
	ds_read2_b32 v[8:9], v62 offset0:52 offset1:117
	s_waitcnt lgkmcnt(0)
	v_cvt_pk_bf16_f32 v14, v8, v9
	ds_read2_b32 v[8:9], v62 offset0:182 offset1:247
	v_mov_b32_e32 v17, v5
	s_waitcnt lgkmcnt(0)
	v_cvt_pk_bf16_f32 v15, v8, v9
	ds_read2_b32 v[8:9], v34 offset0:56 offset1:121
	v_lshl_add_u64 v[16:17], v[6:7], 0, v[16:17]
	global_store_dwordx4 v[16:17], v[12:15], off
	s_waitcnt lgkmcnt(0)
	s_nop 0
	v_cvt_pk_bf16_f32 v12, v8, v9
	ds_read2_b32 v[8:9], v34 offset0:186 offset1:251
	s_waitcnt lgkmcnt(0)
	v_cvt_pk_bf16_f32 v13, v8, v9
	ds_read2_b32 v[8:9], v62 offset0:60 offset1:125
	s_waitcnt lgkmcnt(0)
	v_cvt_pk_bf16_f32 v14, v8, v9
	ds_read2_b32 v[8:9], v62 offset0:190 offset1:255
	s_waitcnt lgkmcnt(0)
	v_cvt_pk_bf16_f32 v15, v8, v9
	v_or_b32_e32 v8, v10, v41
	v_lshlrev_b32_e32 v8, 12, v8
	v_mov_b32_e32 v9, v5
	v_lshl_add_u64 v[6:7], v[6:7], 0, v[8:9]
	global_store_dwordx4 v[6:7], v[12:15], off
	s_waitcnt lgkmcnt(0)

; #define LAS __attribute__((address_space(3)))
; __device__ __forceinline__ int map_in(int n) {
;     if (n < 2048) return (n & ~127) + ropeperm(n & 127);
;     if (n < 5120) { const int rel = n - 2048, j = rel >> 9, p = rel & 127; const int d = (j == 2 || j == 4) ? ropeperm(p) : p; return 2048 + (rel & ~127) + d; }
;     if (n < 11264) return 5168 + (n - 5120);
;     if (n < 15360) return 11312 + (n - 11264);
;     if (n < 15408) return 5120 + (n - 15360);
;     return -1;
; }
; __device__ __forceinline__ void transpose_item(const float* W, int K, int Nsrc, bf16_t* WT, int Ndst, const float* gain, int maptype, LAS float* scr, int item, int lane) {
;     const int nblk = Ndst / 64, kb = item / nblk, nb = item % nblk, k0 = 64 * kb, n0 = 64 * nb;
;     const int nd = n0 + lane; const int src = (maptype == MAP_IN) ? map_in(nd) : nd;
;     const float* wp = W + (size_t)k0 * Nsrc + (src >= 0 ? src : 0);
; #pragma unroll
;     for (int h = 0; h < 2; ++h) {
;         float v[32];
; #pragma unroll
;         for (int i = 0; i < 32; ++i) v[i] = wp[(size_t)(32 * h + i) * Nsrc];
; #pragma unroll
;         for (int i = 0; i < 32; ++i) { float x = (src >= 0) ? v[i] : 0.f; if (gain) x *= gain[k0 + 32 * h + i]; scr[(32 * h + i) * 65 + lane] = x; }
.LBB0_113:
	s_or_b64 exec, exec, s[4:5]
	v_mov_b64_e32 v[12:13], s[16:17]
	s_mov_b32 s4, 0x7860000
	v_lshlrev_b32_sdwa v8, v63, sext(v8) dst_sel:DWORD dst_unused:UNUSED_PAD src0_sel:DWORD src1_sel:WORD_0
	v_cmp_lt_i32_e64 s[6:7], -1, v10
	v_mad_i64_i32 v[12:13], s[4:5], v6, s4, v[12:13]
	v_mul_hi_i32_i24_e32 v15, 0xf0c0, v8
	v_mul_i32_i24_e32 v14, 0xf0c0, v8
	v_cndmask_b32_e64 v10, 0, v10, s[6:7]
	v_lshl_add_u64 v[12:13], v[12:13], 0, v[14:15]
	v_ashrrev_i32_e32 v11, 31, v10
	v_lshl_add_u64 v[12:13], v[10:11], 2, v[12:13]
	v_add_co_u32_e32 v10, vcc, s95, v12
	s_mov_b32 s4, 0x2d000
	s_nop 0
	v_addc_co_u32_e32 v11, vcc, 0, v13, vcc
	v_add_co_u32_e32 v14, vcc, s89, v12
	v_ashrrev_i32_e32 v9, 31, v8
	s_nop 0
	v_addc_co_u32_e32 v15, vcc, 0, v13, vcc
	v_add_co_u32_e32 v16, vcc, s4, v12
	s_mov_b32 s4, 0x4b000
	s_nop 0
	v_addc_co_u32_e32 v17, vcc, 0, v13, vcc
	v_add_co_u32_e32 v18, vcc, s58, v12
	s_nop 1
	v_addc_co_u32_e32 v19, vcc, 0, v13, vcc
	v_add_co_u32_e32 v20, vcc, s4, v12
	s_mov_b32 s4, 0x69000
	s_nop 0
	v_addc_co_u32_e32 v21, vcc, 0, v13, vcc
	v_add_co_u32_e32 v22, vcc, s9, v12
	s_nop 1
	v_addc_co_u32_e32 v23, vcc, 0, v13, vcc
	v_add_co_u32_e32 v24, vcc, s4, v12
	s_mov_b32 s4, 0x87000
	s_nop 0
	v_addc_co_u32_e32 v25, vcc, 0, v13, vcc
	global_load_dword v88, v[12:13], off nt
	global_load_dword v77, v[10:11], off offset:192 nt
	global_load_dword v76, v[14:15], off offset:384 nt
	global_load_dword v75, v[16:17], off offset:576 nt
	global_load_dword v74, v[18:19], off offset:768 nt
	global_load_dword v72, v[20:21], off offset:960 nt
	global_load_dword v70, v[22:23], off offset:1152 nt
	global_load_dword v68, v[24:25], off offset:1344 nt
	v_add_co_u32_e32 v10, vcc, s85, v12
	s_nop 1
	v_addc_co_u32_e32 v11, vcc, 0, v13, vcc
	v_add_co_u32_e32 v14, vcc, s4, v12
	s_mov_b32 s4, 0x96000
	s_nop 0
	v_addc_co_u32_e32 v15, vcc, 0, v13, vcc
	v_add_co_u32_e32 v16, vcc, s4, v12
	s_mov_b32 s4, 0xa5000
	s_nop 0
	v_addc_co_u32_e32 v17, vcc, 0, v13, vcc
	v_add_co_u32_e32 v18, vcc, s4, v12
	s_mov_b32 s4, 0xb4000
	s_nop 0
	v_addc_co_u32_e32 v19, vcc, 0, v13, vcc
	v_add_co_u32_e32 v20, vcc, s4, v12
	s_mov_b32 s4, 0xc3000
	s_nop 0
	v_addc_co_u32_e32 v21, vcc, 0, v13, vcc
	v_add_co_u32_e32 v22, vcc, s4, v12
	s_mov_b32 s4, 0xd2000
	s_nop 0
	v_addc_co_u32_e32 v23, vcc, 0, v13, vcc
	v_add_co_u32_e32 v24, vcc, s4, v12
	s_mov_b32 s4, 0xe1000
	s_nop 0
	v_addc_co_u32_e32 v25, vcc, 0, v13, vcc
	v_add_co_u32_e32 v26, vcc, s4, v12
	s_mov_b32 s4, 0xf0000
	s_nop 0
	v_addc_co_u32_e32 v27, vcc, 0, v13, vcc
	global_load_dword v73, v[10:11], off offset:1536 nt
	global_load_dword v71, v[14:15], off offset:1728 nt
	global_load_dword v69, v[16:17], off offset:1920 nt
	global_load_dword v67, v[18:19], off offset:2112 nt
	global_load_dword v66, v[20:21], off offset:2304 nt
	global_load_dword v31, v[22:23], off offset:2496 nt
	global_load_dword v29, v[24:25], off offset:2688 nt
	s_nop 0
	global_load_dword v27, v[26:27], off offset:2880 nt
	v_add_co_u32_e32 v10, vcc, s4, v12
	s_mov_b32 s4, 0xff000
	s_nop 0
	v_addc_co_u32_e32 v11, vcc, 0, v13, vcc
	v_add_co_u32_e32 v14, vcc, s4, v12
	s_mov_b32 s4, 0x10e000
	s_nop 0
	v_addc_co_u32_e32 v15, vcc, 0, v13, vcc
	v_add_co_u32_e32 v16, vcc, s4, v12
	s_mov_b32 s4, 0x11d000
	s_nop 0
	v_addc_co_u32_e32 v17, vcc, 0, v13, vcc
	v_add_co_u32_e32 v18, vcc, s4, v12
	s_mov_b32 s4, 0x12c000
	s_nop 0
	v_addc_co_u32_e32 v19, vcc, 0, v13, vcc
	v_add_co_u32_e32 v20, vcc, s4, v12
	s_mov_b32 s4, 0x13b000
	s_nop 0
	v_addc_co_u32_e32 v21, vcc, 0, v13, vcc
	v_add_co_u32_e32 v22, vcc, s4, v12
	s_mov_b32 s4, 0x14b000
	s_nop 0
	v_addc_co_u32_e32 v23, vcc, 0, v13, vcc
	v_add_co_u32_e32 v78, vcc, s4, v12
	s_mov_b32 s4, 0x15a000
	s_nop 0
	v_addc_co_u32_e32 v79, vcc, 0, v13, vcc
	v_add_co_u32_e32 v80, vcc, s4, v12
	s_mov_b32 s4, 0x169000
	s_nop 0
	v_addc_co_u32_e32 v81, vcc, 0, v13, vcc
	global_load_dword v65, v[10:11], off offset:3072 nt
	global_load_dword v30, v[14:15], off offset:3264 nt
	global_load_dword v28, v[16:17], off offset:3456 nt
	global_load_dword v26, v[18:19], off offset:3648 nt
	global_load_dword v24, v[20:21], off offset:3840 nt
	s_nop 0
	global_load_dword v22, v[22:23], off offset:4032 nt
	s_nop 0
	global_load_dword v20, v[78:79], off offset:128 nt
	global_load_dword v18, v[80:81], off offset:320 nt
	v_add_co_u32_e32 v10, vcc, s4, v12
	s_mov_b32 s4, 0x178000
	s_nop 0
	v_addc_co_u32_e32 v11, vcc, 0, v13, vcc
	v_add_co_u32_e32 v14, vcc, s4, v12
	s_mov_b32 s4, 0x187000
	s_nop 0
	v_addc_co_u32_e32 v15, vcc, 0, v13, vcc
	v_add_co_u32_e32 v16, vcc, s4, v12
	s_mov_b32 s4, 0x196000
	s_nop 0
	v_addc_co_u32_e32 v17, vcc, 0, v13, vcc
	v_add_co_u32_e32 v78, vcc, s4, v12
	s_mov_b32 s4, 0x1a5000
	s_nop 0
	v_addc_co_u32_e32 v79, vcc, 0, v13, vcc
	v_add_co_u32_e32 v80, vcc, s4, v12
	s_nop 1
	v_addc_co_u32_e32 v81, vcc, 0, v13, vcc
	v_add_co_u32_e32 v82, vcc, 0x1b4000, v12
	s_nop 1
	v_addc_co_u32_e32 v83, vcc, 0, v13, vcc
	v_add_co_u32_e32 v84, vcc, 0x1c3000, v12
	s_nop 1
	v_addc_co_u32_e32 v85, vcc, 0, v13, vcc
	v_add_co_u32_e32 v86, vcc, 0x1d2000, v12
	s_nop 1
	v_addc_co_u32_e32 v87, vcc, 0, v13, vcc
	global_load_dword v25, v[10:11], off offset:512 nt
	global_load_dword v23, v[14:15], off offset:704 nt
	global_load_dword v21, v[16:17], off offset:896 nt
	global_load_dword v19, v[78:79], off offset:1088 nt
	s_nop 0
	global_load_dword v17, v[80:81], off offset:1280 nt
	global_load_dword v16, v[82:83], off offset:1472 nt
	global_load_dword v15, v[84:85], off offset:1664 nt
	global_load_dword v14, v[86:87], off offset:1856 nt
	v_lshlrev_b32_e32 v10, 11, v6
	v_ashrrev_i32_e32 v11, 31, v10
	v_lshl_add_u64 v[10:11], v[10:11], 2, s[14:15]
	v_cndmask_b32_e64 v79, 0, 1, s[70:71]
	s_waitcnt vmcnt(31)
	v_cndmask_b32_e64 v78, 0, v88, s[6:7]
	v_cmp_ne_u32_e64 s[4:5], 1, v79
	s_andn2_b64 vcc, exec, s[70:71]
	v_lshl_add_u64 v[10:11], v[8:9], 2, v[10:11]
	s_cbranch_vccnz .LBB0_115
	global_load_dword v79, v[10:11], off nt
	s_waitcnt vmcnt(0)
	v_mul_f32_e32 v78, v78, v79
; __device__ __forceinline__ void transpose_item(const float* W, int K, int Nsrc, bf16_t* WT, int Ndst, const float* gain, int maptype, LAS float* scr, int item, int lane) {
;     ...
;         for (int i = 0; i < 32; ++i) { float x = (src >= 0) ? v[i] : 0.f; if (gain) x *= gain[k0 + 32 * h + i]; scr[(32 * h + i) * 65 + lane] = x; }
.LBB0_115:
	s_and_b64 vcc, exec, s[4:5]
	s_waitcnt vmcnt(30)
	v_cndmask_b32_e64 v77, 0, v77, s[6:7]
	ds_write_b32 v32, v78
	s_cbranch_vccnz .LBB0_117
	global_load_dword v78, v[10:11], off offset:4 nt
	s_waitcnt vmcnt(0)
	v_mul_f32_e32 v77, v77, v78
.LBB0_117:
	s_and_b64 vcc, exec, s[4:5]
	s_waitcnt vmcnt(29)
	v_cndmask_b32_e64 v76, 0, v76, s[6:7]
	ds_write_b32 v32, v77 offset:260
	s_cbranch_vccnz .LBB0_119
	global_load_dword v77, v[10:11], off offset:8 nt
	s_waitcnt vmcnt(0)
	v_mul_f32_e32 v76, v76, v77
.LBB0_119:
	s_and_b64 vcc, exec, s[4:5]
	s_waitcnt vmcnt(28)
	v_cndmask_b32_e64 v75, 0, v75, s[6:7]
	ds_write_b32 v32, v76 offset:520
	s_cbranch_vccnz .LBB0_121
	global_load_dword v76, v[10:11], off offset:12 nt
	s_waitcnt vmcnt(0)
	v_mul_f32_e32 v75, v75, v76
.LBB0_121:
	s_and_b64 vcc, exec, s[4:5]
	s_waitcnt vmcnt(27)
	v_cndmask_b32_e64 v74, 0, v74, s[6:7]
	ds_write_b32 v32, v75 offset:780
	s_cbranch_vccnz .LBB0_123
	global_load_dword v75, v[10:11], off offset:16 nt
	s_waitcnt vmcnt(0)
	v_mul_f32_e32 v74, v74, v75
.LBB0_123:
	s_and_b64 vcc, exec, s[4:5]
	s_waitcnt vmcnt(26)
	v_cndmask_b32_e64 v72, 0, v72, s[6:7]
	ds_write_b32 v32, v74 offset:1040
	s_cbranch_vccnz .LBB0_125
	global_load_dword v74, v[10:11], off offset:20 nt
	s_waitcnt vmcnt(0)
	v_mul_f32_e32 v72, v72, v74
.LBB0_125:
	s_and_b64 vcc, exec, s[4:5]
	s_waitcnt vmcnt(25)
	v_cndmask_b32_e64 v70, 0, v70, s[6:7]
	ds_write_b32 v32, v72 offset:1300
	s_cbranch_vccnz .LBB0_127
	global_load_dword v72, v[10:11], off offset:24 nt
	s_waitcnt vmcnt(0)
	v_mul_f32_e32 v70, v70, v72
.LBB0_127:
	s_and_b64 vcc, exec, s[4:5]
	s_waitcnt vmcnt(24)
	v_cndmask_b32_e64 v68, 0, v68, s[6:7]
	ds_write_b32 v32, v70 offset:1560
	s_cbranch_vccnz .LBB0_129
	global_load_dword v70, v[10:11], off offset:28 nt
	s_waitcnt vmcnt(0)
	v_mul_f32_e32 v68, v68, v70
.LBB0_129:
	ds_write_b32 v32, v68 offset:1820
	s_and_b64 vcc, exec, s[4:5]
	s_waitcnt vmcnt(23)
	v_cndmask_b32_e64 v68, 0, v73, s[6:7]
	s_cbranch_vccnz .LBB0_131
	global_load_dword v70, v[10:11], off offset:32 nt
	s_waitcnt vmcnt(0)
	v_mul_f32_e32 v68, v68, v70
.LBB0_131:
	ds_write_b32 v32, v68 offset:2080
	s_and_b64 vcc, exec, s[4:5]
	s_waitcnt vmcnt(22)
	v_cndmask_b32_e64 v68, 0, v71, s[6:7]
	s_cbranch_vccnz .LBB0_133
	global_load_dword v70, v[10:11], off offset:36 nt
	s_waitcnt vmcnt(0)
	v_mul_f32_e32 v68, v68, v70
.LBB0_133:
	ds_write_b32 v32, v68 offset:2340
	s_and_b64 vcc, exec, s[4:5]
	s_waitcnt vmcnt(21)
	v_cndmask_b32_e64 v68, 0, v69, s[6:7]
	s_cbranch_vccnz .LBB0_135
	global_load_dword v69, v[10:11], off offset:40 nt
	s_waitcnt vmcnt(0)
	v_mul_f32_e32 v68, v68, v69
.LBB0_135:
	s_and_b64 vcc, exec, s[4:5]
	s_waitcnt vmcnt(20)
	v_cndmask_b32_e64 v67, 0, v67, s[6:7]
	ds_write_b32 v32, v68 offset:2600
	s_cbranch_vccnz .LBB0_137
	global_load_dword v68, v[10:11], off offset:44 nt
	s_waitcnt vmcnt(0)
	v_mul_f32_e32 v67, v67, v68
.LBB0_137:
	s_and_b64 vcc, exec, s[4:5]
	s_waitcnt vmcnt(19)
	v_cndmask_b32_e64 v66, 0, v66, s[6:7]
	ds_write_b32 v32, v67 offset:2860
	s_cbranch_vccnz .LBB0_139
	global_load_dword v67, v[10:11], off offset:48 nt
	s_waitcnt vmcnt(0)
	v_mul_f32_e32 v66, v66, v67
.LBB0_139:
	s_and_b64 vcc, exec, s[4:5]
	s_waitcnt vmcnt(18)
	v_cndmask_b32_e64 v31, 0, v31, s[6:7]
	ds_write_b32 v32, v66 offset:3120
	s_cbranch_vccnz .LBB0_141
	global_load_dword v66, v[10:11], off offset:52 nt
	s_waitcnt vmcnt(0)
	v_mul_f32_e32 v31, v31, v66
.LBB0_141:
	s_and_b64 vcc, exec, s[4:5]
	s_waitcnt vmcnt(17)
	v_cndmask_b32_e64 v29, 0, v29, s[6:7]
	ds_write_b32 v32, v31 offset:3380
	s_cbranch_vccnz .LBB0_143
	global_load_dword v31, v[10:11], off offset:56 nt
	s_waitcnt vmcnt(0)
	v_mul_f32_e32 v29, v29, v31
.LBB0_143:
	s_and_b64 vcc, exec, s[4:5]
	s_waitcnt vmcnt(16)
	v_cndmask_b32_e64 v27, 0, v27, s[6:7]
	ds_write_b32 v32, v29 offset:3640
	s_cbranch_vccnz .LBB0_145
	global_load_dword v29, v[10:11], off offset:60 nt
	s_waitcnt vmcnt(0)
	v_mul_f32_e32 v27, v27, v29
.LBB0_145:
	ds_write_b32 v32, v27 offset:3900
	s_and_b64 vcc, exec, s[4:5]
	s_waitcnt vmcnt(15)
	v_cndmask_b32_e64 v27, 0, v65, s[6:7]
	s_cbranch_vccnz .LBB0_147
	global_load_dword v29, v[10:11], off offset:64 nt
	s_waitcnt vmcnt(0)
	v_mul_f32_e32 v27, v27, v29
.LBB0_147:
	ds_write_b32 v32, v27 offset:4160
	s_and_b64 vcc, exec, s[4:5]
	s_waitcnt vmcnt(14)
	v_cndmask_b32_e64 v27, 0, v30, s[6:7]
	s_cbranch_vccnz .LBB0_149
	global_load_dword v29, v[10:11], off offset:68 nt
	s_waitcnt vmcnt(0)
	v_mul_f32_e32 v27, v27, v29
.LBB0_149:
	ds_write_b32 v32, v27 offset:4420
	s_and_b64 vcc, exec, s[4:5]
	s_waitcnt vmcnt(13)
	v_cndmask_b32_e64 v27, 0, v28, s[6:7]
	s_cbranch_vccnz .LBB0_151
	global_load_dword v28, v[10:11], off offset:72 nt
	s_waitcnt vmcnt(0)
	v_mul_f32_e32 v27, v27, v28
.LBB0_151:
	s_and_b64 vcc, exec, s[4:5]
	s_waitcnt vmcnt(12)
	v_cndmask_b32_e64 v26, 0, v26, s[6:7]
	ds_write_b32 v32, v27 offset:4680
	s_cbranch_vccnz .LBB0_153
	global_load_dword v27, v[10:11], off offset:76 nt
	s_waitcnt vmcnt(0)
	v_mul_f32_e32 v26, v26, v27
.LBB0_153:
	s_and_b64 vcc, exec, s[4:5]
	s_waitcnt vmcnt(11)
	v_cndmask_b32_e64 v24, 0, v24, s[6:7]
	ds_write_b32 v32, v26 offset:4940
	s_cbranch_vccnz .LBB0_155
	global_load_dword v26, v[10:11], off offset:80 nt
	s_waitcnt vmcnt(0)
	v_mul_f32_e32 v24, v24, v26
.LBB0_155:
	s_and_b64 vcc, exec, s[4:5]
	s_waitcnt vmcnt(10)
	v_cndmask_b32_e64 v22, 0, v22, s[6:7]
	ds_write_b32 v32, v24 offset:5200
	s_cbranch_vccnz .LBB0_157
	global_load_dword v24, v[10:11], off offset:84 nt
	s_waitcnt vmcnt(0)
	v_mul_f32_e32 v22, v22, v24
.LBB0_157:
	s_and_b64 vcc, exec, s[4:5]
	s_waitcnt vmcnt(9)
	v_cndmask_b32_e64 v20, 0, v20, s[6:7]
	ds_write_b32 v32, v22 offset:5460
	s_cbranch_vccnz .LBB0_159
	global_load_dword v22, v[10:11], off offset:88 nt
	s_waitcnt vmcnt(0)
	v_mul_f32_e32 v20, v20, v22
; __device__ __forceinline__ void transpose_item(const float* W, int K, int Nsrc, bf16_t* WT, int Ndst, const float* gain, int maptype, LAS float* scr, int item, int lane) {
;     ...
;     for (int h = 0; h < 2; ++h) {
;         float v[32];
; #pragma unroll
;         for (int i = 0; i < 32; ++i) v[i] = wp[(size_t)(32 * h + i) * Nsrc];
; #pragma unroll
;         for (int i = 0; i < 32; ++i) { float x = (src >= 0) ? v[i] : 0.f; if (gain) x *= gain[k0 + 32 * h + i]; scr[(32 * h + i) * 65 + lane] = x; }
.LBB0_159:
	s_and_b64 vcc, exec, s[4:5]
	s_waitcnt vmcnt(8)
	v_cndmask_b32_e64 v18, 0, v18, s[6:7]
	ds_write_b32 v32, v20 offset:5720
	s_cbranch_vccnz .LBB0_161
	global_load_dword v20, v[10:11], off offset:92 nt
	s_waitcnt vmcnt(0)
	v_mul_f32_e32 v18, v18, v20
.LBB0_161:
	ds_write_b32 v32, v18 offset:5980
	s_and_b64 vcc, exec, s[4:5]
	s_waitcnt vmcnt(7)
	v_cndmask_b32_e64 v18, 0, v25, s[6:7]
	s_cbranch_vccnz .LBB0_163
	global_load_dword v20, v[10:11], off offset:96 nt
	s_waitcnt vmcnt(0)
	v_mul_f32_e32 v18, v18, v20
.LBB0_163:
	ds_write_b32 v32, v18 offset:6240
	s_and_b64 vcc, exec, s[4:5]
	s_waitcnt vmcnt(6)
	v_cndmask_b32_e64 v18, 0, v23, s[6:7]
	s_cbranch_vccnz .LBB0_165
	global_load_dword v20, v[10:11], off offset:100 nt
	s_waitcnt vmcnt(0)
	v_mul_f32_e32 v18, v18, v20
.LBB0_165:
	ds_write_b32 v32, v18 offset:6500
	s_and_b64 vcc, exec, s[4:5]
	s_waitcnt vmcnt(5)
	v_cndmask_b32_e64 v18, 0, v21, s[6:7]
	s_cbranch_vccnz .LBB0_167
	global_load_dword v20, v[10:11], off offset:104 nt
	s_waitcnt vmcnt(0)
	v_mul_f32_e32 v18, v18, v20
.LBB0_167:
	ds_write_b32 v32, v18 offset:6760
	s_and_b64 vcc, exec, s[4:5]
	s_waitcnt vmcnt(4)
	v_cndmask_b32_e64 v18, 0, v19, s[6:7]
	s_cbranch_vccnz .LBB0_169
	global_load_dword v19, v[10:11], off offset:108 nt
	s_waitcnt vmcnt(0)
	v_mul_f32_e32 v18, v18, v19
.LBB0_169:
	s_and_b64 vcc, exec, s[4:5]
	s_waitcnt vmcnt(3)
	v_cndmask_b32_e64 v17, 0, v17, s[6:7]
	ds_write_b32 v32, v18 offset:7020
	s_cbranch_vccnz .LBB0_171
	global_load_dword v18, v[10:11], off offset:112 nt
	s_waitcnt vmcnt(0)
	v_mul_f32_e32 v17, v17, v18
.LBB0_171:
	s_and_b64 vcc, exec, s[4:5]
	s_waitcnt vmcnt(2)
	v_cndmask_b32_e64 v16, 0, v16, s[6:7]
	ds_write_b32 v32, v17 offset:7280
	s_cbranch_vccnz .LBB0_173
	global_load_dword v17, v[10:11], off offset:116 nt
	s_waitcnt vmcnt(0)
	v_mul_f32_e32 v16, v16, v17
.LBB0_173:
	s_and_b64 vcc, exec, s[4:5]
	s_waitcnt vmcnt(1)
	v_cndmask_b32_e64 v15, 0, v15, s[6:7]
	ds_write_b32 v32, v16 offset:7540
	s_cbranch_vccnz .LBB0_175
	global_load_dword v16, v[10:11], off offset:120 nt
	s_waitcnt vmcnt(0)
	v_mul_f32_e32 v15, v15, v16
.LBB0_175:
	s_and_b64 vcc, exec, s[4:5]
	s_waitcnt vmcnt(0)
	v_cndmask_b32_e64 v67, 0, v14, s[6:7]
	ds_write_b32 v32, v15 offset:7800
	s_cbranch_vccnz .LBB0_177
	global_load_dword v14, v[10:11], off offset:124 nt
	s_waitcnt vmcnt(0)
	v_mul_f32_e32 v67, v67, v14
.LBB0_177:
	v_add_co_u32_e32 v14, vcc, 0x1e1000, v12
	s_nop 1
	v_addc_co_u32_e32 v15, vcc, 0, v13, vcc
	v_add_co_u32_e32 v16, vcc, 0x1f0000, v12
	s_nop 1
	v_addc_co_u32_e32 v17, vcc, 0, v13, vcc
	v_add_co_u32_e32 v18, vcc, 0x1ff000, v12
	s_nop 1
	v_addc_co_u32_e32 v19, vcc, 0, v13, vcc
	v_add_co_u32_e32 v20, vcc, 0x20e000, v12
	s_nop 1
	v_addc_co_u32_e32 v21, vcc, 0, v13, vcc
	v_add_co_u32_e32 v22, vcc, 0x21d000, v12
	s_nop 1
	v_addc_co_u32_e32 v23, vcc, 0, v13, vcc
	v_add_co_u32_e32 v24, vcc, 0x22c000, v12
	s_nop 1
	v_addc_co_u32_e32 v25, vcc, 0, v13, vcc
	v_add_co_u32_e32 v26, vcc, 0x23b000, v12
	s_nop 1
	v_addc_co_u32_e32 v27, vcc, 0, v13, vcc
	v_add_co_u32_e32 v30, vcc, 0x24a000, v12
	s_nop 1
	v_addc_co_u32_e32 v31, vcc, 0, v13, vcc
	global_load_dword v77, v[14:15], off offset:2048 nt
	global_load_dword v76, v[16:17], off offset:2240 nt
	global_load_dword v74, v[18:19], off offset:2432 nt
	global_load_dword v72, v[20:21], off offset:2624 nt
	global_load_dword v69, v[22:23], off offset:2816 nt
	global_load_dword v65, v[24:25], off offset:3008 nt
	global_load_dword v28, v[26:27], off offset:3200 nt
	s_nop 0
	global_load_dword v25, v[30:31], off offset:3392 nt
	v_add_co_u32_e32 v14, vcc, 0x259000, v12
	s_nop 1
	v_addc_co_u32_e32 v15, vcc, 0, v13, vcc
	v_add_co_u32_e32 v16, vcc, 0x268000, v12
	s_nop 1
	v_addc_co_u32_e32 v17, vcc, 0, v13, vcc
	v_add_co_u32_e32 v18, vcc, 0x277000, v12
	s_nop 1
	v_addc_co_u32_e32 v19, vcc, 0, v13, vcc
	v_add_co_u32_e32 v20, vcc, 0x287000, v12
	s_nop 1
	v_addc_co_u32_e32 v21, vcc, 0, v13, vcc
	v_add_co_u32_e32 v22, vcc, 0x296000, v12
	s_nop 1
	v_addc_co_u32_e32 v23, vcc, 0, v13, vcc
	v_add_co_u32_e32 v26, vcc, 0x2a5000, v12
	s_nop 1
	v_addc_co_u32_e32 v27, vcc, 0, v13, vcc
	v_add_co_u32_e32 v30, vcc, 0x2b4000, v12
	s_nop 1
	v_addc_co_u32_e32 v31, vcc, 0, v13, vcc
	v_add_co_u32_e32 v78, vcc, 0x2c3000, v12
	s_nop 1
	v_addc_co_u32_e32 v79, vcc, 0, v13, vcc
	global_load_dword v75, v[14:15], off offset:3584 nt
	global_load_dword v73, v[16:17], off offset:3776 nt
	global_load_dword v70, v[18:19], off offset:3968 nt
	global_load_dword v66, v[20:21], off offset:64 nt
	global_load_dword v29, v[22:23], off offset:256 nt
	global_load_dword v24, v[26:27], off offset:448 nt
	s_nop 0
	global_load_dword v21, v[30:31], off offset:640 nt
	global_load_dword v19, v[78:79], off offset:832 nt
	v_add_co_u32_e32 v14, vcc, 0x2d2000, v12
	s_nop 1
	v_addc_co_u32_e32 v15, vcc, 0, v13, vcc
	v_add_co_u32_e32 v16, vcc, 0x2e1000, v12
	s_nop 1
	v_addc_co_u32_e32 v17, vcc, 0, v13, vcc
	v_add_co_u32_e32 v22, vcc, 0x2f0000, v12
	s_nop 1
	v_addc_co_u32_e32 v23, vcc, 0, v13, vcc
	v_add_co_u32_e32 v26, vcc, 0x2ff000, v12
	s_nop 1
	v_addc_co_u32_e32 v27, vcc, 0, v13, vcc
	v_add_co_u32_e32 v78, vcc, 0x30e000, v12
	s_nop 1
	v_addc_co_u32_e32 v79, vcc, 0, v13, vcc
	v_add_co_u32_e32 v80, vcc, 0x31d000, v12
	s_nop 1
	v_addc_co_u32_e32 v81, vcc, 0, v13, vcc
	v_add_co_u32_e32 v82, vcc, 0x32c000, v12
	s_nop 1
	v_addc_co_u32_e32 v83, vcc, 0, v13, vcc
	v_add_co_u32_e32 v84, vcc, 0x33b000, v12
	s_nop 1
	v_addc_co_u32_e32 v85, vcc, 0, v13, vcc
	global_load_dword v71, v[14:15], off offset:1024 nt
	global_load_dword v68, v[16:17], off offset:1216 nt
	global_load_dword v30, v[22:23], off offset:1408 nt
	s_nop 0
	global_load_dword v26, v[26:27], off offset:1600 nt
; __device__ __forceinline__ void transpose_item(const float* W, int K, int Nsrc, bf16_t* WT, int Ndst, const float* gain, int maptype, LAS float* scr, int item, int lane) {
;     ...
;     for (int h = 0; h < 2; ++h) {
;         float v[32];
; #pragma unroll
;         for (int i = 0; i < 32; ++i) v[i] = wp[(size_t)(32 * h + i) * Nsrc];
; #pragma unroll
;         for (int i = 0; i < 32; ++i) { float x = (src >= 0) ? v[i] : 0.f; if (gain) x *= gain[k0 + 32 * h + i]; scr[(32 * h + i) * 65 + lane] = x; }
	s_nop 0
	global_load_dword v22, v[78:79], off offset:1792 nt
	global_load_dword v18, v[80:81], off offset:1984 nt
	global_load_dword v16, v[82:83], off offset:2176 nt
	global_load_dword v15, v[84:85], off offset:2368 nt
	v_add_co_u32_e32 v78, vcc, 0x34a000, v12
	s_nop 1
	v_addc_co_u32_e32 v79, vcc, 0, v13, vcc
	v_add_co_u32_e32 v80, vcc, 0x359000, v12
	s_nop 1
	v_addc_co_u32_e32 v81, vcc, 0, v13, vcc
	v_add_co_u32_e32 v82, vcc, 0x368000, v12
	s_nop 1
	v_addc_co_u32_e32 v83, vcc, 0, v13, vcc
	v_add_co_u32_e32 v84, vcc, 0x377000, v12
	s_nop 1
	v_addc_co_u32_e32 v85, vcc, 0, v13, vcc
	v_add_co_u32_e32 v86, vcc, 0x386000, v12
	s_nop 1
	v_addc_co_u32_e32 v87, vcc, 0, v13, vcc
	v_add_co_u32_e32 v88, vcc, 0x395000, v12
	s_nop 1
	v_addc_co_u32_e32 v89, vcc, 0, v13, vcc
	v_add_co_u32_e32 v90, vcc, 0x3a4000, v12
	s_nop 1
	v_addc_co_u32_e32 v91, vcc, 0, v13, vcc
	v_add_co_u32_e32 v92, vcc, 0x3b3000, v12
	s_nop 1
	v_addc_co_u32_e32 v93, vcc, 0, v13, vcc
	global_load_dword v31, v[78:79], off offset:2560 nt
	global_load_dword v27, v[80:81], off offset:2752 nt
	global_load_dword v23, v[82:83], off offset:2944 nt
	global_load_dword v20, v[84:85], off offset:3136 nt
	global_load_dword v17, v[86:87], off offset:3328 nt
	global_load_dword v14, v[88:89], off offset:3520 nt
	global_load_dword v13, v[90:91], off offset:3712 nt
	global_load_dword v12, v[92:93], off offset:3904 nt
	ds_write_b32 v32, v67 offset:8060
	s_and_b64 vcc, exec, s[4:5]
	s_waitcnt vmcnt(31)
	v_cndmask_b32_e64 v67, 0, v77, s[6:7]
	s_cbranch_vccnz .LBB0_179
	global_load_dword v77, v[10:11], off offset:128 nt
	s_waitcnt vmcnt(0)
	v_mul_f32_e32 v67, v67, v77
.LBB0_179:
	ds_write_b32 v32, v67 offset:8320
	s_and_b64 vcc, exec, s[4:5]
	s_waitcnt vmcnt(30)
	v_cndmask_b32_e64 v67, 0, v76, s[6:7]
	s_cbranch_vccnz .LBB0_181
	global_load_dword v76, v[10:11], off offset:132 nt
	s_waitcnt vmcnt(0)
	v_mul_f32_e32 v67, v67, v76
.LBB0_181:
	ds_write_b32 v32, v67 offset:8580
	s_and_b64 vcc, exec, s[4:5]
	s_waitcnt vmcnt(29)
	v_cndmask_b32_e64 v67, 0, v74, s[6:7]
	s_cbranch_vccnz .LBB0_183
	global_load_dword v74, v[10:11], off offset:136 nt
	s_waitcnt vmcnt(0)
	v_mul_f32_e32 v67, v67, v74
.LBB0_183:
	ds_write_b32 v32, v67 offset:8840
	s_and_b64 vcc, exec, s[4:5]
	s_waitcnt vmcnt(28)
	v_cndmask_b32_e64 v67, 0, v72, s[6:7]
	s_cbranch_vccnz .LBB0_185
	global_load_dword v72, v[10:11], off offset:140 nt
	s_waitcnt vmcnt(0)
	v_mul_f32_e32 v67, v67, v72
.LBB0_185:
	ds_write_b32 v32, v67 offset:9100
	s_and_b64 vcc, exec, s[4:5]
	s_waitcnt vmcnt(27)
	v_cndmask_b32_e64 v67, 0, v69, s[6:7]
	s_cbranch_vccnz .LBB0_187
	global_load_dword v69, v[10:11], off offset:144 nt
	s_waitcnt vmcnt(0)
	v_mul_f32_e32 v67, v67, v69
.LBB0_187:
	s_and_b64 vcc, exec, s[4:5]
	s_waitcnt vmcnt(26)
	v_cndmask_b32_e64 v65, 0, v65, s[6:7]
	ds_write_b32 v32, v67 offset:9360
	s_cbranch_vccnz .LBB0_189
	global_load_dword v67, v[10:11], off offset:148 nt
	s_waitcnt vmcnt(0)
	v_mul_f32_e32 v65, v65, v67
.LBB0_189:
	s_and_b64 vcc, exec, s[4:5]
	s_waitcnt vmcnt(25)
	v_cndmask_b32_e64 v28, 0, v28, s[6:7]
	ds_write_b32 v32, v65 offset:9620
	s_cbranch_vccnz .LBB0_191
	global_load_dword v65, v[10:11], off offset:152 nt
	s_waitcnt vmcnt(0)
	v_mul_f32_e32 v28, v28, v65
.LBB0_191:
	s_and_b64 vcc, exec, s[4:5]
	s_waitcnt vmcnt(24)
	v_cndmask_b32_e64 v25, 0, v25, s[6:7]
	ds_write_b32 v32, v28 offset:9880
	s_cbranch_vccnz .LBB0_193
	global_load_dword v28, v[10:11], off offset:156 nt
	s_waitcnt vmcnt(0)
	v_mul_f32_e32 v25, v25, v28
.LBB0_193:
	ds_write_b32 v32, v25 offset:10140
	s_and_b64 vcc, exec, s[4:5]
	s_waitcnt vmcnt(23)
	v_cndmask_b32_e64 v25, 0, v75, s[6:7]
	s_cbranch_vccnz .LBB0_195
	global_load_dword v28, v[10:11], off offset:160 nt
	s_waitcnt vmcnt(0)
	v_mul_f32_e32 v25, v25, v28
.LBB0_195:
	ds_write_b32 v32, v25 offset:10400
	s_and_b64 vcc, exec, s[4:5]
	s_waitcnt vmcnt(22)
	v_cndmask_b32_e64 v25, 0, v73, s[6:7]
	s_cbranch_vccnz .LBB0_197
	global_load_dword v28, v[10:11], off offset:164 nt
	s_waitcnt vmcnt(0)
	v_mul_f32_e32 v25, v25, v28
.LBB0_197:
	ds_write_b32 v32, v25 offset:10660
	s_and_b64 vcc, exec, s[4:5]
	s_waitcnt vmcnt(21)
	v_cndmask_b32_e64 v25, 0, v70, s[6:7]
	s_cbranch_vccnz .LBB0_199
	global_load_dword v28, v[10:11], off offset:168 nt
	s_waitcnt vmcnt(0)
	v_mul_f32_e32 v25, v25, v28
.LBB0_199:
	ds_write_b32 v32, v25 offset:10920
	s_and_b64 vcc, exec, s[4:5]
	s_waitcnt vmcnt(20)
	v_cndmask_b32_e64 v25, 0, v66, s[6:7]
	s_cbranch_vccnz .LBB0_201
	global_load_dword v28, v[10:11], off offset:172 nt
	s_waitcnt vmcnt(0)
	v_mul_f32_e32 v25, v25, v28
.LBB0_201:
	ds_write_b32 v32, v25 offset:11180
	s_and_b64 vcc, exec, s[4:5]
	s_waitcnt vmcnt(19)
	v_cndmask_b32_e64 v25, 0, v29, s[6:7]
	s_cbranch_vccnz .LBB0_203
	global_load_dword v28, v[10:11], off offset:176 nt
	s_waitcnt vmcnt(0)
	v_mul_f32_e32 v25, v25, v28
; __device__ __forceinline__ void transpose_item(const float* W, int K, int Nsrc, bf16_t* WT, int Ndst, const float* gain, int maptype, LAS float* scr, int item, int lane) {
;     ...
;     for (int h = 0; h < 2; ++h) {
;         float v[32];
; #pragma unroll
;         for (int i = 0; i < 32; ++i) v[i] = wp[(size_t)(32 * h + i) * Nsrc];
; #pragma unroll
;         for (int i = 0; i < 32; ++i) { float x = (src >= 0) ? v[i] : 0.f; if (gain) x *= gain[k0 + 32 * h + i]; scr[(32 * h + i) * 65 + lane] = x; }
;     }
;     asm volatile("s_waitcnt lgkmcnt(0)" ::: "memory");
.LBB0_203:
	s_and_b64 vcc, exec, s[4:5]
	s_waitcnt vmcnt(18)
	v_cndmask_b32_e64 v24, 0, v24, s[6:7]
	ds_write_b32 v32, v25 offset:11440
	s_cbranch_vccnz .LBB0_205
	global_load_dword v25, v[10:11], off offset:180 nt
	s_waitcnt vmcnt(0)
	v_mul_f32_e32 v24, v24, v25
.LBB0_205:
	s_and_b64 vcc, exec, s[4:5]
	s_waitcnt vmcnt(17)
	v_cndmask_b32_e64 v21, 0, v21, s[6:7]
	ds_write_b32 v32, v24 offset:11700
	s_cbranch_vccnz .LBB0_207
	global_load_dword v24, v[10:11], off offset:184 nt
	s_waitcnt vmcnt(0)
	v_mul_f32_e32 v21, v21, v24
.LBB0_207:
	s_and_b64 vcc, exec, s[4:5]
	s_waitcnt vmcnt(16)
	v_cndmask_b32_e64 v19, 0, v19, s[6:7]
	ds_write_b32 v32, v21 offset:11960
	s_cbranch_vccnz .LBB0_209
	global_load_dword v21, v[10:11], off offset:188 nt
	s_waitcnt vmcnt(0)
	v_mul_f32_e32 v19, v19, v21
.LBB0_209:
	ds_write_b32 v32, v19 offset:12220
	s_and_b64 vcc, exec, s[4:5]
	s_waitcnt vmcnt(15)
	v_cndmask_b32_e64 v19, 0, v71, s[6:7]
	s_cbranch_vccnz .LBB0_211
	global_load_dword v21, v[10:11], off offset:192 nt
	s_waitcnt vmcnt(0)
	v_mul_f32_e32 v19, v19, v21
.LBB0_211:
	ds_write_b32 v32, v19 offset:12480
	s_and_b64 vcc, exec, s[4:5]
	s_waitcnt vmcnt(14)
	v_cndmask_b32_e64 v19, 0, v68, s[6:7]
	s_cbranch_vccnz .LBB0_213
	global_load_dword v21, v[10:11], off offset:196 nt
	s_waitcnt vmcnt(0)
	v_mul_f32_e32 v19, v19, v21
.LBB0_213:
	ds_write_b32 v32, v19 offset:12740
	s_and_b64 vcc, exec, s[4:5]
	s_waitcnt vmcnt(13)
	v_cndmask_b32_e64 v19, 0, v30, s[6:7]
	s_cbranch_vccnz .LBB0_215
	global_load_dword v21, v[10:11], off offset:200 nt
	s_waitcnt vmcnt(0)
	v_mul_f32_e32 v19, v19, v21
.LBB0_215:
	ds_write_b32 v32, v19 offset:13000
	s_and_b64 vcc, exec, s[4:5]
	s_waitcnt vmcnt(12)
	v_cndmask_b32_e64 v19, 0, v26, s[6:7]
	s_cbranch_vccnz .LBB0_217
	global_load_dword v21, v[10:11], off offset:204 nt
	s_waitcnt vmcnt(0)
	v_mul_f32_e32 v19, v19, v21
.LBB0_217:
	ds_write_b32 v32, v19 offset:13260
	s_and_b64 vcc, exec, s[4:5]
	s_waitcnt vmcnt(11)
	v_cndmask_b32_e64 v19, 0, v22, s[6:7]
	s_cbranch_vccnz .LBB0_219
	global_load_dword v21, v[10:11], off offset:208 nt
	s_waitcnt vmcnt(0)
	v_mul_f32_e32 v19, v19, v21
.LBB0_219:
	s_and_b64 vcc, exec, s[4:5]
	s_waitcnt vmcnt(10)
	v_cndmask_b32_e64 v18, 0, v18, s[6:7]
	ds_write_b32 v32, v19 offset:13520
	s_cbranch_vccnz .LBB0_221
	global_load_dword v19, v[10:11], off offset:212 nt
	s_waitcnt vmcnt(0)
	v_mul_f32_e32 v18, v18, v19
.LBB0_221:
	s_and_b64 vcc, exec, s[4:5]
	s_waitcnt vmcnt(9)
	v_cndmask_b32_e64 v16, 0, v16, s[6:7]
	ds_write_b32 v32, v18 offset:13780
	s_cbranch_vccnz .LBB0_223
	global_load_dword v18, v[10:11], off offset:216 nt
	s_waitcnt vmcnt(0)
	v_mul_f32_e32 v16, v16, v18
.LBB0_223:
	s_and_b64 vcc, exec, s[4:5]
	s_waitcnt vmcnt(8)
	v_cndmask_b32_e64 v15, 0, v15, s[6:7]
	ds_write_b32 v32, v16 offset:14040
	s_cbranch_vccnz .LBB0_225
	global_load_dword v16, v[10:11], off offset:220 nt
	s_waitcnt vmcnt(0)
	v_mul_f32_e32 v15, v15, v16
.LBB0_225:
	ds_write_b32 v32, v15 offset:14300
	s_and_b64 vcc, exec, s[4:5]
	s_waitcnt vmcnt(7)
	v_cndmask_b32_e64 v15, 0, v31, s[6:7]
	s_cbranch_vccnz .LBB0_227
	global_load_dword v16, v[10:11], off offset:224 nt
	s_waitcnt vmcnt(0)
	v_mul_f32_e32 v15, v15, v16
.LBB0_227:
	ds_write_b32 v32, v15 offset:14560
	s_and_b64 vcc, exec, s[4:5]
	s_waitcnt vmcnt(6)
	v_cndmask_b32_e64 v15, 0, v27, s[6:7]
	s_cbranch_vccnz .LBB0_229
	global_load_dword v16, v[10:11], off offset:228 nt
	s_waitcnt vmcnt(0)
	v_mul_f32_e32 v15, v15, v16
.LBB0_229:
	ds_write_b32 v32, v15 offset:14820
	s_and_b64 vcc, exec, s[4:5]
	s_waitcnt vmcnt(5)
	v_cndmask_b32_e64 v15, 0, v23, s[6:7]
	s_cbranch_vccnz .LBB0_231
	global_load_dword v16, v[10:11], off offset:232 nt
	s_waitcnt vmcnt(0)
	v_mul_f32_e32 v15, v15, v16
.LBB0_231:
	ds_write_b32 v32, v15 offset:15080
	s_and_b64 vcc, exec, s[4:5]
	s_waitcnt vmcnt(4)
	v_cndmask_b32_e64 v15, 0, v20, s[6:7]
	s_cbranch_vccnz .LBB0_233
	global_load_dword v16, v[10:11], off offset:236 nt
	s_waitcnt vmcnt(0)
	v_mul_f32_e32 v15, v15, v16
.LBB0_233:
	ds_write_b32 v32, v15 offset:15340
	s_and_b64 vcc, exec, s[4:5]
	s_waitcnt vmcnt(3)
	v_cndmask_b32_e64 v15, 0, v17, s[6:7]
	s_cbranch_vccnz .LBB0_235
	global_load_dword v16, v[10:11], off offset:240 nt
	s_waitcnt vmcnt(0)
	v_mul_f32_e32 v15, v15, v16
.LBB0_235:
	s_and_b64 vcc, exec, s[4:5]
	s_waitcnt vmcnt(2)
	v_cndmask_b32_e64 v14, 0, v14, s[6:7]
	ds_write_b32 v32, v15 offset:15600
	s_cbranch_vccnz .LBB0_237
	global_load_dword v15, v[10:11], off offset:244 nt
	s_waitcnt vmcnt(0)
	v_mul_f32_e32 v14, v14, v15
.LBB0_237:
	s_and_b64 vcc, exec, s[4:5]
	s_waitcnt vmcnt(1)
	v_cndmask_b32_e64 v13, 0, v13, s[6:7]
	ds_write_b32 v32, v14 offset:15860
	s_cbranch_vccnz .LBB0_239
	global_load_dword v14, v[10:11], off offset:248 nt
	s_waitcnt vmcnt(0)
	v_mul_f32_e32 v13, v13, v14
.LBB0_239:
	s_and_b64 vcc, exec, s[4:5]
	s_waitcnt vmcnt(0)
	v_cndmask_b32_e64 v12, 0, v12, s[6:7]
	ds_write_b32 v32, v13 offset:16120
	s_cbranch_vccnz .LBB0_15
	global_load_dword v10, v[10:11], off offset:252 nt
	s_waitcnt vmcnt(0)
	v_mul_f32_e32 v12, v12, v10
	s_branch .LBB0_15

; __device__ __forceinline__ unsigned cvt_pk_bf16(float lo, float hi) { unsigned r; asm volatile("v_cvt_pk_bf16_f32 %0, %1, %2" : "=v"(r) : "v"(lo), "v"(hi)); return r; }
; __device__ __forceinline__ void prep_phase(const Params& P, LAS unsigned char* lds) {
;     ...
;     for (int i = gt; i < DEPTH * 256 * 512; i += NGT) {
;         const int L = i / (256 * 512), o = (i >> 9) & 255, k = i & 511; float v = 0.f;
;         if (o < 128) { if (k < 256) v = P.in[5][(size_t)L * 256 * 128 + k * 128 + ropeperm(o)]; }
;         else { if (k >= 256) v = P.in[8][(size_t)L * 256 * 128 + (k - 256) * 128 + (o - 128)]; }
;         ((bf16_t*)(ws + WS_CW2))[i] = (bf16_t)(cvt_pk_bf16(v, 0.f) & 0xffff);
.LBB0_263:
	v_ashrrev_i32_e32 v6, 31, v16
	v_lshrrev_b32_e32 v6, 15, v6
	v_add_u32_e32 v6, v16, v6
	v_bfe_u32 v17, v16, 9, 8
	v_ashrrev_i32_e32 v14, 17, v6
	v_cmp_lt_u32_e32 vcc, s0, v17
	s_and_saveexec_b64 s[2:3], vcc
	s_xor_b64 s[36:37], exec, s[2:3]
	s_cbranch_execz .LBB0_267
	v_mov_b32_e32 v6, 0
	s_and_saveexec_b64 s[38:39], s[4:5]
	s_cbranch_execz .LBB0_266
	v_ashrrev_i32_e32 v15, 31, v14
	v_lshlrev_b64 v[14:15], 17, v[14:15]
	v_lshl_add_u64 v[14:15], v[8:9], 0, v[14:15]
	v_lshlrev_b32_e32 v6, 2, v17
	v_lshl_add_u64 v[14:15], v[14:15], 0, v[6:7]
	v_add_co_u32_e32 v14, vcc, 0xfffe0000, v14
	s_nop 1
	v_addc_co_u32_e32 v15, vcc, -1, v15, vcc
	global_load_dword v6, v[14:15], off offset:-512 nt

; __device__ __forceinline__ unsigned cvt_pk_bf16(float lo, float hi) { unsigned r; asm volatile("v_cvt_pk_bf16_f32 %0, %1, %2" : "=v"(r) : "v"(lo), "v"(hi)); return r; }
; __device__ __forceinline__ void prep_phase(const Params& P, LAS unsigned char* lds) {
;     ...
;     for (int i = gt; i < DEPTH * 256 * 512; i += NGT) {
;         const int L = i / (256 * 512), o = (i >> 9) & 255, k = i & 511; float v = 0.f;
;         if (o < 128) { if (k < 256) v = P.in[5][(size_t)L * 256 * 128 + k * 128 + ropeperm(o)]; }
;         else { if (k >= 256) v = P.in[8][(size_t)L * 256 * 128 + (k - 256) * 128 + (o - 128)]; }
;         ((bf16_t*)(ws + WS_CW2))[i] = (bf16_t)(cvt_pk_bf16(v, 0.f) & 0xffff);
.LBB0_267:
	s_andn2_saveexec_b64 s[36:37], s[36:37]
	s_cbranch_execz .LBB0_262
	s_waitcnt vmcnt(0)
	v_mov_b32_e32 v6, 0
	s_and_saveexec_b64 s[38:39], s[6:7]
	s_cbranch_execz .LBB0_261
	v_lshrrev_b32_e32 v6, 9, v16
	v_ashrrev_i32_e32 v15, 31, v14
	v_lshrrev_b32_e32 v17, 1, v17
	v_lshlrev_b32_e32 v6, 6, v6
	v_and_or_b32 v6, v6, 64, v17
	v_lshlrev_b64 v[14:15], 17, v[14:15]
	v_lshl_add_u64 v[14:15], v[10:11], 0, v[14:15]
	v_lshlrev_b32_e32 v6, 2, v6
	v_lshl_add_u64 v[14:15], v[14:15], 0, v[6:7]
	global_load_dword v6, v[14:15], off nt
	s_branch .LBB0_261
